# row passes: wave reductions via DPP quad_perm/row_mirror + permlane16/32_swap instead of ds_bpermute; attention: row-sum init folded into first add, unit-start barrier after first tile loads
# baseline (speedup 1.0000x reference)
.Lfxa_skip:
	s_waitcnt vmcnt(3)
	v_mov_b32_e32 v2, v81
	v_mov_b32_e32 v3, v82
	v_mov_b32_e32 v84, v80
	v_mov_b32_e32 v85, v83
	v_pk_add_f32 v[2:3], v[2:3], v[84:85]
	s_waitcnt vmcnt(2)
	v_mov_b32_e32 v84, v77
	v_mov_b32_e32 v85, v78
	v_mov_b32_e32 v94, v76
	v_mov_b32_e32 v95, v79
	v_pk_add_f32 v[84:85], v[84:85], v[94:95]
	v_add_f32_e32 v1, v2, v3
	v_pk_add_f32 v[84:85], v[84:85], v[84:85] op_sel:[0,1] op_sel_hi:[1,0]
	v_add_f32_e32 v2, 0, v1
	s_waitcnt vmcnt(1)
	v_add_f32_e32 v94, v72, v73
	v_add_f32_e32 v104, v74, v75
	s_waitcnt vmcnt(0)
	v_mov_b32_e32 v3, v68
	v_mov_b32_e32 v85, v69
	v_mov_b32_e32 v95, v70
	v_mov_b32_e32 v105, v71
	v_pk_add_f32 v[2:3], v[2:3], v[84:85]
	v_pk_add_f32 v[84:85], v[94:95], v[104:105]
	s_nop 0
	v_pk_add_f32 v[2:3], v[2:3], v[84:85]
	s_nop 0
	v_add_f32_e32 v1, v2, v3
	s_nop 1
	v_add_f32_dpp v1, v1, v1 quad_perm:[1,0,3,2] row_mask:0xf bank_mask:0xf
	s_nop 1
	v_add_f32_dpp v1, v1, v1 quad_perm:[2,3,0,1] row_mask:0xf bank_mask:0xf
	s_nop 1
	v_add_f32_dpp v1, v1, v1 row_half_mirror row_mask:0xf bank_mask:0xf
	s_nop 1
	v_add_f32_dpp v1, v1, v1 row_mirror row_mask:0xf bank_mask:0xf
	v_mov_b32_e32 v2, v1
	s_nop 1
	v_permlane16_swap_b32_e32 v1, v2
	v_add_f32_e32 v1, v1, v2
	v_mov_b32_e32 v2, v1
	s_nop 1
	v_permlane32_swap_b32_e32 v1, v2
	v_add_f32_e32 v1, v1, v2
	v_fmamk_f32 v3, v1, 0xba800000, v83
	v_fmamk_f32 v81, v1, 0xba800000, v81
	v_fmamk_f32 v2, v1, 0xba800000, v82
	v_fmac_f32_e32 v80, 0xba800000, v1
	v_mul_f32_e32 v82, v81, v81
	v_mul_f32_e32 v83, v3, v3
	v_fmac_f32_e32 v82, v80, v80
	v_fmac_f32_e32 v83, v2, v2
	v_add_f32_e32 v84, v82, v83
	v_fmamk_f32 v83, v1, 0xba800000, v79
	v_fmamk_f32 v77, v1, 0xba800000, v77
	v_fmamk_f32 v82, v1, 0xba800000, v78
	v_fmac_f32_e32 v76, 0xba800000, v1
	v_mul_f32_e32 v78, v77, v77
	v_mul_f32_e32 v79, v83, v83
	v_fmac_f32_e32 v78, v76, v76
	v_fmac_f32_e32 v79, v82, v82
	v_add_f32_e32 v78, v78, v79
	v_fmamk_f32 v85, v1, 0xba800000, v75
	v_fmamk_f32 v73, v1, 0xba800000, v73
	v_add_f32_e32 v78, v84, v78
	v_fmamk_f32 v84, v1, 0xba800000, v74
	v_fmac_f32_e32 v72, 0xba800000, v1
	v_mul_f32_e32 v74, v73, v73
	v_mul_f32_e32 v75, v85, v85
	v_fmamk_f32 v95, v1, 0xba800000, v71
	v_fmamk_f32 v69, v1, 0xba800000, v69
	v_fmac_f32_e32 v74, v72, v72
	v_fmac_f32_e32 v75, v84, v84
	v_fmamk_f32 v94, v1, 0xba800000, v70
	v_fmac_f32_e32 v68, 0xba800000, v1
	v_mul_f32_e32 v70, v69, v69
	v_mul_f32_e32 v71, v95, v95
	v_add_f32_e32 v74, v74, v75
	v_fmac_f32_e32 v70, v68, v68
	v_fmac_f32_e32 v71, v94, v94
	v_add_f32_e32 v74, v74, v78
	v_add_f32_e32 v70, v70, v71
	v_add_f32_e32 v70, v70, v74
	s_nop 1
	v_add_f32_dpp v70, v70, v70 quad_perm:[1,0,3,2] row_mask:0xf bank_mask:0xf
	s_nop 1
	v_add_f32_dpp v70, v70, v70 quad_perm:[2,3,0,1] row_mask:0xf bank_mask:0xf
	s_nop 1
	v_add_f32_dpp v70, v70, v70 row_half_mirror row_mask:0xf bank_mask:0xf
	s_nop 1
	v_add_f32_dpp v70, v70, v70 row_mirror row_mask:0xf bank_mask:0xf
	v_mov_b32_e32 v71, v70
	s_nop 1
	v_permlane16_swap_b32_e32 v70, v71
	v_add_f32_e32 v70, v70, v71
	v_mov_b32_e32 v71, v70
	s_nop 1
	v_permlane32_swap_b32_e32 v70, v71
	v_add_f32_e32 v70, v70, v71
	v_fmamk_f32 v70, v70, 0x3a800000, v228
	v_cmp_gt_f32_e32 vcc, s49, v70
	v_mul_f32_e32 v71, 0x4f800000, v70
	s_nop 0
	v_cndmask_b32_e32 v70, v70, v71, vcc
	v_sqrt_f32_e32 v71, v70
	s_nop 0
	v_add_u32_e32 v74, -1, v71
	v_fma_f32 v75, -v74, v71, v70
	v_cmp_ge_f32_e64 s[0:1], 0, v75
	v_add_u32_e32 v75, 1, v71
	s_nop 0
	v_cndmask_b32_e64 v74, v71, v74, s[0:1]
	v_fma_f32 v71, -v75, v71, v70
	v_cmp_lt_f32_e64 s[0:1], 0, v71
	s_nop 1
	v_cndmask_b32_e64 v71, v74, v75, s[0:1]
	v_mul_f32_e32 v74, 0x37800000, v71
	v_cndmask_b32_e32 v71, v71, v74, vcc
	v_cmp_class_f32_e32 vcc, v70, v229
	s_nop 1
	v_cndmask_b32_e32 v70, v71, v70, vcc
	v_div_scale_f32 v71, s[0:1], v70, v70, 1.0
	v_rcp_f32_e32 v74, v71
	s_nop 0
	v_fma_f32 v75, -v71, v74, 1.0
	v_fmac_f32_e32 v74, v75, v74
	v_div_scale_f32 v75, vcc, 1.0, v70, 1.0
	v_mul_f32_e32 v78, v75, v74
	v_fma_f32 v79, -v71, v78, v75
	v_fmac_f32_e32 v78, v79, v74
	v_fma_f32 v71, -v71, v78, v75
	v_div_fmas_f32 v71, v71, v74, v78
	v_div_fixup_f32 v96, v71, v70, 1.0
	s_and_saveexec_b64 s[0:1], s[8:9]
	s_cbranch_execz .LBB0_338
	s_add_u32 s18, s4, s13
	v_mul_f32_e32 v70, 0x3a800000, v1
	s_addc_u32 s19, s5, s14
	v_mov_b32_e32 v71, v96
	global_store_dwordx2 v0, v[70:71], s[18:19]

.Lfxb_skip:
	s_waitcnt vmcnt(3)
	v_mov_b32_e32 v2, v81
	v_mov_b32_e32 v3, v82
	v_mov_b32_e32 v98, v80
	v_mov_b32_e32 v99, v83
	v_pk_add_f32 v[2:3], v[2:3], v[98:99]
	s_waitcnt vmcnt(2)
	v_mov_b32_e32 v98, v77
	v_mov_b32_e32 v99, v78
	v_mov_b32_e32 v100, v76
	v_mov_b32_e32 v101, v79
	v_pk_add_f32 v[98:99], v[98:99], v[100:101]
	v_add_f32_e32 v1, v2, v3
	v_pk_add_f32 v[98:99], v[98:99], v[98:99] op_sel:[0,1] op_sel_hi:[1,0]
	v_add_f32_e32 v2, 0, v1
	s_waitcnt vmcnt(1)
	v_add_f32_e32 v100, v72, v73
	v_add_f32_e32 v102, v74, v75
	s_waitcnt vmcnt(0)
	v_mov_b32_e32 v3, v68
	v_mov_b32_e32 v99, v69
	v_mov_b32_e32 v101, v70
	v_mov_b32_e32 v103, v71
	v_pk_add_f32 v[2:3], v[2:3], v[98:99]
	v_pk_add_f32 v[98:99], v[100:101], v[102:103]
	s_nop 0
	v_pk_add_f32 v[2:3], v[2:3], v[98:99]
	s_nop 0
	v_add_f32_e32 v1, v2, v3
	s_nop 1
	v_add_f32_dpp v1, v1, v1 quad_perm:[1,0,3,2] row_mask:0xf bank_mask:0xf
	s_nop 1
	v_add_f32_dpp v1, v1, v1 quad_perm:[2,3,0,1] row_mask:0xf bank_mask:0xf
	s_nop 1
	v_add_f32_dpp v1, v1, v1 row_half_mirror row_mask:0xf bank_mask:0xf
	s_nop 1
	v_add_f32_dpp v1, v1, v1 row_mirror row_mask:0xf bank_mask:0xf
	v_mov_b32_e32 v2, v1
	s_nop 1
	v_permlane16_swap_b32_e32 v1, v2
	v_add_f32_e32 v1, v1, v2
	v_mov_b32_e32 v2, v1
	s_nop 1
	v_permlane32_swap_b32_e32 v1, v2
	v_add_f32_e32 v1, v1, v2
	v_fmamk_f32 v3, v1, 0xba800000, v83
	v_fmamk_f32 v81, v1, 0xba800000, v81
	v_fmamk_f32 v2, v1, 0xba800000, v82
	v_fmac_f32_e32 v80, 0xba800000, v1
	v_mul_f32_e32 v82, v81, v81
	v_mul_f32_e32 v83, v3, v3
	v_fmac_f32_e32 v82, v80, v80
	v_fmac_f32_e32 v83, v2, v2
	v_fmamk_f32 v79, v1, 0xba800000, v79
	v_fmamk_f32 v77, v1, 0xba800000, v77
	v_add_f32_e32 v82, v82, v83
	v_fmamk_f32 v78, v1, 0xba800000, v78
	v_fmac_f32_e32 v76, 0xba800000, v1
	v_mul_f32_e32 v83, v77, v77
	v_mul_f32_e32 v97, v79, v79
	v_fmac_f32_e32 v83, v76, v76
	v_fmac_f32_e32 v97, v78, v78
	v_add_f32_e32 v83, v83, v97
	v_fmamk_f32 v75, v1, 0xba800000, v75
	v_fmamk_f32 v73, v1, 0xba800000, v73
	v_add_f32_e32 v82, v82, v83
	v_fmamk_f32 v74, v1, 0xba800000, v74
	v_fmac_f32_e32 v72, 0xba800000, v1
	v_mul_f32_e32 v83, v73, v73
	v_mul_f32_e32 v97, v75, v75
	v_fmac_f32_e32 v83, v72, v72
	v_fmac_f32_e32 v97, v74, v74
	v_add_f32_e32 v83, v83, v97
	v_fmamk_f32 v71, v1, 0xba800000, v71
	v_fmamk_f32 v69, v1, 0xba800000, v69
	v_add_f32_e32 v82, v83, v82
	v_fmamk_f32 v70, v1, 0xba800000, v70
	v_fmac_f32_e32 v68, 0xba800000, v1
	v_mul_f32_e32 v83, v69, v69
	v_mul_f32_e32 v97, v71, v71
	v_fmac_f32_e32 v83, v68, v68
	v_fmac_f32_e32 v97, v70, v70
	v_add_f32_e32 v83, v83, v97
	v_add_f32_e32 v82, v83, v82
	s_nop 1
	v_add_f32_dpp v82, v82, v82 quad_perm:[1,0,3,2] row_mask:0xf bank_mask:0xf
	s_nop 1
	v_add_f32_dpp v82, v82, v82 quad_perm:[2,3,0,1] row_mask:0xf bank_mask:0xf
	s_nop 1
	v_add_f32_dpp v82, v82, v82 row_half_mirror row_mask:0xf bank_mask:0xf
	s_nop 1
	v_add_f32_dpp v82, v82, v82 row_mirror row_mask:0xf bank_mask:0xf
	v_mov_b32_e32 v83, v82
	s_nop 1
	v_permlane16_swap_b32_e32 v82, v83
	v_add_f32_e32 v82, v82, v83
	v_mov_b32_e32 v83, v82
	s_nop 1
	v_permlane32_swap_b32_e32 v82, v83
	v_add_f32_e32 v82, v82, v83
	v_fmamk_f32 v82, v82, 0x3a800000, v228
	v_cmp_gt_f32_e32 vcc, s49, v82
	v_mul_f32_e32 v83, 0x4f800000, v82
	s_nop 0
	v_cndmask_b32_e32 v82, v82, v83, vcc
	v_sqrt_f32_e32 v83, v82
	s_nop 0
	v_add_u32_e32 v97, -1, v83
	v_fma_f32 v98, -v97, v83, v82
	v_cmp_ge_f32_e64 s[4:5], 0, v98
	v_add_u32_e32 v98, 1, v83
	s_nop 0
	v_cndmask_b32_e64 v97, v83, v97, s[4:5]
	v_fma_f32 v83, -v98, v83, v82
	v_cmp_lt_f32_e64 s[4:5], 0, v83
	s_nop 1
	v_cndmask_b32_e64 v83, v97, v98, s[4:5]
	v_mul_f32_e32 v97, 0x37800000, v83
	v_cndmask_b32_e32 v83, v83, v97, vcc
	v_cmp_class_f32_e32 vcc, v82, v229
	s_nop 1
	v_cndmask_b32_e32 v82, v83, v82, vcc
	v_div_scale_f32 v83, s[4:5], v82, v82, 1.0
	v_rcp_f32_e32 v97, v83
	s_nop 0
	v_fma_f32 v98, -v83, v97, 1.0
	v_fmac_f32_e32 v97, v98, v97
	v_div_scale_f32 v98, vcc, 1.0, v82, 1.0
	v_mul_f32_e32 v99, v98, v97
	v_fma_f32 v100, -v83, v99, v98
	v_fmac_f32_e32 v99, v100, v97
	v_fma_f32 v83, -v83, v99, v98
	v_div_fmas_f32 v83, v83, v97, v99
	v_div_fixup_f32 v82, v83, v82, 1.0
	s_and_saveexec_b64 s[4:5], s[0:1]
	s_cbranch_execz .LBB0_400
	s_add_u32 s14, s6, s11
	v_mul_f32_e32 v98, 0x3a800000, v1
	s_addc_u32 s15, s7, s12
	v_mov_b32_e32 v99, v82
	global_store_dwordx2 v0, v[98:99], s[14:15]
	s_branch .LBB0_400

.LBB0_639:
	v_mov_b32_e32 v184, v222
	s_lshl_b32 s2, s0, 2
	v_readfirstlane_b32 s18, v184
	s_ashr_i32 s19, s18, 8
	s_bfe_u32 s22, s18, 0x20006
	s_lshl_b32 s12, s73, 7
	s_or_b32 s2, s2, s74
	s_lshl_b32 s1, s22, 5
	s_lshl_b32 s24, s19, 5
	s_mul_i32 s23, s2, 0x4100
	s_ashr_i32 s25, s12, 31
	s_mul_hi_u32 s13, s2, 0x4100
	s_add_u32 s23, s23, s12
	v_and_b32_e32 v181, 31, v184
	s_addc_u32 s13, s13, s25
	s_or_b32 s23, s23, s1
	v_or_b32_e32 v2, s23, v181
	v_mov_b32_e32 v3, s13
	v_lshlrev_b64 v[2:3], 7, v[2:3]
	v_lshl_add_u64 v[2:3], s[6:7], 0, v[2:3]
	s_ashr_i32 s25, s24, 31
	v_bfe_u32 v180, v184, 5, 1
	v_lshl_add_u64 v[2:3], s[24:25], 1, v[2:3]
	s_mul_i32 s24, s2, 0x208000
	s_mul_hi_u32 s23, s2, 0x208000
	v_lshlrev_b32_e32 v162, 4, v180
	v_mov_b32_e32 v163, v0
	s_add_u32 s26, s11, s24
	v_lshl_add_u64 v[2:3], v[2:3], 0, v[162:163]
	s_addc_u32 s27, s72, s23
	v_ashrrev_i32_e32 v52, 3, v184
	global_load_dwordx4 v[158:161], v[2:3], off
	global_load_dwordx4 v[154:157], v[2:3], off offset:32
	s_add_u32 s28, s36, s24
	v_ashrrev_i32_e32 v53, 31, v52
	v_mov_b64_e32 v[2:3], s[26:27]
	v_lshlrev_b32_e32 v1, 4, v184
	s_addc_u32 s29, s10, s23
	v_lshlrev_b64 v[32:33], 7, v[52:53]
	v_mad_i64_i32 v[2:3], s[26:27], v52, s55, v[2:3]
	v_and_b32_e32 v50, 0x70, v1
	v_mov_b32_e32 v51, v0
	v_lshl_add_u64 v[166:167], v[2:3], 0, v[50:51]
	v_lshl_add_u64 v[2:3], s[28:29], 0, v[32:33]
	v_lshl_add_u64 v[168:169], v[2:3], 0, v[50:51]
	v_add_co_u32_e32 v46, vcc, s3, v168
	v_mov_b32_e32 v14, v0
	v_mov_b32_e32 v15, v0
	v_addc_co_u32_e32 v47, vcc, 0, v169, vcc
	v_mov_b32_e32 v1, v0
	v_mov_b32_e32 v2, v0
	v_mov_b32_e32 v3, v0
	v_mov_b32_e32 v4, v0
	v_mov_b32_e32 v5, v0
	v_mov_b32_e32 v6, v0
	v_mov_b32_e32 v7, v0
	v_mov_b32_e32 v8, v0
	v_mov_b32_e32 v9, v0
	v_mov_b32_e32 v10, v0
	v_mov_b32_e32 v11, v0
	v_mov_b32_e32 v12, v0
	v_mov_b32_e32 v13, v0
	v_mov_b64_e32 v[30:31], v[14:15]
	v_add_co_u32_e32 v54, vcc, s59, v168
	v_mov_b64_e32 v[28:29], v[12:13]
	v_mov_b64_e32 v[26:27], v[10:11]
	v_mov_b64_e32 v[24:25], v[8:9]
	v_mov_b64_e32 v[22:23], v[6:7]
	v_mov_b64_e32 v[20:21], v[4:5]
	v_mov_b64_e32 v[18:19], v[2:3]
	v_mov_b64_e32 v[16:17], v[0:1]
	v_addc_co_u32_e32 v55, vcc, 0, v169, vcc
	global_load_dwordx4 v[34:37], v[168:169], off
	global_load_dwordx4 v[38:41], v[166:167], off
	global_load_dwordx4 v[42:45], v[166:167], off offset:128
	s_nop 0
	global_load_dwordx4 v[46:49], v[46:47], off
	s_nop 0
	global_load_dwordx4 v[54:57], v[54:55], off
	v_mad_u64_u32 v[164:165], s[26:27], v52, s60, v[50:51]
	v_add_co_u32_e32 v50, vcc, s33, v168
	s_cmp_gt_i32 s73, 1
	v_add_u32_e32 v182, 0, v164
	v_addc_co_u32_e32 v51, vcc, 0, v169, vcc
	s_cselect_b32 s92, 0x8000, s33
	global_load_dwordx4 v[58:61], v[166:167], off offset:256
	global_load_dwordx4 v[62:65], v[50:51], off
	s_cselect_b32 s2, 0x104, 4
	s_mov_b32 s25, 1
	s_add_i32 s13, s2, -1
	s_cmp_lt_i32 s73, 2
	s_barrier
	s_waitcnt vmcnt(5)
	ds_write_b128 v182, v[38:41] offset:36864
	s_waitcnt vmcnt(4)
	ds_write_b128 v182, v[42:45] offset:46080
	ds_write_b128 v182, v[34:37]
	s_waitcnt vmcnt(3)
	ds_write_b128 v182, v[46:49] offset:9216
	s_waitcnt vmcnt(2)
	ds_write_b128 v182, v[54:57] offset:18432
	v_lshl_add_u64 v[34:35], v[168:169], 0, s[92:93]
	s_waitcnt lgkmcnt(0)
	s_barrier
	global_load_dwordx4 v[138:141], v[34:35], off
	global_load_dwordx4 v[142:145], v[166:167], off offset:384
	v_mul_u32_u24_e32 v34, 0x90, v181
	v_add3_u32 v163, 0, v34, v162
	v_lshl_add_u32 v165, s19, 6, v163
	ds_read_b128 v[54:57], v165
	s_waitcnt lgkmcnt(0)
	v_mfma_f32_32x32x16_bf16 v[36:51], v[54:57], v[158:161], v[16:31]
	ds_read_b128 v[54:57], v165 offset:4608
	s_waitcnt lgkmcnt(0)
	v_mfma_f32_32x32x16_bf16 v[16:31], v[54:57], v[158:161], v[16:31]
	ds_read_b128 v[54:57], v165 offset:32
	s_waitcnt lgkmcnt(0)
	v_mfma_f32_32x32x16_bf16 v[36:51], v[54:57], v[154:157], v[36:51]
	ds_read_b128 v[54:57], v165 offset:4640
	v_max3_f32 v34, v36, v37, v38
	s_nop 0
	v_max3_f32 v34, v34, v39, v40
	s_nop 0
	v_max3_f32 v34, v34, v41, v42
	s_nop 0
	v_max3_f32 v34, v34, v43, v44
	s_waitcnt lgkmcnt(0)
	v_mfma_f32_32x32x16_bf16 v[16:31], v[54:57], v[154:157], v[16:31]
	v_max3_f32 v34, v34, v45, v46
	s_nop 0
	v_max3_f32 v34, v34, v47, v48
	s_nop 0
	v_max3_f32 v34, v34, v49, v50
	s_nop 0
	v_max3_f32 v34, v34, v51, v16
	s_nop 0
	v_max3_f32 v34, v34, v17, v18
	s_nop 0
	v_max3_f32 v34, v34, v19, v20
	s_nop 0
	v_max3_f32 v34, v34, v21, v22
	s_nop 0
	v_max3_f32 v34, v34, v23, v24
	s_nop 0
	v_max3_f32 v34, v34, v25, v26
	s_nop 0
	v_max3_f32 v34, v34, v27, v28
	s_nop 0
	v_max3_f32 v34, v34, v29, v30
	s_nop 0
	v_max3_f32 v34, v34, v31, v31
	s_setprio 0
	ds_read_b128 v[54:57], v165 offset:9216
	ds_read_b128 v[106:109], v165 offset:9248
	ds_read_b128 v[110:113], v165 offset:13824
	ds_read_b128 v[114:117], v165 offset:13856
	v_mov_b32_e32 v35, v34
	s_nop 1
	v_permlane32_swap_b32_e32 v34, v35
	v_max_f32_e32 v35, v35, v35
	v_max_f32_e32 v34, v34, v34
	v_max_f32_e32 v35, v34, v35
	v_add_f32_e32 v183, 0, v35
	v_xor_b32_e32 v34, 0x80000000, v183
	v_sub_f32_e32 v53, v36, v35
	v_sub_f32_e32 v16, v16, v35
	v_sub_f32_e32 v66, v37, v35
	v_sub_f32_e32 v17, v17, v35
	v_sub_f32_e32 v67, v38, v35
	v_sub_f32_e32 v18, v18, v35
	v_sub_f32_e32 v68, v39, v35
	v_sub_f32_e32 v19, v19, v35
	v_sub_f32_e32 v69, v40, v35
	v_sub_f32_e32 v20, v20, v35
	v_sub_f32_e32 v70, v41, v35
	v_sub_f32_e32 v21, v21, v35
	v_sub_f32_e32 v71, v42, v35
	v_sub_f32_e32 v22, v22, v35
	v_sub_f32_e32 v72, v43, v35
	v_sub_f32_e32 v23, v23, v35
	v_sub_f32_e32 v118, v44, v35
	v_sub_f32_e32 v24, v24, v35
	v_sub_f32_e32 v119, v45, v35
	v_sub_f32_e32 v25, v25, v35
	v_sub_f32_e32 v120, v46, v35
	v_sub_f32_e32 v26, v26, v35
	v_sub_f32_e32 v121, v47, v35
	v_sub_f32_e32 v27, v27, v35
	v_sub_f32_e32 v122, v48, v35
	v_sub_f32_e32 v28, v28, v35
	v_sub_f32_e32 v123, v49, v35
	v_sub_f32_e32 v29, v29, v35
	v_sub_f32_e32 v50, v50, v35
	v_sub_f32_e32 v30, v30, v35
	v_sub_f32_e32 v51, v51, v35
	v_sub_f32_e32 v31, v31, v35
	v_mov_b32_e32 v35, v34
	v_mov_b32_e32 v36, v34
	v_mov_b32_e32 v37, v34
	v_mov_b32_e32 v38, v34
	v_mov_b32_e32 v39, v34
	v_mov_b32_e32 v40, v34
	v_mov_b32_e32 v41, v34
	v_mov_b32_e32 v42, v34
	v_mov_b32_e32 v43, v34
	v_mov_b32_e32 v44, v34
	v_mov_b32_e32 v45, v34
	v_mov_b32_e32 v46, v34
	v_mov_b32_e32 v47, v34
	v_mov_b32_e32 v48, v34
	v_mov_b32_e32 v49, v34
	s_waitcnt lgkmcnt(3)
	s_nop 4
	v_mfma_f32_32x32x16_bf16 v[82:97], v[54:57], v[158:161], v[34:49]
	v_exp_f32_e32 v102, v53
	v_exp_f32_e32 v103, v66
	v_exp_f32_e32 v104, v67
	v_exp_f32_e32 v105, v68
	s_nop 0
	v_exp_f32_e32 v98, v69
	v_exp_f32_e32 v99, v70
	v_exp_f32_e32 v100, v71
	v_exp_f32_e32 v101, v72
	s_nop 0
	s_waitcnt lgkmcnt(1)
	s_nop 4
	v_mfma_f32_32x32x16_bf16 v[66:81], v[110:113], v[158:161], v[34:49]
	v_exp_f32_e32 v194, v118
	v_exp_f32_e32 v187, v119
	v_exp_f32_e32 v186, v120
	v_exp_f32_e32 v185, v121
	s_nop 0
	v_exp_f32_e32 v133, v122
	v_exp_f32_e32 v132, v123
	v_exp_f32_e32 v131, v50
	v_exp_f32_e32 v130, v51
	s_nop 0
	v_mfma_f32_32x32x16_bf16 v[82:97], v[106:109], v[154:157], v[82:97]
	v_exp_f32_e32 v129, v16
	v_exp_f32_e32 v128, v17
	v_exp_f32_e32 v127, v18
	v_exp_f32_e32 v126, v19
	s_nop 0
	v_exp_f32_e32 v125, v20
	v_exp_f32_e32 v124, v21
	v_exp_f32_e32 v123, v22
	v_exp_f32_e32 v122, v23
	s_nop 0
	s_waitcnt lgkmcnt(0)
	v_mfma_f32_32x32x16_bf16 v[66:81], v[114:117], v[154:157], v[66:81]
	v_exp_f32_e32 v109, v24
	v_exp_f32_e32 v108, v25
	v_exp_f32_e32 v107, v26
	v_exp_f32_e32 v106, v27
	s_nop 0
	v_exp_f32_e32 v113, v28
	v_exp_f32_e32 v112, v29
	v_exp_f32_e32 v111, v30
	v_exp_f32_e32 v110, v31
	s_nop 0
	s_waitcnt vmcnt(2)
	ds_write_b128 v182, v[62:65] offset:27648
	ds_write_b128 v182, v[58:61] offset:55296
	s_cbranch_scc1 .LBB0_665
	s_add_u32 s24, s4, s24
	v_and_b32_e32 v18, 7, v184
	s_addc_u32 s25, s5, s23
	v_mad_i64_i32 v[16:17], s[26:27], v52, s55, 0
	v_lshlrev_b32_e32 v170, 4, v18
	v_lshl_add_u64 v[174:175], s[24:25], 0, v[32:33]
	v_mov_b64_e32 v[32:33], v[14:15]
	v_lshl_add_u64 v[172:173], s[24:25], 0, v[16:17]
	v_mov_b64_e32 v[30:31], v[12:13]
	v_mov_b64_e32 v[28:29], v[10:11]
	v_mov_b64_e32 v[26:27], v[8:9]
	v_mov_b64_e32 v[24:25], v[6:7]
	v_mov_b64_e32 v[22:23], v[4:5]
	v_mov_b64_e32 v[20:21], v[2:3]
	v_mov_b64_e32 v[18:19], v[0:1]
	v_mov_b64_e32 v[16:17], v[14:15]
	v_mov_b32_e32 v171, v0
	s_mov_b32 s25, 1
	v_mov_b32_e32 v50, 0
	s_mov_b32 s23, 12
	v_mov_b64_e32 v[14:15], v[12:13]
	v_mov_b64_e32 v[12:13], v[10:11]
	v_mov_b64_e32 v[10:11], v[8:9]
	v_mov_b64_e32 v[8:9], v[6:7]
	v_mov_b64_e32 v[6:7], v[4:5]
	v_mov_b64_e32 v[4:5], v[2:3]
	v_mov_b64_e32 v[2:3], v[0:1]
.LBB0_641:
	v_lshl_add_u64 v[178:179], v[174:175], 0, v[170:171]
	s_mov_b32 s24, 0x1894a000
	v_add_co_u32_e32 v52, vcc, s24, v178
	v_lshl_add_u64 v[56:57], v[172:173], 0, v[170:171]
	s_nop 0
	v_addc_co_u32_e32 v53, vcc, 0, v179, vcc
	s_mov_b32 s24, 0x19980000
	v_add_co_u32_e32 v176, vcc, s24, v56
	s_nop 0
	v_addc_co_u32_e32 v177, vcc, 0, v57, vcc
	global_load_dwordx4 v[52:55], v[52:53], off
	s_mul_i32 s26, s25, 0x2400
	global_load_dwordx4 v[56:59], v[176:177], off offset:512
	s_add_i32 s24, s23, -7
	s_add_i32 s27, s26, 0xffffdc00
	s_cmp_lg_u32 s25, 0
	s_cselect_b32 s27, s27, 0x9000
	v_add_u32_e32 v1, s27, v163
	ds_read_b128 v[60:63], v1 offset:36864
	ds_read_b128 v[114:117], v1 offset:36896
	ds_read_b128 v[118:121], v1 offset:41472
	ds_read_b128 v[134:137], v1 offset:41504
	ds_read_b128 v[146:149], v1 offset:36928
	ds_read_b128 v[150:153], v1 offset:36960
	ds_read_b128 v[196:199], v1 offset:41536
	ds_read_b128 v[200:203], v1 offset:41568
	s_setprio 3
	v_cvt_pk_bf16_f32 v204, v102, v103
	v_cvt_pk_bf16_f32 v205, v104, v105
	v_cvt_pk_bf16_f32 v206, v98, v99
	v_cvt_pk_bf16_f32 v207, v100, v101
	s_waitcnt lgkmcnt(7)
	s_nop 0
	v_mfma_f32_32x32x16_bf16 v[18:33], v[60:63], v[204:207], v[18:33]
	v_mov_b32_e32 v1, v102
	v_add_f32_e32 v1, v1, v103
	v_add_f32_e32 v1, v1, v104
	v_add_f32_e32 v1, v1, v105
	s_waitcnt lgkmcnt(5)
	v_mfma_f32_32x32x16_bf16 v[2:17], v[118:121], v[204:207], v[2:17]
	v_cvt_pk_bf16_f32 v60, v194, v187
	v_cvt_pk_bf16_f32 v61, v186, v185
	v_cvt_pk_bf16_f32 v62, v133, v132
	v_cvt_pk_bf16_f32 v63, v131, v130
	v_add_f32_e32 v1, v1, v98
	v_add_f32_e32 v1, v1, v99
	v_add_f32_e32 v1, v1, v100
	v_add_f32_e32 v1, v1, v101
	s_nop 0
	v_mfma_f32_32x32x16_bf16 v[18:33], v[114:117], v[60:63], v[18:33]
	v_add_f32_e32 v1, v1, v194
	v_add_f32_e32 v1, v1, v187
	v_add_f32_e32 v1, v1, v186
	v_add_f32_e32 v1, v1, v185
	s_waitcnt lgkmcnt(4)
	v_mfma_f32_32x32x16_bf16 v[2:17], v[134:137], v[60:63], v[2:17]
	v_cvt_pk_bf16_f32 v98, v129, v128
	v_cvt_pk_bf16_f32 v99, v127, v126
	v_cvt_pk_bf16_f32 v100, v125, v124
	v_cvt_pk_bf16_f32 v101, v123, v122
	v_add_f32_e32 v1, v1, v133
	v_add_f32_e32 v1, v1, v132
	v_add_f32_e32 v1, v1, v131
	v_add_f32_e32 v1, v1, v130
	s_waitcnt lgkmcnt(3)
	v_mfma_f32_32x32x16_bf16 v[18:33], v[146:149], v[98:101], v[18:33]
	v_add_f32_e32 v1, v1, v129
	v_add_f32_e32 v1, v1, v128
	v_add_f32_e32 v1, v1, v127
	v_add_f32_e32 v1, v1, v126
	s_waitcnt lgkmcnt(1)
	v_mfma_f32_32x32x16_bf16 v[2:17], v[196:199], v[98:101], v[2:17]
	v_cvt_pk_bf16_f32 v60, v109, v108
	v_cvt_pk_bf16_f32 v61, v107, v106
	v_cvt_pk_bf16_f32 v62, v113, v112
	v_cvt_pk_bf16_f32 v63, v111, v110
	v_add_f32_e32 v1, v1, v125
	v_add_f32_e32 v1, v1, v124
	v_add_f32_e32 v1, v1, v123
	v_add_f32_e32 v1, v1, v122
	s_nop 0
	v_mfma_f32_32x32x16_bf16 v[18:33], v[150:153], v[60:63], v[18:33]
	v_add_f32_e32 v1, v1, v109
	v_add_f32_e32 v1, v1, v108
	v_add_f32_e32 v1, v1, v107
	v_add_f32_e32 v1, v1, v106
	s_waitcnt lgkmcnt(0)
	v_mfma_f32_32x32x16_bf16 v[2:17], v[200:203], v[60:63], v[2:17]
	v_add_f32_e32 v1, v1, v113
	v_add_f32_e32 v1, v1, v112
	v_add_f32_e32 v1, v1, v111
	v_add_f32_e32 v1, v1, v110
	s_setprio 2
	s_waitcnt lgkmcnt(0)
	s_barrier
	ds_read_b128 v[240:243], v165 offset:18432
	ds_read_b128 v[244:247], v165 offset:23040
	ds_read_b128 v[130:133], v165 offset:18464
	ds_read_b128 v[146:149], v165 offset:23072
	s_waitcnt lgkmcnt(2)
	v_mfma_f32_32x32x16_bf16 v[114:129], v[240:243], v[158:161], v[34:49]
	v_exp_f32_e32 v185, v82
	v_exp_f32_e32 v186, v83
	v_exp_f32_e32 v187, v84
	v_exp_f32_e32 v194, v85
	v_exp_f32_e32 v195, v86
	v_exp_f32_e32 v196, v87
	v_exp_f32_e32 v197, v88
	v_exp_f32_e32 v198, v89
	s_waitcnt lgkmcnt(1)
	v_mfma_f32_32x32x16_bf16 v[98:113], v[244:247], v[158:161], v[34:49]
	v_exp_f32_e32 v199, v90
	v_exp_f32_e32 v200, v91
	v_exp_f32_e32 v201, v92
	v_exp_f32_e32 v202, v93
	v_exp_f32_e32 v134, v94
	v_exp_f32_e32 v135, v95
	v_exp_f32_e32 v136, v96
	v_exp_f32_e32 v137, v97
	v_mfma_f32_32x32x16_bf16 v[114:129], v[130:133], v[154:157], v[114:129]
	v_exp_f32_e32 v96, v66
	v_exp_f32_e32 v97, v67
	v_exp_f32_e32 v203, v68
	v_exp_f32_e32 v204, v69
	v_exp_f32_e32 v130, v70
	v_exp_f32_e32 v131, v71
	v_exp_f32_e32 v132, v72
	v_exp_f32_e32 v133, v73
	s_waitcnt lgkmcnt(0)
	v_mfma_f32_32x32x16_bf16 v[98:113], v[146:149], v[154:157], v[98:113]
	v_exp_f32_e32 v205, v74
	v_exp_f32_e32 v206, v75
	v_exp_f32_e32 v207, v76
	v_exp_f32_e32 v208, v77
	v_exp_f32_e32 v209, v78
	v_exp_f32_e32 v210, v79
	v_exp_f32_e32 v211, v80
	v_exp_f32_e32 v212, v81
	s_cmp_gt_i32 s25, 2
	s_cselect_b32 s27, -3, 2
	s_add_i32 s27, s27, s25
	v_add_u32_e32 v88, s26, v163
	s_add_i32 s26, s23, -6
	s_mulk_i32 s27, 0x2400
	s_min_u32 s26, s26, s13
	v_add_u32_e32 v51, s27, v182
	s_min_u32 s24, s24, s13
	s_lshl_b32 s92, s26, 13
	s_waitcnt vmcnt(3)
	ds_write_b128 v182, v[138:141]
	s_waitcnt vmcnt(2)
	ds_write_b128 v51, v[142:145] offset:36864
	v_add_f32_e32 v1, v50, v1
	v_lshl_add_u64 v[50:51], v[168:169], 0, s[92:93]
	s_lshl_b32 s92, s24, 7
	global_load_dwordx4 v[146:149], v[50:51], off
	v_lshl_add_u64 v[50:51], v[166:167], 0, s[92:93]
	global_load_dwordx4 v[150:153], v[50:51], off
	ds_read_b128 v[240:243], v165 offset:27648
	ds_read_b128 v[244:247], v165 offset:32256
	ds_read_b128 v[60:63], v88 offset:41472
	ds_read_b128 v[64:67], v88 offset:36864
	ds_read_b128 v[68:71], v88 offset:36896
	ds_read_b128 v[72:75], v88 offset:41504
	ds_read_b128 v[76:79], v88 offset:36928
	ds_read_b128 v[80:83], v88 offset:41536
	ds_read_b128 v[84:87], v88 offset:36960
	ds_read_b128 v[88:91], v88 offset:41568
	s_add_i32 s27, s25, 1
	s_setprio 1
	v_cvt_pk_bf16_f32 v92, v185, v186
	v_cvt_pk_bf16_f32 v93, v187, v194
	v_cvt_pk_bf16_f32 v94, v195, v196
	v_cvt_pk_bf16_f32 v95, v197, v198
	s_waitcnt lgkmcnt(6)
	s_nop 0
	v_mfma_f32_32x32x16_bf16 v[18:33], v[64:67], v[92:95], v[18:33]
	v_mov_b32_e32 v213, v185
	v_add_f32_e32 v213, v213, v186
	v_add_f32_e32 v213, v213, v187
	v_add_f32_e32 v213, v213, v194
	s_nop 0
	v_mfma_f32_32x32x16_bf16 v[2:17], v[60:63], v[92:95], v[2:17]
	v_cvt_pk_bf16_f32 v64, v199, v200
	v_cvt_pk_bf16_f32 v65, v201, v202
	v_cvt_pk_bf16_f32 v66, v134, v135
	v_cvt_pk_bf16_f32 v67, v136, v137
	v_add_f32_e32 v213, v213, v195
	v_add_f32_e32 v213, v213, v196
	v_add_f32_e32 v213, v213, v197
	v_add_f32_e32 v213, v213, v198
	s_waitcnt lgkmcnt(5)
	v_mfma_f32_32x32x16_bf16 v[18:33], v[68:71], v[64:67], v[18:33]
	v_add_f32_e32 v213, v213, v199
	v_add_f32_e32 v213, v213, v200
	v_add_f32_e32 v213, v213, v201
	v_add_f32_e32 v213, v213, v202
	s_waitcnt lgkmcnt(4)
	v_mfma_f32_32x32x16_bf16 v[2:17], v[72:75], v[64:67], v[2:17]
	v_cvt_pk_bf16_f32 v60, v96, v97
	v_cvt_pk_bf16_f32 v61, v203, v204
	v_cvt_pk_bf16_f32 v62, v130, v131
	v_cvt_pk_bf16_f32 v63, v132, v133
	v_add_f32_e32 v213, v213, v134
	v_add_f32_e32 v213, v213, v135
	v_add_f32_e32 v213, v213, v136
	v_add_f32_e32 v213, v213, v137
	s_waitcnt lgkmcnt(3)
	v_mfma_f32_32x32x16_bf16 v[18:33], v[76:79], v[60:63], v[18:33]
	v_add_f32_e32 v213, v213, v96
	v_add_f32_e32 v213, v213, v97
	v_add_f32_e32 v213, v213, v203
	v_add_f32_e32 v213, v213, v204
	s_waitcnt lgkmcnt(2)
	v_mfma_f32_32x32x16_bf16 v[2:17], v[80:83], v[60:63], v[2:17]
	v_cvt_pk_bf16_f32 v64, v205, v206
	v_cvt_pk_bf16_f32 v65, v207, v208
	v_cvt_pk_bf16_f32 v66, v209, v210
	v_cvt_pk_bf16_f32 v67, v211, v212
	v_add_f32_e32 v213, v213, v130
	v_add_f32_e32 v213, v213, v131
	v_add_f32_e32 v213, v213, v132
	v_add_f32_e32 v213, v213, v133
	s_waitcnt lgkmcnt(1)
	v_mfma_f32_32x32x16_bf16 v[18:33], v[84:87], v[64:67], v[18:33]
	v_add_f32_e32 v213, v213, v205
	v_add_f32_e32 v213, v213, v206
	v_add_f32_e32 v213, v213, v207
	v_add_f32_e32 v213, v213, v208
	s_waitcnt lgkmcnt(0)
	v_mfma_f32_32x32x16_bf16 v[2:17], v[88:91], v[64:67], v[2:17]
	v_add_f32_e32 v213, v213, v209
	v_add_f32_e32 v213, v213, v210
	v_add_f32_e32 v213, v213, v211
	v_add_f32_e32 v213, v213, v212
	s_setprio 0
	ds_read_b128 v[64:67], v165 offset:27680
	ds_read_b128 v[72:75], v165 offset:32288
	s_cmp_lg_u32 s25, 4
	s_cselect_b32 s24, s27, 0
	s_waitcnt lgkmcnt(2)
	v_mfma_f32_32x32x16_bf16 v[130:145], v[240:243], v[158:161], v[34:49]
	v_exp_f32_e32 v185, v114
	v_exp_f32_e32 v186, v115
	v_exp_f32_e32 v187, v116
	v_exp_f32_e32 v194, v117
	v_exp_f32_e32 v195, v118
	v_exp_f32_e32 v196, v119
	v_exp_f32_e32 v197, v120
	v_exp_f32_e32 v198, v121
	s_waitcnt lgkmcnt(1)
	v_mfma_f32_32x32x16_bf16 v[82:97], v[244:247], v[158:161], v[34:49]
	v_exp_f32_e32 v199, v122
	v_exp_f32_e32 v200, v123
	v_exp_f32_e32 v201, v124
	v_exp_f32_e32 v202, v125
	v_exp_f32_e32 v122, v126
	v_exp_f32_e32 v123, v127
	v_exp_f32_e32 v124, v128
	v_exp_f32_e32 v125, v129
	v_mfma_f32_32x32x16_bf16 v[130:145], v[64:67], v[154:157], v[130:145]
	v_exp_f32_e32 v126, v98
	v_exp_f32_e32 v127, v99
	v_exp_f32_e32 v128, v100
	v_exp_f32_e32 v129, v101
	v_exp_f32_e32 v203, v102
	v_exp_f32_e32 v204, v103
	v_exp_f32_e32 v205, v104
	v_exp_f32_e32 v206, v105
	s_waitcnt lgkmcnt(0)
	v_mfma_f32_32x32x16_bf16 v[82:97], v[72:75], v[154:157], v[82:97]
	v_exp_f32_e32 v102, v106
	v_exp_f32_e32 v103, v107
	v_exp_f32_e32 v104, v108
	v_exp_f32_e32 v105, v109
	v_exp_f32_e32 v106, v110
	v_exp_f32_e32 v107, v111
	v_exp_f32_e32 v108, v112
	v_exp_f32_e32 v109, v113
	s_cmp_gt_i32 s24, 2
	s_cselect_b32 s25, -3, 2
	s_add_i32 s25, s25, s24
	s_mulk_i32 s25, 0x2400
	v_add_u32_e32 v50, s25, v182
	s_add_i32 s25, s24, 1
	s_cmp_lg_u32 s24, 4
	s_cselect_b32 s24, s25, 0
	s_add_i32 s25, s23, -5
	s_min_u32 s25, s25, s13
	s_lshl_b32 s92, s25, 13
	s_waitcnt vmcnt(3)
	ds_write_b128 v182, v[52:55] offset:9216
	s_waitcnt vmcnt(2)
	ds_write_b128 v50, v[56:59] offset:36864
	v_lshl_add_u64 v[50:51], v[168:169], 0, s[92:93]
	s_lshl_b32 s92, s26, 7
	v_lshl_add_u64 v[52:53], v[166:167], 0, s[92:93]
	global_load_dwordx4 v[118:121], v[50:51], off
	global_load_dwordx4 v[114:117], v[52:53], off
	s_mul_i32 s26, s24, 0x2400
	s_add_i32 s27, s26, 0xffffdc00
	s_cmp_lg_u32 s24, 0
	s_cselect_b32 s27, s27, 0x9000
	v_add_u32_e32 v78, s27, v163
	ds_read_b128 v[50:53], v78 offset:36864
	ds_read_b128 v[54:57], v78 offset:36896
	ds_read_b128 v[58:61], v78 offset:41472
	ds_read_b128 v[62:65], v78 offset:41504
	ds_read_b128 v[66:69], v78 offset:36928
	ds_read_b128 v[70:73], v78 offset:36960
	ds_read_b128 v[74:77], v78 offset:41536
	ds_read_b128 v[78:81], v78 offset:41568
	s_setprio 3
	v_cvt_pk_bf16_f32 v98, v185, v186
	v_cvt_pk_bf16_f32 v99, v187, v194
	v_cvt_pk_bf16_f32 v100, v195, v196
	v_cvt_pk_bf16_f32 v101, v197, v198
	s_waitcnt lgkmcnt(7)
	s_nop 0
	v_mfma_f32_32x32x16_bf16 v[18:33], v[50:53], v[98:101], v[18:33]
	v_mov_b32_e32 v110, v185
	v_add_f32_e32 v110, v110, v186
	v_add_f32_e32 v110, v110, v187
	v_add_f32_e32 v110, v110, v194
	s_waitcnt lgkmcnt(5)
	v_mfma_f32_32x32x16_bf16 v[2:17], v[58:61], v[98:101], v[2:17]
	v_cvt_pk_bf16_f32 v50, v199, v200
	v_cvt_pk_bf16_f32 v51, v201, v202
	v_cvt_pk_bf16_f32 v52, v122, v123
	v_cvt_pk_bf16_f32 v53, v124, v125
	v_add_f32_e32 v110, v110, v195
	v_add_f32_e32 v110, v110, v196
	v_add_f32_e32 v110, v110, v197
	v_add_f32_e32 v110, v110, v198
	s_nop 0
	v_mfma_f32_32x32x16_bf16 v[18:33], v[54:57], v[50:53], v[18:33]
	v_add_f32_e32 v110, v110, v199
	v_add_f32_e32 v110, v110, v200
	v_add_f32_e32 v110, v110, v201
	v_add_f32_e32 v110, v110, v202
	s_waitcnt lgkmcnt(4)
	v_mfma_f32_32x32x16_bf16 v[2:17], v[62:65], v[50:53], v[2:17]
	v_cvt_pk_bf16_f32 v54, v126, v127
	v_cvt_pk_bf16_f32 v55, v128, v129
	v_cvt_pk_bf16_f32 v56, v203, v204
	v_cvt_pk_bf16_f32 v57, v205, v206
	v_add_f32_e32 v110, v110, v122
	v_add_f32_e32 v110, v110, v123
	v_add_f32_e32 v110, v110, v124
	v_add_f32_e32 v110, v110, v125
	s_waitcnt lgkmcnt(3)
	v_mfma_f32_32x32x16_bf16 v[18:33], v[66:69], v[54:57], v[18:33]
	v_add_f32_e32 v110, v110, v126
	v_add_f32_e32 v110, v110, v127
	v_add_f32_e32 v110, v110, v128
	v_add_f32_e32 v110, v110, v129
	s_waitcnt lgkmcnt(1)
	v_mfma_f32_32x32x16_bf16 v[2:17], v[74:77], v[54:57], v[2:17]
	v_cvt_pk_bf16_f32 v50, v102, v103
	v_cvt_pk_bf16_f32 v51, v104, v105
	v_cvt_pk_bf16_f32 v52, v106, v107
	v_cvt_pk_bf16_f32 v53, v108, v109
	v_add_f32_e32 v110, v110, v203
	v_add_f32_e32 v110, v110, v204
	v_add_f32_e32 v110, v110, v205
	v_add_f32_e32 v110, v110, v206
	s_nop 0
	v_mfma_f32_32x32x16_bf16 v[18:33], v[70:73], v[50:53], v[18:33]
	v_add_f32_e32 v110, v110, v102
	v_add_f32_e32 v110, v110, v103
	v_add_f32_e32 v110, v110, v104
	v_add_f32_e32 v110, v110, v105
	s_waitcnt lgkmcnt(0)
	v_mfma_f32_32x32x16_bf16 v[2:17], v[78:81], v[50:53], v[2:17]
	v_add_f32_e32 v110, v110, v106
	v_add_f32_e32 v110, v110, v107
	v_add_f32_e32 v110, v110, v108
	v_add_f32_e32 v110, v110, v109
	s_setprio 2
	s_waitcnt lgkmcnt(0)
	s_barrier
	ds_read_b128 v[240:243], v165
	ds_read_b128 v[244:247], v165 offset:4608
	ds_read_b128 v[102:105], v165 offset:32
	ds_read_b128 v[106:109], v165 offset:4640
	v_add_f32_e32 v1, v1, v213
	s_waitcnt lgkmcnt(2)
	v_mfma_f32_32x32x16_bf16 v[66:81], v[240:243], v[158:161], v[34:49]
	v_exp_f32_e32 v185, v130
	v_exp_f32_e32 v186, v131
	v_exp_f32_e32 v187, v132
	v_exp_f32_e32 v194, v133
	v_exp_f32_e32 v195, v134
	v_exp_f32_e32 v196, v135
	v_exp_f32_e32 v197, v136
	v_exp_f32_e32 v198, v137
	v_mfma_f32_32x32x16_bf16 v[50:65], v[244:247], v[158:161], v[34:49]
	v_exp_f32_e32 v134, v138
	v_exp_f32_e32 v135, v139
	v_exp_f32_e32 v136, v140
	v_exp_f32_e32 v137, v141
	v_exp_f32_e32 v138, v142
	v_exp_f32_e32 v139, v143
	v_exp_f32_e32 v140, v144
	v_exp_f32_e32 v141, v145
	s_waitcnt lgkmcnt(1)
	v_mfma_f32_32x32x16_bf16 v[66:81], v[102:105], v[154:157], v[66:81]
	v_exp_f32_e32 v142, v82
	v_exp_f32_e32 v143, v83
	v_exp_f32_e32 v144, v84
	v_exp_f32_e32 v145, v85
	v_exp_f32_e32 v199, v86
	v_exp_f32_e32 v200, v87
	v_exp_f32_e32 v201, v88
	v_exp_f32_e32 v202, v89
	s_waitcnt lgkmcnt(0)
	v_mfma_f32_32x32x16_bf16 v[50:65], v[106:109], v[154:157], v[50:65]
	v_exp_f32_e32 v203, v90
	v_exp_f32_e32 v204, v91
	v_exp_f32_e32 v205, v92
	v_exp_f32_e32 v206, v93
	v_exp_f32_e32 v207, v94
	v_exp_f32_e32 v208, v95
	v_exp_f32_e32 v209, v96
	v_exp_f32_e32 v210, v97
	s_cmp_gt_i32 s24, 2
	s_cselect_b32 s27, -3, 2
	s_add_i32 s27, s27, s24
	s_mulk_i32 s27, 0x2400
	v_add_u32_e32 v82, s27, v182
	s_mov_b32 s27, 0x18950000
	s_waitcnt vmcnt(3)
	ds_write_b128 v182, v[146:149] offset:18432
	s_waitcnt vmcnt(2)
	ds_write_b128 v82, v[150:153] offset:36864
	v_add_co_u32_e32 v82, vcc, s27, v178
	s_lshl_b32 s92, s25, 7
	s_nop 0
	v_addc_co_u32_e32 v83, vcc, 0, v179, vcc
	global_load_dwordx4 v[126:129], v[82:83], off
	v_lshl_add_u64 v[82:83], v[166:167], 0, s[92:93]
	global_load_dwordx4 v[122:125], v[82:83], off
	v_add_u32_e32 v111, s26, v163
	v_add_f32_e32 v1, v1, v110
	ds_read_b128 v[240:243], v165 offset:9216
	ds_read_b128 v[244:247], v165 offset:13824
	ds_read_b128 v[82:85], v111 offset:41472
	ds_read_b128 v[86:89], v111 offset:36864
	ds_read_b128 v[90:93], v111 offset:36896
	ds_read_b128 v[94:97], v111 offset:41504
	ds_read_b128 v[98:101], v111 offset:36928
	ds_read_b128 v[102:105], v111 offset:41536
	ds_read_b128 v[106:109], v111 offset:36960
	ds_read_b128 v[110:113], v111 offset:41568
	s_add_i32 s26, s24, 1
	s_setprio 1
	v_cvt_pk_bf16_f32 v130, v185, v186
	v_cvt_pk_bf16_f32 v131, v187, v194
	v_cvt_pk_bf16_f32 v132, v195, v196
	v_cvt_pk_bf16_f32 v133, v197, v198
	s_waitcnt lgkmcnt(6)
	s_nop 0
	v_mfma_f32_32x32x16_bf16 v[18:33], v[86:89], v[130:133], v[18:33]
	v_mov_b32_e32 v146, v185
	v_add_f32_e32 v146, v146, v186
	v_add_f32_e32 v146, v146, v187
	v_add_f32_e32 v146, v146, v194
	s_nop 0
	v_mfma_f32_32x32x16_bf16 v[2:17], v[82:85], v[130:133], v[2:17]
	v_cvt_pk_bf16_f32 v86, v134, v135
	v_cvt_pk_bf16_f32 v87, v136, v137
	v_cvt_pk_bf16_f32 v88, v138, v139
	v_cvt_pk_bf16_f32 v89, v140, v141
	v_add_f32_e32 v146, v146, v195
	v_add_f32_e32 v146, v146, v196
	v_add_f32_e32 v146, v146, v197
	v_add_f32_e32 v146, v146, v198
	s_waitcnt lgkmcnt(5)
	v_mfma_f32_32x32x16_bf16 v[18:33], v[90:93], v[86:89], v[18:33]
	v_add_f32_e32 v146, v146, v134
	v_add_f32_e32 v146, v146, v135
	v_add_f32_e32 v146, v146, v136
	v_add_f32_e32 v146, v146, v137
	s_waitcnt lgkmcnt(4)
	v_mfma_f32_32x32x16_bf16 v[2:17], v[94:97], v[86:89], v[2:17]
	v_cvt_pk_bf16_f32 v82, v142, v143
	v_cvt_pk_bf16_f32 v83, v144, v145
	v_cvt_pk_bf16_f32 v84, v199, v200
	v_cvt_pk_bf16_f32 v85, v201, v202
	v_add_f32_e32 v146, v146, v138
	v_add_f32_e32 v146, v146, v139
	v_add_f32_e32 v146, v146, v140
	v_add_f32_e32 v146, v146, v141
	s_waitcnt lgkmcnt(3)
	v_mfma_f32_32x32x16_bf16 v[18:33], v[98:101], v[82:85], v[18:33]
	v_add_f32_e32 v146, v146, v142
	v_add_f32_e32 v146, v146, v143
	v_add_f32_e32 v146, v146, v144
	v_add_f32_e32 v146, v146, v145
	s_waitcnt lgkmcnt(2)
	v_mfma_f32_32x32x16_bf16 v[2:17], v[102:105], v[82:85], v[2:17]
	v_cvt_pk_bf16_f32 v86, v203, v204
	v_cvt_pk_bf16_f32 v87, v205, v206
	v_cvt_pk_bf16_f32 v88, v207, v208
	v_cvt_pk_bf16_f32 v89, v209, v210
	v_add_f32_e32 v146, v146, v199
	v_add_f32_e32 v146, v146, v200
	v_add_f32_e32 v146, v146, v201
	v_add_f32_e32 v146, v146, v202
	s_waitcnt lgkmcnt(1)
	v_mfma_f32_32x32x16_bf16 v[18:33], v[106:109], v[86:89], v[18:33]
	v_add_f32_e32 v146, v146, v203
	v_add_f32_e32 v146, v146, v204
	v_add_f32_e32 v146, v146, v205
	v_add_f32_e32 v146, v146, v206
	s_waitcnt lgkmcnt(0)
	v_mfma_f32_32x32x16_bf16 v[2:17], v[110:113], v[86:89], v[2:17]
	v_add_f32_e32 v146, v146, v207
	v_add_f32_e32 v146, v146, v208
	v_add_f32_e32 v146, v146, v209
	v_add_f32_e32 v146, v146, v210
	s_setprio 0
	ds_read_b128 v[130:133], v165 offset:9248
	ds_read_b128 v[138:141], v165 offset:13856
	s_cmp_lg_u32 s24, 4
	s_cselect_b32 s24, s26, 0
	s_waitcnt lgkmcnt(2)
	v_mfma_f32_32x32x16_bf16 v[98:113], v[240:243], v[158:161], v[34:49]
	v_exp_f32_e32 v142, v66
	v_exp_f32_e32 v143, v67
	v_exp_f32_e32 v144, v68
	v_exp_f32_e32 v145, v69
	v_exp_f32_e32 v147, v70
	v_exp_f32_e32 v148, v71
	v_exp_f32_e32 v149, v72
	v_exp_f32_e32 v150, v73
	s_waitcnt lgkmcnt(1)
	v_mfma_f32_32x32x16_bf16 v[82:97], v[244:247], v[158:161], v[34:49]
	v_exp_f32_e32 v151, v74
	v_exp_f32_e32 v152, v75
	v_exp_f32_e32 v153, v76
	v_exp_f32_e32 v178, v77
	v_exp_f32_e32 v134, v78
	v_exp_f32_e32 v135, v79
	v_exp_f32_e32 v136, v80
	v_exp_f32_e32 v137, v81
	v_mfma_f32_32x32x16_bf16 v[98:113], v[130:133], v[154:157], v[98:113]
	v_exp_f32_e32 v179, v50
	v_exp_f32_e32 v185, v51
	v_exp_f32_e32 v186, v52
	v_exp_f32_e32 v187, v53
	v_exp_f32_e32 v194, v54
	v_exp_f32_e32 v195, v55
	v_exp_f32_e32 v196, v56
	v_exp_f32_e32 v197, v57
	s_waitcnt lgkmcnt(0)
	v_mfma_f32_32x32x16_bf16 v[82:97], v[138:141], v[154:157], v[82:97]
	v_exp_f32_e32 v198, v58
	v_exp_f32_e32 v199, v59
	v_exp_f32_e32 v200, v60
	v_exp_f32_e32 v201, v61
	v_exp_f32_e32 v138, v62
	v_exp_f32_e32 v139, v63
	v_exp_f32_e32 v140, v64
	v_exp_f32_e32 v141, v65
	s_cmp_gt_i32 s24, 2
	s_cselect_b32 s25, -3, 2
	s_add_i32 s25, s25, s24
	s_mulk_i32 s25, 0x2400
	v_add_u32_e32 v50, s25, v182
	s_add_i32 s25, s24, 1
	s_cmp_lg_u32 s24, 4
	s_cselect_b32 s25, s25, 0
	s_add_i32 s24, s23, -3
	s_min_u32 s26, s24, s13
	s_lshl_b32 s92, s26, 13
	s_waitcnt vmcnt(3)
	ds_write_b128 v182, v[118:121] offset:27648
	s_waitcnt vmcnt(2)
	ds_write_b128 v50, v[114:117] offset:36864
	v_lshl_add_u64 v[50:51], v[168:169], 0, s[92:93]
	global_load_dwordx4 v[118:121], v[50:51], off
	global_load_dwordx4 v[114:117], v[176:177], off offset:1024
	s_mul_i32 s27, s25, 0x2400
	s_add_i32 s28, s27, 0xffffdc00
	s_cmp_lg_u32 s25, 0
	s_cselect_b32 s28, s28, 0x9000
	v_add_u32_e32 v78, s28, v163
	ds_read_b128 v[50:53], v78 offset:36864
	ds_read_b128 v[54:57], v78 offset:36896
	ds_read_b128 v[58:61], v78 offset:41472
	ds_read_b128 v[62:65], v78 offset:41504
	ds_read_b128 v[66:69], v78 offset:36928
	ds_read_b128 v[70:73], v78 offset:36960
	ds_read_b128 v[74:77], v78 offset:41536
	ds_read_b128 v[78:81], v78 offset:41568
	s_setprio 3
	v_cvt_pk_bf16_f32 v130, v142, v143
	v_cvt_pk_bf16_f32 v131, v144, v145
	v_cvt_pk_bf16_f32 v132, v147, v148
	v_cvt_pk_bf16_f32 v133, v149, v150
	s_waitcnt lgkmcnt(7)
	s_nop 0
	v_mfma_f32_32x32x16_bf16 v[18:33], v[50:53], v[130:133], v[18:33]
	v_mov_b32_e32 v176, v142
	v_add_f32_e32 v176, v176, v143
	v_add_f32_e32 v176, v176, v144
	v_add_f32_e32 v176, v176, v145
	s_waitcnt lgkmcnt(5)
	v_mfma_f32_32x32x16_bf16 v[2:17], v[58:61], v[130:133], v[2:17]
	v_cvt_pk_bf16_f32 v50, v151, v152
	v_cvt_pk_bf16_f32 v51, v153, v178
	v_cvt_pk_bf16_f32 v52, v134, v135
	v_cvt_pk_bf16_f32 v53, v136, v137
	v_add_f32_e32 v176, v176, v147
	v_add_f32_e32 v176, v176, v148
	v_add_f32_e32 v176, v176, v149
	v_add_f32_e32 v176, v176, v150
	s_nop 0
	v_mfma_f32_32x32x16_bf16 v[18:33], v[54:57], v[50:53], v[18:33]
	v_add_f32_e32 v176, v176, v151
	v_add_f32_e32 v176, v176, v152
	v_add_f32_e32 v176, v176, v153
	v_add_f32_e32 v176, v176, v178
	s_waitcnt lgkmcnt(4)
	v_mfma_f32_32x32x16_bf16 v[2:17], v[62:65], v[50:53], v[2:17]
	v_cvt_pk_bf16_f32 v54, v179, v185
	v_cvt_pk_bf16_f32 v55, v186, v187
	v_cvt_pk_bf16_f32 v56, v194, v195
	v_cvt_pk_bf16_f32 v57, v196, v197
	v_add_f32_e32 v176, v176, v134
	v_add_f32_e32 v176, v176, v135
	v_add_f32_e32 v176, v176, v136
	v_add_f32_e32 v176, v176, v137
	s_waitcnt lgkmcnt(3)
	v_mfma_f32_32x32x16_bf16 v[18:33], v[66:69], v[54:57], v[18:33]
	v_add_f32_e32 v176, v176, v179
	v_add_f32_e32 v176, v176, v185
	v_add_f32_e32 v176, v176, v186
	v_add_f32_e32 v176, v176, v187
	s_waitcnt lgkmcnt(1)
	v_mfma_f32_32x32x16_bf16 v[2:17], v[74:77], v[54:57], v[2:17]
	v_cvt_pk_bf16_f32 v50, v198, v199
	v_cvt_pk_bf16_f32 v51, v200, v201
	v_cvt_pk_bf16_f32 v52, v138, v139
	v_cvt_pk_bf16_f32 v53, v140, v141
	v_add_f32_e32 v176, v176, v194
	v_add_f32_e32 v176, v176, v195
	v_add_f32_e32 v176, v176, v196
	v_add_f32_e32 v176, v176, v197
	s_nop 0
	v_mfma_f32_32x32x16_bf16 v[18:33], v[70:73], v[50:53], v[18:33]
	v_add_f32_e32 v176, v176, v198
	v_add_f32_e32 v176, v176, v199
	v_add_f32_e32 v176, v176, v200
	v_add_f32_e32 v176, v176, v201
	s_waitcnt lgkmcnt(0)
	v_mfma_f32_32x32x16_bf16 v[2:17], v[78:81], v[50:53], v[2:17]
	v_add_f32_e32 v176, v176, v138
	v_add_f32_e32 v176, v176, v139
	v_add_f32_e32 v176, v176, v140
	v_add_f32_e32 v176, v176, v141
	s_setprio 2
	s_waitcnt lgkmcnt(0)
	s_barrier
	ds_read_b128 v[240:243], v165 offset:18432
	ds_read_b128 v[244:247], v165 offset:23040
	ds_read_b128 v[134:137], v165 offset:18464
	ds_read_b128 v[138:141], v165 offset:23072
	v_add_f32_e32 v1, v1, v146
	s_waitcnt lgkmcnt(2)
	v_mfma_f32_32x32x16_bf16 v[66:81], v[240:243], v[158:161], v[34:49]
	v_exp_f32_e32 v142, v98
	v_exp_f32_e32 v143, v99
	v_exp_f32_e32 v144, v100
	v_exp_f32_e32 v145, v101
	v_exp_f32_e32 v146, v102
	v_exp_f32_e32 v147, v103
	v_exp_f32_e32 v148, v104
	v_exp_f32_e32 v149, v105
	v_mfma_f32_32x32x16_bf16 v[50:65], v[244:247], v[158:161], v[34:49]
	v_exp_f32_e32 v150, v106
	v_exp_f32_e32 v151, v107
	v_exp_f32_e32 v152, v108
	v_exp_f32_e32 v153, v109
	v_exp_f32_e32 v177, v110
	v_exp_f32_e32 v178, v111
	v_exp_f32_e32 v179, v112
	v_exp_f32_e32 v185, v113
	s_waitcnt lgkmcnt(1)
	v_mfma_f32_32x32x16_bf16 v[66:81], v[134:137], v[154:157], v[66:81]
	v_exp_f32_e32 v186, v82
	v_exp_f32_e32 v187, v83
	v_exp_f32_e32 v194, v84
	v_exp_f32_e32 v195, v85
	v_exp_f32_e32 v134, v86
	v_exp_f32_e32 v135, v87
	v_exp_f32_e32 v136, v88
	v_exp_f32_e32 v137, v89
	s_waitcnt lgkmcnt(0)
	v_mfma_f32_32x32x16_bf16 v[50:65], v[138:141], v[154:157], v[50:65]
	v_exp_f32_e32 v196, v90
	v_exp_f32_e32 v197, v91
	v_exp_f32_e32 v198, v92
	v_exp_f32_e32 v199, v93
	v_exp_f32_e32 v138, v94
	v_exp_f32_e32 v139, v95
	v_exp_f32_e32 v140, v96
	v_exp_f32_e32 v141, v97
	s_cmp_gt_i32 s25, 2
	s_cselect_b32 s28, -3, 2
	s_waitcnt vmcnt(3)
	ds_write_b128 v182, v[126:129]
	s_add_i32 s28, s28, s25
	v_add_u32_e32 v126, s27, v163
	s_add_i32 s27, s23, -2
	s_mulk_i32 s28, 0x2400
	s_min_u32 s27, s27, s13
	v_add_u32_e32 v82, s28, v182
	s_lshl_b32 s92, s27, 13
	s_waitcnt vmcnt(2)
	ds_write_b128 v82, v[122:125] offset:36864
	v_lshl_add_u64 v[82:83], v[168:169], 0, s[92:93]
	s_lshl_b32 s92, s26, 7
	global_load_dwordx4 v[98:101], v[82:83], off
	v_lshl_add_u64 v[82:83], v[166:167], 0, s[92:93]
	global_load_dwordx4 v[102:105], v[82:83], off
	ds_read_b128 v[240:243], v165 offset:27648
	ds_read_b128 v[244:247], v165 offset:32256
	ds_read_b128 v[82:85], v126 offset:41472
	ds_read_b128 v[86:89], v126 offset:36864
	ds_read_b128 v[90:93], v126 offset:36896
	ds_read_b128 v[94:97], v126 offset:41504
	ds_read_b128 v[106:109], v126 offset:36928
	ds_read_b128 v[110:113], v126 offset:41536
	ds_read_b128 v[122:125], v126 offset:36960
	ds_read_b128 v[126:129], v126 offset:41568
	v_add_f32_e32 v1, v1, v176
	s_add_i32 s28, s25, 1
	s_setprio 1
	v_cvt_pk_bf16_f32 v130, v142, v143
	v_cvt_pk_bf16_f32 v131, v144, v145
	v_cvt_pk_bf16_f32 v132, v146, v147
	v_cvt_pk_bf16_f32 v133, v148, v149
	s_waitcnt lgkmcnt(6)
	s_nop 0
	v_mfma_f32_32x32x16_bf16 v[18:33], v[86:89], v[130:133], v[18:33]
	v_mov_b32_e32 v176, v142
	v_add_f32_e32 v176, v176, v143
	v_add_f32_e32 v176, v176, v144
	v_add_f32_e32 v176, v176, v145
	s_nop 0
	v_mfma_f32_32x32x16_bf16 v[2:17], v[82:85], v[130:133], v[2:17]
	v_cvt_pk_bf16_f32 v86, v150, v151
	v_cvt_pk_bf16_f32 v87, v152, v153
	v_cvt_pk_bf16_f32 v88, v177, v178
	v_cvt_pk_bf16_f32 v89, v179, v185
	v_add_f32_e32 v176, v176, v146
	v_add_f32_e32 v176, v176, v147
	v_add_f32_e32 v176, v176, v148
	v_add_f32_e32 v176, v176, v149
	s_waitcnt lgkmcnt(5)
	v_mfma_f32_32x32x16_bf16 v[18:33], v[90:93], v[86:89], v[18:33]
	v_add_f32_e32 v176, v176, v150
	v_add_f32_e32 v176, v176, v151
	v_add_f32_e32 v176, v176, v152
	v_add_f32_e32 v176, v176, v153
	s_waitcnt lgkmcnt(4)
	v_mfma_f32_32x32x16_bf16 v[2:17], v[94:97], v[86:89], v[2:17]
	v_cvt_pk_bf16_f32 v82, v186, v187
	v_cvt_pk_bf16_f32 v83, v194, v195
	v_cvt_pk_bf16_f32 v84, v134, v135
	v_cvt_pk_bf16_f32 v85, v136, v137
	v_add_f32_e32 v176, v176, v177
	v_add_f32_e32 v176, v176, v178
	v_add_f32_e32 v176, v176, v179
	v_add_f32_e32 v176, v176, v185
	s_waitcnt lgkmcnt(3)
	v_mfma_f32_32x32x16_bf16 v[18:33], v[106:109], v[82:85], v[18:33]
	v_add_f32_e32 v176, v176, v186
	v_add_f32_e32 v176, v176, v187
	v_add_f32_e32 v176, v176, v194
	v_add_f32_e32 v176, v176, v195
	s_waitcnt lgkmcnt(2)
	v_mfma_f32_32x32x16_bf16 v[2:17], v[110:113], v[82:85], v[2:17]
	v_cvt_pk_bf16_f32 v86, v196, v197
	v_cvt_pk_bf16_f32 v87, v198, v199
	v_cvt_pk_bf16_f32 v88, v138, v139
	v_cvt_pk_bf16_f32 v89, v140, v141
	v_add_f32_e32 v176, v176, v134
	v_add_f32_e32 v176, v176, v135
	v_add_f32_e32 v176, v176, v136
	v_add_f32_e32 v176, v176, v137
	s_waitcnt lgkmcnt(1)
	v_mfma_f32_32x32x16_bf16 v[18:33], v[122:125], v[86:89], v[18:33]
	v_add_f32_e32 v176, v176, v196
	v_add_f32_e32 v176, v176, v197
	v_add_f32_e32 v176, v176, v198
	v_add_f32_e32 v176, v176, v199
	s_waitcnt lgkmcnt(0)
	v_mfma_f32_32x32x16_bf16 v[2:17], v[126:129], v[86:89], v[2:17]
	v_add_f32_e32 v176, v176, v138
	v_add_f32_e32 v176, v176, v139
	v_add_f32_e32 v176, v176, v140
	v_add_f32_e32 v176, v176, v141
	s_setprio 0
	ds_read_b128 v[106:109], v165 offset:27680
	ds_read_b128 v[122:125], v165 offset:32288
	s_cmp_lg_u32 s25, 4
	s_cselect_b32 s25, s28, 0
	s_waitcnt lgkmcnt(2)
	v_mfma_f32_32x32x16_bf16 v[138:153], v[240:243], v[158:161], v[34:49]
	v_exp_f32_e32 v126, v66
	v_exp_f32_e32 v127, v67
	v_exp_f32_e32 v128, v68
	v_exp_f32_e32 v129, v69
	v_exp_f32_e32 v130, v70
	v_exp_f32_e32 v131, v71
	v_exp_f32_e32 v132, v72
	v_exp_f32_e32 v133, v73
	s_waitcnt lgkmcnt(1)
	v_mfma_f32_32x32x16_bf16 v[82:97], v[244:247], v[158:161], v[34:49]
	v_exp_f32_e32 v134, v74
	v_exp_f32_e32 v135, v75
	v_exp_f32_e32 v136, v76
	v_exp_f32_e32 v137, v77
	v_exp_f32_e32 v177, v78
	v_exp_f32_e32 v178, v79
	v_exp_f32_e32 v179, v80
	v_exp_f32_e32 v185, v81
	v_mfma_f32_32x32x16_bf16 v[138:153], v[106:109], v[154:157], v[138:153]
	v_exp_f32_e32 v80, v50
	v_exp_f32_e32 v81, v51
	v_exp_f32_e32 v186, v52
	v_exp_f32_e32 v187, v53
	v_exp_f32_e32 v194, v54
	v_exp_f32_e32 v195, v55
	v_exp_f32_e32 v196, v56
	v_exp_f32_e32 v197, v57
	s_waitcnt lgkmcnt(0)
	v_mfma_f32_32x32x16_bf16 v[82:97], v[122:125], v[154:157], v[82:97]
	v_exp_f32_e32 v198, v58
	v_exp_f32_e32 v199, v59
	v_exp_f32_e32 v200, v60
	v_exp_f32_e32 v201, v61
	v_exp_f32_e32 v122, v62
	v_exp_f32_e32 v123, v63
	v_exp_f32_e32 v124, v64
	v_exp_f32_e32 v125, v65
	s_cmp_gt_i32 s25, 2
	s_cselect_b32 s26, -3, 2
	s_add_i32 s26, s26, s25
	s_mulk_i32 s26, 0x2400
	v_add_u32_e32 v50, s26, v182
	s_add_i32 s26, s25, 1
	s_cmp_lg_u32 s25, 4
	s_cselect_b32 s25, s26, 0
	s_add_i32 s26, s23, -1
	s_min_u32 s26, s26, s13
	s_lshl_b32 s92, s26, 13
	s_waitcnt vmcnt(3)
	ds_write_b128 v182, v[118:121] offset:9216
	s_waitcnt vmcnt(2)
	ds_write_b128 v50, v[114:117] offset:36864
	v_lshl_add_u64 v[50:51], v[168:169], 0, s[92:93]
	s_lshl_b32 s92, s27, 7
	v_lshl_add_u64 v[52:53], v[166:167], 0, s[92:93]
	global_load_dwordx4 v[56:59], v[50:51], off
	s_nop 0
	global_load_dwordx4 v[52:55], v[52:53], off
	s_mul_i32 s27, s25, 0x2400
	s_add_i32 s28, s27, 0xffffdc00
	s_cmp_lg_u32 s25, 0
	s_cselect_b32 s28, s28, 0x9000
	v_add_u32_e32 v50, s28, v163
	ds_read_b128 v[60:63], v50 offset:36864
	ds_read_b128 v[64:67], v50 offset:36896
	ds_read_b128 v[68:71], v50 offset:41472
	ds_read_b128 v[72:75], v50 offset:41504
	ds_read_b128 v[76:79], v50 offset:36928
	ds_read_b128 v[106:109], v50 offset:36960
	ds_read_b128 v[110:113], v50 offset:41536
	ds_read_b128 v[114:117], v50 offset:41568
	s_setprio 3
	v_cvt_pk_bf16_f32 v118, v126, v127
	v_cvt_pk_bf16_f32 v119, v128, v129
	v_cvt_pk_bf16_f32 v120, v130, v131
	v_cvt_pk_bf16_f32 v121, v132, v133
	s_waitcnt lgkmcnt(7)
	s_nop 0
	v_mfma_f32_32x32x16_bf16 v[18:33], v[60:63], v[118:121], v[18:33]
	v_mov_b32_e32 v50, v126
	v_add_f32_e32 v50, v50, v127
	v_add_f32_e32 v50, v50, v128
	v_add_f32_e32 v50, v50, v129
	s_waitcnt lgkmcnt(5)
	v_mfma_f32_32x32x16_bf16 v[2:17], v[68:71], v[118:121], v[2:17]
	v_cvt_pk_bf16_f32 v60, v134, v135
	v_cvt_pk_bf16_f32 v61, v136, v137
	v_cvt_pk_bf16_f32 v62, v177, v178
	v_cvt_pk_bf16_f32 v63, v179, v185
	v_add_f32_e32 v50, v50, v130
	v_add_f32_e32 v50, v50, v131
	v_add_f32_e32 v50, v50, v132
	v_add_f32_e32 v50, v50, v133
	s_nop 0
	v_mfma_f32_32x32x16_bf16 v[18:33], v[64:67], v[60:63], v[18:33]
	v_add_f32_e32 v50, v50, v134
	v_add_f32_e32 v50, v50, v135
	v_add_f32_e32 v50, v50, v136
	v_add_f32_e32 v50, v50, v137
	s_waitcnt lgkmcnt(4)
	v_mfma_f32_32x32x16_bf16 v[2:17], v[72:75], v[60:63], v[2:17]
	v_cvt_pk_bf16_f32 v64, v80, v81
	v_cvt_pk_bf16_f32 v65, v186, v187
	v_cvt_pk_bf16_f32 v66, v194, v195
	v_cvt_pk_bf16_f32 v67, v196, v197
	v_add_f32_e32 v50, v50, v177
	v_add_f32_e32 v50, v50, v178
	v_add_f32_e32 v50, v50, v179
	v_add_f32_e32 v50, v50, v185
	s_waitcnt lgkmcnt(3)
	v_mfma_f32_32x32x16_bf16 v[18:33], v[76:79], v[64:67], v[18:33]
	v_add_f32_e32 v50, v50, v80
	v_add_f32_e32 v50, v50, v81
	v_add_f32_e32 v50, v50, v186
	v_add_f32_e32 v50, v50, v187
	s_waitcnt lgkmcnt(1)
	v_mfma_f32_32x32x16_bf16 v[2:17], v[110:113], v[64:67], v[2:17]
	v_cvt_pk_bf16_f32 v60, v198, v199
	v_cvt_pk_bf16_f32 v61, v200, v201
	v_cvt_pk_bf16_f32 v62, v122, v123
	v_cvt_pk_bf16_f32 v63, v124, v125
	v_add_f32_e32 v50, v50, v194
	v_add_f32_e32 v50, v50, v195
	v_add_f32_e32 v50, v50, v196
	v_add_f32_e32 v50, v50, v197
	s_nop 0
	v_mfma_f32_32x32x16_bf16 v[18:33], v[106:109], v[60:63], v[18:33]
	v_add_f32_e32 v50, v50, v198
	v_add_f32_e32 v50, v50, v199
	v_add_f32_e32 v50, v50, v200
	v_add_f32_e32 v50, v50, v201
	s_waitcnt lgkmcnt(0)
	v_mfma_f32_32x32x16_bf16 v[2:17], v[114:117], v[60:63], v[2:17]
	v_add_f32_e32 v50, v50, v122
	v_add_f32_e32 v50, v50, v123
	v_add_f32_e32 v50, v50, v124
	v_add_f32_e32 v50, v50, v125
	s_setprio 2
	s_waitcnt lgkmcnt(0)
	s_barrier
	ds_read_b128 v[240:243], v165
	ds_read_b128 v[244:247], v165 offset:4608
	ds_read_b128 v[68:71], v165 offset:32
	ds_read_b128 v[72:75], v165 offset:4640
	v_add_f32_e32 v1, v1, v176
	s_waitcnt lgkmcnt(2)
	v_mfma_f32_32x32x16_bf16 v[122:137], v[240:243], v[158:161], v[34:49]
	v_exp_f32_e32 v176, v138
	v_exp_f32_e32 v177, v139
	v_exp_f32_e32 v178, v140
	v_exp_f32_e32 v179, v141
	v_exp_f32_e32 v185, v142
	v_exp_f32_e32 v186, v143
	v_exp_f32_e32 v187, v144
	v_exp_f32_e32 v194, v145
	v_mfma_f32_32x32x16_bf16 v[106:121], v[244:247], v[158:161], v[34:49]
	v_exp_f32_e32 v195, v146
	v_exp_f32_e32 v196, v147
	v_exp_f32_e32 v197, v148
	v_exp_f32_e32 v198, v149
	v_exp_f32_e32 v146, v150
	v_exp_f32_e32 v147, v151
	v_exp_f32_e32 v148, v152
	v_exp_f32_e32 v149, v153
	s_waitcnt lgkmcnt(1)
	v_mfma_f32_32x32x16_bf16 v[122:137], v[68:71], v[154:157], v[122:137]
	v_exp_f32_e32 v150, v82
	v_exp_f32_e32 v151, v83
	v_exp_f32_e32 v152, v84
	v_exp_f32_e32 v153, v85
	v_exp_f32_e32 v199, v86
	v_exp_f32_e32 v200, v87
	v_exp_f32_e32 v201, v88
	v_exp_f32_e32 v202, v89
	s_waitcnt lgkmcnt(0)
	v_mfma_f32_32x32x16_bf16 v[106:121], v[72:75], v[154:157], v[106:121]
	v_exp_f32_e32 v203, v90
	v_exp_f32_e32 v204, v91
	v_exp_f32_e32 v205, v92
	v_exp_f32_e32 v206, v93
	v_exp_f32_e32 v207, v94
	v_exp_f32_e32 v208, v95
	v_exp_f32_e32 v209, v96
	v_exp_f32_e32 v210, v97
	s_cmp_gt_i32 s25, 2
	s_cselect_b32 s28, -3, 2
	s_add_i32 s28, s28, s25
	s_mulk_i32 s28, 0x2400
	v_add_u32_e32 v88, s27, v163
	s_min_u32 s27, s23, s13
	v_add_u32_e32 v51, s28, v182
	s_lshl_b32 s92, s27, 13
	s_waitcnt vmcnt(3)
	ds_write_b128 v182, v[98:101] offset:18432
	s_waitcnt vmcnt(2)
	ds_write_b128 v51, v[102:105] offset:36864
	v_add_f32_e32 v1, v1, v50
	v_lshl_add_u64 v[50:51], v[168:169], 0, s[92:93]
	s_lshl_b32 s92, s26, 7
	global_load_dwordx4 v[138:141], v[50:51], off
	v_lshl_add_u64 v[50:51], v[166:167], 0, s[92:93]
	global_load_dwordx4 v[142:145], v[50:51], off
	ds_read_b128 v[240:243], v165 offset:9216
	ds_read_b128 v[244:247], v165 offset:13824
	ds_read_b128 v[60:63], v88 offset:41472
	ds_read_b128 v[64:67], v88 offset:36864
	ds_read_b128 v[68:71], v88 offset:36896
	ds_read_b128 v[72:75], v88 offset:41504
	ds_read_b128 v[76:79], v88 offset:36928
	ds_read_b128 v[80:83], v88 offset:41536
	ds_read_b128 v[84:87], v88 offset:36960
	ds_read_b128 v[88:91], v88 offset:41568
	s_setprio 1
	v_mov_b32_e32 v51, v122
	v_cvt_pk_bf16_f32 v92, v176, v177
	v_cvt_pk_bf16_f32 v93, v178, v179
	v_cvt_pk_bf16_f32 v94, v185, v186
	v_cvt_pk_bf16_f32 v95, v187, v194
	s_waitcnt lgkmcnt(6)
	s_nop 0
	v_mfma_f32_32x32x16_bf16 v[18:33], v[64:67], v[92:95], v[18:33]
	v_max3_f32 v51, v51, v123, v124
	v_max3_f32 v51, v51, v125, v126
	v_mov_b32_e32 v50, v176
	v_add_f32_e32 v50, v50, v177
	v_add_f32_e32 v50, v50, v178
	v_add_f32_e32 v50, v50, v179
	s_nop 0
	v_mfma_f32_32x32x16_bf16 v[2:17], v[60:63], v[92:95], v[2:17]
	v_cvt_pk_bf16_f32 v64, v195, v196
	v_cvt_pk_bf16_f32 v65, v197, v198
	v_cvt_pk_bf16_f32 v66, v146, v147
	v_cvt_pk_bf16_f32 v67, v148, v149
	v_max3_f32 v51, v51, v127, v128
	v_max3_f32 v51, v51, v129, v130
	v_add_f32_e32 v50, v50, v185
	v_add_f32_e32 v50, v50, v186
	v_add_f32_e32 v50, v50, v187
	v_add_f32_e32 v50, v50, v194
	s_waitcnt lgkmcnt(5)
	v_mfma_f32_32x32x16_bf16 v[18:33], v[68:71], v[64:67], v[18:33]
	v_max3_f32 v51, v51, v131, v132
	v_max3_f32 v51, v51, v133, v134
	v_add_f32_e32 v50, v50, v195
	v_add_f32_e32 v50, v50, v196
	v_add_f32_e32 v50, v50, v197
	v_add_f32_e32 v50, v50, v198
	s_waitcnt lgkmcnt(4)
	v_mfma_f32_32x32x16_bf16 v[2:17], v[72:75], v[64:67], v[2:17]
	v_cvt_pk_bf16_f32 v60, v150, v151
	v_cvt_pk_bf16_f32 v61, v152, v153
	v_cvt_pk_bf16_f32 v62, v199, v200
	v_cvt_pk_bf16_f32 v63, v201, v202
	v_max3_f32 v51, v51, v135, v136
	v_max3_f32 v51, v51, v137, v106
	v_add_f32_e32 v50, v50, v146
	v_add_f32_e32 v50, v50, v147
	v_add_f32_e32 v50, v50, v148
	v_add_f32_e32 v50, v50, v149
	s_waitcnt lgkmcnt(3)
	v_mfma_f32_32x32x16_bf16 v[18:33], v[76:79], v[60:63], v[18:33]
	v_max3_f32 v51, v51, v107, v108
	v_max3_f32 v51, v51, v109, v110
	v_add_f32_e32 v50, v50, v150
	v_add_f32_e32 v50, v50, v151
	v_add_f32_e32 v50, v50, v152
	v_add_f32_e32 v50, v50, v153
	s_waitcnt lgkmcnt(2)
	v_mfma_f32_32x32x16_bf16 v[2:17], v[80:83], v[60:63], v[2:17]
	v_cvt_pk_bf16_f32 v64, v203, v204
	v_cvt_pk_bf16_f32 v65, v205, v206
	v_cvt_pk_bf16_f32 v66, v207, v208
	v_cvt_pk_bf16_f32 v67, v209, v210
	v_max3_f32 v51, v51, v111, v112
	v_max3_f32 v51, v51, v113, v114
	v_add_f32_e32 v50, v50, v199
	v_add_f32_e32 v50, v50, v200
	v_add_f32_e32 v50, v50, v201
	v_add_f32_e32 v50, v50, v202
	s_waitcnt lgkmcnt(1)
	v_mfma_f32_32x32x16_bf16 v[18:33], v[84:87], v[64:67], v[18:33]
	v_max3_f32 v51, v51, v115, v116
	v_max3_f32 v51, v51, v117, v118
	v_add_f32_e32 v50, v50, v203
	v_add_f32_e32 v50, v50, v204
	v_add_f32_e32 v50, v50, v205
	v_add_f32_e32 v50, v50, v206
	s_waitcnt lgkmcnt(0)
	v_mfma_f32_32x32x16_bf16 v[2:17], v[88:91], v[64:67], v[2:17]
	v_max3_f32 v51, v51, v119, v120
	v_max3_f32 v51, v51, v121, v121
	v_add_f32_e32 v50, v50, v207
	v_add_f32_e32 v50, v50, v208
	v_add_f32_e32 v50, v50, v209
	v_add_f32_e32 v50, v50, v210
	s_setprio 0
	ds_read_b128 v[146:149], v165 offset:9248
	ds_read_b128 v[60:63], v165 offset:13856
	v_add_f32_e32 v50, v1, v50
	v_mov_b32_e32 v1, v51
	s_nop 1
	v_permlane32_swap_b32_e32 v51, v1
	v_max_f32_e32 v1, v1, v1
	v_max_f32_e32 v51, v51, v51
	v_max_f32_e32 v1, v51, v1
	v_cmp_lt_f32_e32 vcc, s52, v1
	s_cbranch_vccz .LBB0_643
	v_max_f32_e32 v1, v1, v1
	v_max_f32_e32 v68, 0, v1
	v_add_f32_e32 v183, v183, v68
	v_xor_b32_e32 v34, 0x80000000, v183
	v_pk_add_f32 v[122:123], v[122:123], v[68:69] op_sel_hi:[1,0] neg_lo:[0,1] neg_hi:[0,1]
	v_pk_add_f32 v[106:107], v[106:107], v[68:69] op_sel_hi:[1,0] neg_lo:[0,1] neg_hi:[0,1]
	v_pk_add_f32 v[124:125], v[124:125], v[68:69] op_sel_hi:[1,0] neg_lo:[0,1] neg_hi:[0,1]
	v_pk_add_f32 v[108:109], v[108:109], v[68:69] op_sel_hi:[1,0] neg_lo:[0,1] neg_hi:[0,1]
	v_pk_add_f32 v[126:127], v[126:127], v[68:69] op_sel_hi:[1,0] neg_lo:[0,1] neg_hi:[0,1]
	v_pk_add_f32 v[110:111], v[110:111], v[68:69] op_sel_hi:[1,0] neg_lo:[0,1] neg_hi:[0,1]
	v_pk_add_f32 v[128:129], v[128:129], v[68:69] op_sel_hi:[1,0] neg_lo:[0,1] neg_hi:[0,1]
	v_pk_add_f32 v[112:113], v[112:113], v[68:69] op_sel_hi:[1,0] neg_lo:[0,1] neg_hi:[0,1]
	v_pk_add_f32 v[130:131], v[130:131], v[68:69] op_sel_hi:[1,0] neg_lo:[0,1] neg_hi:[0,1]
	v_pk_add_f32 v[114:115], v[114:115], v[68:69] op_sel_hi:[1,0] neg_lo:[0,1] neg_hi:[0,1]
	v_pk_add_f32 v[132:133], v[132:133], v[68:69] op_sel_hi:[1,0] neg_lo:[0,1] neg_hi:[0,1]
	v_pk_add_f32 v[116:117], v[116:117], v[68:69] op_sel_hi:[1,0] neg_lo:[0,1] neg_hi:[0,1]
	v_pk_add_f32 v[134:135], v[134:135], v[68:69] op_sel_hi:[1,0] neg_lo:[0,1] neg_hi:[0,1]
	v_pk_add_f32 v[118:119], v[118:119], v[68:69] op_sel_hi:[1,0] neg_lo:[0,1] neg_hi:[0,1]
	v_pk_add_f32 v[136:137], v[136:137], v[68:69] op_sel_hi:[1,0] neg_lo:[0,1] neg_hi:[0,1]
	v_pk_add_f32 v[120:121], v[120:121], v[68:69] op_sel_hi:[1,0] neg_lo:[0,1] neg_hi:[0,1]
	v_exp_f32_e64 v68, -v68
	v_mov_b32_e32 v35, v34
	v_mov_b32_e32 v36, v34
	v_mov_b32_e32 v37, v34
	v_mov_b32_e32 v38, v34
	v_mov_b32_e32 v39, v34
	v_mov_b32_e32 v40, v34
	v_mov_b32_e32 v41, v34
	v_mov_b32_e32 v42, v34
	v_mov_b32_e32 v43, v34
	v_mov_b32_e32 v44, v34
	v_mov_b32_e32 v45, v34
	v_mov_b32_e32 v46, v34
	v_mov_b32_e32 v47, v34
	v_mov_b32_e32 v48, v34
	v_mov_b32_e32 v49, v34
	s_nop 11
	v_pk_mul_f32 v[32:33], v[32:33], v[68:69] op_sel_hi:[1,0]
	v_pk_mul_f32 v[30:31], v[30:31], v[68:69] op_sel_hi:[1,0]
	v_pk_mul_f32 v[28:29], v[28:29], v[68:69] op_sel_hi:[1,0]
	v_pk_mul_f32 v[26:27], v[26:27], v[68:69] op_sel_hi:[1,0]
	v_pk_mul_f32 v[24:25], v[24:25], v[68:69] op_sel_hi:[1,0]
	v_pk_mul_f32 v[22:23], v[22:23], v[68:69] op_sel_hi:[1,0]
	v_pk_mul_f32 v[20:21], v[20:21], v[68:69] op_sel_hi:[1,0]
	v_pk_mul_f32 v[18:19], v[18:19], v[68:69] op_sel_hi:[1,0]
	v_pk_mul_f32 v[16:17], v[16:17], v[68:69] op_sel_hi:[1,0]
	v_pk_mul_f32 v[14:15], v[14:15], v[68:69] op_sel_hi:[1,0]
	v_pk_mul_f32 v[12:13], v[12:13], v[68:69] op_sel_hi:[1,0]
	v_pk_mul_f32 v[10:11], v[10:11], v[68:69] op_sel_hi:[1,0]
	v_pk_mul_f32 v[8:9], v[8:9], v[68:69] op_sel_hi:[1,0]
	v_pk_mul_f32 v[6:7], v[6:7], v[68:69] op_sel_hi:[1,0]
	v_pk_mul_f32 v[4:5], v[4:5], v[68:69] op_sel_hi:[1,0]
	v_pk_mul_f32 v[2:3], v[2:3], v[68:69] op_sel_hi:[1,0]
	v_mul_f32_e32 v50, v50, v68

.LBB0_658:
	s_lshl_b32 s1, s0, 1
	s_xor_b64 s[26:27], s[12:13], -1
	s_lshl_b32 s63, s73, 7
	s_add_i32 s19, s1, s74
	s_lshl_b32 s23, s74, 1
	s_lshl_b32 s24, s0, 2
	s_ashr_i32 s22, s63, 31
	s_mul_hi_u32 s18, s19, 0x208000
	s_mul_i32 s19, s19, 0x208000
	s_mov_b64 s[12:13], -1
	s_and_b64 vcc, exec, s[26:27]
	s_cbranch_vccz .LBB0_694
	v_mov_b32_e32 v76, v222
	v_mov_b32_e32 v53, v0
	v_readfirstlane_b32 s1, v76
	s_ashr_i32 s25, s1, 8
	s_add_i32 s25, s25, s23
	s_lshr_b32 s1, s1, 1
	s_add_i32 s2, s25, s24
	s_and_b32 s1, s1, 0x60
	s_mul_hi_i32 s12, s2, 0x4100
	s_mulk_i32 s2, 0x4100
	s_add_u32 s2, s2, s63
	v_and_b32_e32 v207, 31, v76
	s_addc_u32 s12, s12, s22
	s_or_b32 s2, s2, s1
	v_or_b32_e32 v2, s2, v207
	v_mov_b32_e32 v3, s12
	v_bfe_u32 v206, v76, 5, 1
	v_lshlrev_b64 v[2:3], 7, v[2:3]
	v_lshl_add_u64 v[2:3], s[14:15], 0, v[2:3]
	v_lshlrev_b32_e32 v52, 4, v206
	s_add_u32 s12, s40, s19
	v_lshl_add_u64 v[2:3], v[2:3], 0, v[52:53]
	s_addc_u32 s13, s41, s18
	v_ashrrev_i32_e32 v74, 3, v76
	global_load_dwordx4 v[180:183], v[2:3], off
	global_load_dwordx4 v[176:179], v[2:3], off offset:32
	global_load_dwordx4 v[172:175], v[2:3], off offset:64
	global_load_dwordx4 v[168:171], v[2:3], off offset:96
	s_add_u32 s26, s38, s19
	v_ashrrev_i32_e32 v75, 31, v74
	v_mov_b64_e32 v[2:3], s[12:13]
	v_lshlrev_b32_e32 v1, 4, v76
	s_addc_u32 s27, s39, s18
	v_lshlrev_b64 v[72:73], 7, v[74:75]
	v_mad_i64_i32 v[2:3], s[12:13], v74, s55, v[2:3]
	v_and_b32_e32 v54, 0x70, v1
	v_mov_b32_e32 v55, v0
	v_lshl_add_u64 v[196:197], v[2:3], 0, v[54:55]
	v_lshl_add_u64 v[2:3], s[26:27], 0, v[72:73]
	v_lshl_add_u64 v[198:199], v[2:3], 0, v[54:55]
	v_add_co_u32_e32 v44, vcc, s3, v198
	v_mov_b32_e32 v14, v0
	v_mov_b32_e32 v15, v0
	v_addc_co_u32_e32 v45, vcc, 0, v199, vcc
	v_mov_b32_e32 v1, v0
	v_mov_b32_e32 v2, v0
	v_mov_b32_e32 v3, v0
	v_mov_b32_e32 v4, v0
	v_mov_b32_e32 v5, v0
	v_mov_b32_e32 v6, v0
	v_mov_b32_e32 v7, v0
	v_mov_b32_e32 v8, v0
	v_mov_b32_e32 v9, v0
	v_mov_b32_e32 v10, v0
	v_mov_b32_e32 v11, v0
	v_mov_b32_e32 v12, v0
	v_mov_b32_e32 v13, v0
	v_mov_b64_e32 v[30:31], v[14:15]
	v_add_co_u32_e32 v48, vcc, s59, v198
	v_mov_b64_e32 v[28:29], v[12:13]
	v_mov_b64_e32 v[26:27], v[10:11]
	v_mov_b64_e32 v[24:25], v[8:9]
	v_mov_b64_e32 v[22:23], v[6:7]
	v_mov_b64_e32 v[20:21], v[4:5]
	v_mov_b64_e32 v[18:19], v[2:3]
	v_mov_b64_e32 v[16:17], v[0:1]
	v_addc_co_u32_e32 v49, vcc, 0, v199, vcc
	global_load_dwordx4 v[32:35], v[198:199], off
	global_load_dwordx4 v[36:39], v[196:197], off
	global_load_dwordx4 v[40:43], v[196:197], off offset:128
	s_nop 0
	global_load_dwordx4 v[44:47], v[44:45], off
	s_nop 0
	global_load_dwordx4 v[48:51], v[48:49], off
	v_mul_u32_u24_e32 v53, 0x90, v207
	v_mad_u64_u32 v[194:195], s[12:13], v74, s60, v[54:55]
	v_add3_u32 v195, 0, v53, v52
	v_add_co_u32_e32 v52, vcc, s33, v198
	v_add_u32_e32 v208, 0, v194
	s_nop 0
	v_addc_co_u32_e32 v53, vcc, 0, v199, vcc
	global_load_dwordx4 v[64:67], v[196:197], off offset:256
	global_load_dwordx4 v[68:71], v[52:53], off
	s_cmp_gt_i32 s73, 1
	s_cselect_b32 s92, 0x8000, s33
	s_cselect_b32 s2, 0x104, 4
	s_mov_b32 s27, 1
	s_add_i32 s12, s2, -1
	s_cmp_lt_i32 s73, 2
	s_barrier
	s_waitcnt vmcnt(5)
	ds_write_b128 v208, v[36:39] offset:36864
	s_waitcnt vmcnt(4)
	ds_write_b128 v208, v[40:43] offset:46080
	ds_write_b128 v208, v[32:35]
	s_waitcnt vmcnt(3)
	ds_write_b128 v208, v[44:47] offset:9216
	s_waitcnt vmcnt(2)
	ds_write_b128 v208, v[48:51] offset:18432
	s_waitcnt lgkmcnt(0)
	s_barrier
	ds_read_b128 v[48:51], v195
	ds_read_b128 v[52:55], v195 offset:4608
	s_waitcnt lgkmcnt(1)
	v_mfma_f32_32x32x16_bf16 v[32:47], v[48:51], v[180:183], v[16:31]
	v_lshl_add_u64 v[48:49], v[198:199], 0, s[92:93]
	global_load_dwordx4 v[152:155], v[48:49], off
	global_load_dwordx4 v[156:159], v[196:197], off offset:384
	ds_read_b128 v[48:51], v195 offset:32
	s_waitcnt lgkmcnt(0)
	v_mfma_f32_32x32x16_bf16 v[32:47], v[48:51], v[176:179], v[32:47]
	ds_read_b128 v[48:51], v195 offset:4640
	v_mfma_f32_32x32x16_bf16 v[16:31], v[52:55], v[180:183], v[16:31]
	s_waitcnt lgkmcnt(0)
	v_mfma_f32_32x32x16_bf16 v[16:31], v[48:51], v[176:179], v[16:31]
	ds_read_b128 v[48:51], v195 offset:64
	s_waitcnt lgkmcnt(0)
	v_mfma_f32_32x32x16_bf16 v[32:47], v[48:51], v[172:175], v[32:47]
	ds_read_b128 v[48:51], v195 offset:4672
	s_waitcnt lgkmcnt(0)
	v_mfma_f32_32x32x16_bf16 v[16:31], v[48:51], v[172:175], v[16:31]
	ds_read_b128 v[48:51], v195 offset:96
	s_waitcnt lgkmcnt(0)
	v_mfma_f32_32x32x16_bf16 v[32:47], v[48:51], v[168:171], v[32:47]
	ds_read_b128 v[48:51], v195 offset:4704
	s_waitcnt lgkmcnt(0)
	v_mfma_f32_32x32x16_bf16 v[16:31], v[48:51], v[168:171], v[16:31]
	v_max3_f32 v48, v32, v33, v34
	s_nop 0
	v_max3_f32 v48, v48, v35, v36
	s_nop 0
	v_max3_f32 v48, v48, v37, v38
	s_nop 0
	v_max3_f32 v48, v48, v39, v40
	s_nop 0
	v_max3_f32 v48, v48, v41, v42
	s_nop 0
	v_max3_f32 v48, v48, v43, v44
	s_nop 0
	v_max3_f32 v48, v48, v45, v46
	s_nop 0
	v_max3_f32 v48, v48, v47, v16
	s_nop 0
	v_max3_f32 v48, v48, v17, v18
	s_nop 0
	v_max3_f32 v48, v48, v19, v20
	s_nop 0
	v_max3_f32 v48, v48, v21, v22
	s_nop 0
	v_max3_f32 v48, v48, v23, v24
	s_nop 0
	v_max3_f32 v48, v48, v25, v26
	s_nop 0
	v_max3_f32 v48, v48, v27, v28
	s_nop 0
	v_max3_f32 v48, v48, v29, v30
	s_nop 0
	v_max3_f32 v48, v48, v31, v31
	s_setprio 0
	ds_read_b128 v[78:81], v195 offset:9216
	ds_read_b128 v[120:123], v195 offset:9248
	ds_read_b128 v[124:127], v195 offset:13824
	ds_read_b128 v[128:131], v195 offset:13856
	ds_read_b128 v[132:135], v195 offset:9280
	ds_read_b128 v[148:151], v195 offset:9312
	ds_read_b128 v[160:163], v195 offset:13888
	ds_read_b128 v[164:167], v195 offset:13920
	v_mov_b32_e32 v49, v48
	s_nop 1
	v_permlane32_swap_b32_e32 v48, v49
	v_max_f32_e32 v49, v49, v49
	v_max_f32_e32 v48, v48, v48
	v_max_f32_e32 v49, v48, v49
	v_add_f32_e32 v209, 0, v49
	v_xor_b32_e32 v48, 0x80000000, v209
	v_sub_f32_e32 v32, v32, v49
	v_sub_f32_e32 v16, v16, v49
	v_sub_f32_e32 v33, v33, v49
	v_sub_f32_e32 v17, v17, v49
	v_sub_f32_e32 v34, v34, v49
	v_sub_f32_e32 v18, v18, v49
	v_sub_f32_e32 v35, v35, v49
	v_sub_f32_e32 v19, v19, v49
	v_sub_f32_e32 v36, v36, v49
	v_sub_f32_e32 v20, v20, v49
	v_sub_f32_e32 v37, v37, v49
	v_sub_f32_e32 v21, v21, v49
	v_sub_f32_e32 v38, v38, v49
	v_sub_f32_e32 v22, v22, v49
	v_sub_f32_e32 v39, v39, v49
	v_sub_f32_e32 v23, v23, v49
	v_sub_f32_e32 v40, v40, v49
	v_sub_f32_e32 v24, v24, v49
	v_sub_f32_e32 v41, v41, v49
	v_sub_f32_e32 v25, v25, v49
	v_sub_f32_e32 v42, v42, v49
	v_sub_f32_e32 v26, v26, v49
	v_sub_f32_e32 v43, v43, v49
	v_sub_f32_e32 v27, v27, v49
	v_sub_f32_e32 v44, v44, v49
	v_sub_f32_e32 v28, v28, v49
	v_sub_f32_e32 v45, v45, v49
	v_sub_f32_e32 v29, v29, v49
	v_sub_f32_e32 v46, v46, v49
	v_sub_f32_e32 v30, v30, v49
	v_sub_f32_e32 v47, v47, v49
	v_sub_f32_e32 v31, v31, v49
	v_mov_b32_e32 v49, v48
	v_mov_b32_e32 v50, v48
	v_mov_b32_e32 v51, v48
	v_mov_b32_e32 v52, v48
	v_mov_b32_e32 v53, v48
	v_mov_b32_e32 v54, v48
	v_mov_b32_e32 v55, v48
	v_mov_b32_e32 v56, v48
	v_mov_b32_e32 v57, v48
	v_mov_b32_e32 v58, v48
	v_mov_b32_e32 v59, v48
	v_mov_b32_e32 v60, v48
	v_mov_b32_e32 v61, v48
	v_mov_b32_e32 v62, v48
	v_mov_b32_e32 v63, v48
	s_waitcnt lgkmcnt(7)
	s_nop 4
	v_mfma_f32_32x32x16_bf16 v[96:111], v[78:81], v[180:183], v[48:63]
	v_exp_f32_e32 v116, v32
	v_exp_f32_e32 v117, v33
	v_exp_f32_e32 v118, v34
	v_exp_f32_e32 v119, v35
	s_nop 0
	s_waitcnt lgkmcnt(5)
	s_nop 4
	v_mfma_f32_32x32x16_bf16 v[80:95], v[124:127], v[180:183], v[48:63]
	v_exp_f32_e32 v112, v36
	v_exp_f32_e32 v113, v37
	v_exp_f32_e32 v114, v38
	v_exp_f32_e32 v115, v39
	s_nop 0
	v_mfma_f32_32x32x16_bf16 v[96:111], v[120:123], v[176:179], v[96:111]
	v_exp_f32_e32 v187, v40
	v_exp_f32_e32 v186, v41
	v_exp_f32_e32 v185, v42
	v_exp_f32_e32 v184, v43
	s_nop 0
	s_waitcnt lgkmcnt(4)
	v_mfma_f32_32x32x16_bf16 v[80:95], v[128:131], v[176:179], v[80:95]
	v_exp_f32_e32 v147, v44
	v_exp_f32_e32 v146, v45
	v_exp_f32_e32 v145, v46
	v_exp_f32_e32 v144, v47
	s_nop 0
	s_waitcnt lgkmcnt(3)
	v_mfma_f32_32x32x16_bf16 v[96:111], v[132:135], v[172:175], v[96:111]
	v_exp_f32_e32 v143, v16
	v_exp_f32_e32 v142, v17
	v_exp_f32_e32 v141, v18
	v_exp_f32_e32 v140, v19
	s_nop 0
	s_waitcnt lgkmcnt(1)
	v_mfma_f32_32x32x16_bf16 v[80:95], v[160:163], v[172:175], v[80:95]
	v_exp_f32_e32 v139, v20
	v_exp_f32_e32 v138, v21
	v_exp_f32_e32 v137, v22
	v_exp_f32_e32 v136, v23
	s_nop 0
	v_mfma_f32_32x32x16_bf16 v[96:111], v[148:151], v[168:171], v[96:111]
	v_exp_f32_e32 v123, v24
	v_exp_f32_e32 v122, v25
	v_exp_f32_e32 v121, v26
	v_exp_f32_e32 v120, v27
	s_nop 0
	s_waitcnt lgkmcnt(0)
	v_mfma_f32_32x32x16_bf16 v[80:95], v[164:167], v[168:171], v[80:95]
	v_exp_f32_e32 v127, v28
	v_exp_f32_e32 v126, v29
	v_exp_f32_e32 v125, v30
	v_exp_f32_e32 v124, v31
	s_nop 0
	s_waitcnt vmcnt(2)
	ds_write_b128 v208, v[68:71] offset:27648
	ds_write_b128 v208, v[64:67] offset:55296
	s_cbranch_scc1 .LBB0_681
	v_mad_i64_i32 v[16:17], s[26:27], v74, s55, 0
	s_add_u32 s26, s4, s19
	v_and_b32_e32 v18, 7, v76
	s_addc_u32 s27, s5, s18
	v_lshlrev_b32_e32 v200, 4, v18
	v_lshl_add_u64 v[202:203], s[26:27], 0, v[16:17]
	v_mov_b64_e32 v[30:31], v[14:15]
	v_mov_b64_e32 v[46:47], v[14:15]
	v_mov_b32_e32 v201, v0
	v_lshl_add_u64 v[204:205], s[26:27], 0, v[72:73]
	s_mov_b32 s27, 1
	v_mov_b32_e32 v64, 0
	s_mov_b32 s13, 12
	v_mov_b64_e32 v[28:29], v[12:13]
	v_mov_b64_e32 v[26:27], v[10:11]
	v_mov_b64_e32 v[24:25], v[8:9]
	v_mov_b64_e32 v[22:23], v[6:7]
	v_mov_b64_e32 v[20:21], v[4:5]
	v_mov_b64_e32 v[18:19], v[2:3]
	v_mov_b64_e32 v[16:17], v[0:1]
	v_mov_b64_e32 v[44:45], v[12:13]
	v_mov_b64_e32 v[42:43], v[10:11]
	v_mov_b64_e32 v[40:41], v[8:9]
	v_mov_b64_e32 v[38:39], v[6:7]
	v_mov_b64_e32 v[36:37], v[4:5]
	v_mov_b64_e32 v[34:35], v[2:3]
	v_mov_b64_e32 v[32:33], v[0:1]
.LBB0_661:
	v_lshl_add_u64 v[164:165], v[204:205], 0, v[200:201]
	s_mov_b32 s26, 0x1da8a000
	v_add_co_u32_e32 v2, vcc, s26, v164
	v_lshl_add_u64 v[6:7], v[202:203], 0, v[200:201]
	s_nop 0
	v_addc_co_u32_e32 v3, vcc, 0, v165, vcc
	s_mov_b32 s26, 0x1e2a0000
	v_add_co_u32_e32 v14, vcc, s26, v6
	s_nop 0
	v_addc_co_u32_e32 v15, vcc, 0, v7, vcc
	global_load_dwordx4 v[2:5], v[2:3], off
	s_mul_i32 s28, s27, 0x2400
	global_load_dwordx4 v[6:9], v[14:15], off offset:512
	s_add_i32 s26, s13, -7
	s_add_i32 s29, s28, 0xffffdc00
	s_cmp_lg_u32 s27, 0
	s_cselect_b32 s29, s29, 0x9000
	v_add_u32_e32 v1, s29, v195
	ds_read_b128 v[10:13], v1 offset:36864
	ds_read_b128 v[66:69], v1 offset:36896
	ds_read_b128 v[70:73], v1 offset:41472
	ds_read_b128 v[74:77], v1 offset:41504
	ds_read_b128 v[128:131], v1 offset:36928
	ds_read_b128 v[132:135], v1 offset:36960
	ds_read_b128 v[148:151], v1 offset:41536
	ds_read_b128 v[160:163], v1 offset:41568
	s_setprio 3
	v_cvt_pk_bf16_f32 v210, v116, v117
	v_cvt_pk_bf16_f32 v211, v118, v119
	v_cvt_pk_bf16_f32 v212, v112, v113
	v_cvt_pk_bf16_f32 v213, v114, v115
	s_waitcnt lgkmcnt(7)
	s_nop 0
	v_mfma_f32_32x32x16_bf16 v[16:31], v[10:13], v[210:213], v[16:31]
	v_mov_b32_e32 v1, v116
	v_add_f32_e32 v1, v1, v117
	v_add_f32_e32 v1, v1, v118
	v_add_f32_e32 v1, v1, v119
	s_waitcnt lgkmcnt(5)
	v_mfma_f32_32x32x16_bf16 v[32:47], v[70:73], v[210:213], v[32:47]
	v_cvt_pk_bf16_f32 v10, v187, v186
	v_cvt_pk_bf16_f32 v11, v185, v184
	v_cvt_pk_bf16_f32 v12, v147, v146
	v_cvt_pk_bf16_f32 v13, v145, v144
	v_add_f32_e32 v1, v1, v112
	v_add_f32_e32 v1, v1, v113
	v_add_f32_e32 v1, v1, v114
	v_add_f32_e32 v1, v1, v115
	s_nop 0
	v_mfma_f32_32x32x16_bf16 v[16:31], v[66:69], v[10:13], v[16:31]
	v_add_f32_e32 v1, v1, v187
	v_add_f32_e32 v1, v1, v186
	v_add_f32_e32 v1, v1, v185
	v_add_f32_e32 v1, v1, v184
	s_waitcnt lgkmcnt(4)
	v_mfma_f32_32x32x16_bf16 v[32:47], v[74:77], v[10:13], v[32:47]
	v_cvt_pk_bf16_f32 v66, v143, v142
	v_cvt_pk_bf16_f32 v67, v141, v140
	v_cvt_pk_bf16_f32 v68, v139, v138
	v_cvt_pk_bf16_f32 v69, v137, v136
	v_add_f32_e32 v1, v1, v147
	v_add_f32_e32 v1, v1, v146
	v_add_f32_e32 v1, v1, v145
	v_add_f32_e32 v1, v1, v144
	s_waitcnt lgkmcnt(3)
	v_mfma_f32_32x32x16_bf16 v[16:31], v[128:131], v[66:69], v[16:31]
	v_add_f32_e32 v1, v1, v143
	v_add_f32_e32 v1, v1, v142
	v_add_f32_e32 v1, v1, v141
	v_add_f32_e32 v1, v1, v140
	s_waitcnt lgkmcnt(1)
	v_mfma_f32_32x32x16_bf16 v[32:47], v[148:151], v[66:69], v[32:47]
	v_cvt_pk_bf16_f32 v10, v123, v122
	v_cvt_pk_bf16_f32 v11, v121, v120
	v_cvt_pk_bf16_f32 v12, v127, v126
	v_cvt_pk_bf16_f32 v13, v125, v124
	v_add_f32_e32 v1, v1, v139
	v_add_f32_e32 v1, v1, v138
	v_add_f32_e32 v1, v1, v137
	v_add_f32_e32 v1, v1, v136
	s_nop 0
	v_mfma_f32_32x32x16_bf16 v[16:31], v[132:135], v[10:13], v[16:31]
	v_add_f32_e32 v1, v1, v123
	v_add_f32_e32 v1, v1, v122
	v_add_f32_e32 v1, v1, v121
	v_add_f32_e32 v1, v1, v120
	s_waitcnt lgkmcnt(0)
	v_mfma_f32_32x32x16_bf16 v[32:47], v[160:163], v[10:13], v[32:47]
	v_add_f32_e32 v1, v1, v127
	v_add_f32_e32 v1, v1, v126
	v_add_f32_e32 v1, v1, v125
	v_add_f32_e32 v1, v1, v124
	s_setprio 2
	s_waitcnt lgkmcnt(0)
	s_barrier
	ds_read_b128 v[240:243], v195 offset:18432
	ds_read_b128 v[244:247], v195 offset:23040
	ds_read_b128 v[66:69], v195 offset:18464
	ds_read_b128 v[74:77], v195 offset:23072
	ds_read_b128 v[144:147], v195 offset:18496
	ds_read_b128 v[148:151], v195 offset:18528
	ds_read_b128 v[160:163], v195 offset:23104
	ds_read_b128 v[184:187], v195 offset:23136
	s_waitcnt lgkmcnt(6)
	v_mfma_f32_32x32x16_bf16 v[128:143], v[240:243], v[180:183], v[48:63]
	v_exp_f32_e32 v166, v96
	v_exp_f32_e32 v167, v97
	v_exp_f32_e32 v210, v98
	v_exp_f32_e32 v211, v99
	s_waitcnt lgkmcnt(5)
	v_mfma_f32_32x32x16_bf16 v[112:127], v[244:247], v[180:183], v[48:63]
	v_exp_f32_e32 v212, v100
	v_exp_f32_e32 v213, v101
	v_exp_f32_e32 v214, v102
	v_exp_f32_e32 v215, v103
	v_mfma_f32_32x32x16_bf16 v[128:143], v[66:69], v[176:179], v[128:143]
	v_exp_f32_e32 v100, v104
	v_exp_f32_e32 v101, v105
	v_exp_f32_e32 v102, v106
	v_exp_f32_e32 v103, v107
	s_waitcnt lgkmcnt(4)
	v_mfma_f32_32x32x16_bf16 v[112:127], v[74:77], v[176:179], v[112:127]
	v_exp_f32_e32 v104, v108
	v_exp_f32_e32 v105, v109
	v_exp_f32_e32 v106, v110
	v_exp_f32_e32 v107, v111
	s_waitcnt lgkmcnt(3)
	v_mfma_f32_32x32x16_bf16 v[128:143], v[144:147], v[172:175], v[128:143]
	v_exp_f32_e32 v108, v80
	v_exp_f32_e32 v109, v81
	v_exp_f32_e32 v110, v82
	v_exp_f32_e32 v111, v83
	s_waitcnt lgkmcnt(1)
	v_mfma_f32_32x32x16_bf16 v[112:127], v[160:163], v[172:175], v[112:127]
	v_exp_f32_e32 v144, v84
	v_exp_f32_e32 v145, v85
	v_exp_f32_e32 v146, v86
	v_exp_f32_e32 v147, v87
	v_mfma_f32_32x32x16_bf16 v[128:143], v[148:151], v[168:171], v[128:143]
	v_exp_f32_e32 v216, v88
	v_exp_f32_e32 v217, v89
	v_exp_f32_e32 v218, v90
	v_exp_f32_e32 v219, v91
	s_waitcnt lgkmcnt(0)
	v_mfma_f32_32x32x16_bf16 v[112:127], v[184:187], v[168:171], v[112:127]
	v_exp_f32_e32 v148, v92
	v_exp_f32_e32 v149, v93
	v_exp_f32_e32 v150, v94
	v_exp_f32_e32 v151, v95
	s_cmp_gt_i32 s27, 2
	s_cselect_b32 s29, -3, 2
	s_add_i32 s29, s29, s27
	v_add_u32_e32 v92, s28, v195
	s_add_i32 s28, s13, -6
	s_mulk_i32 s29, 0x2400
	s_min_u32 s28, s28, s12
	v_add_u32_e32 v10, s29, v208
	s_min_u32 s26, s26, s12
	s_lshl_b32 s92, s28, 13
	s_waitcnt vmcnt(3)
	ds_write_b128 v208, v[152:155]
	s_waitcnt vmcnt(2)
	ds_write_b128 v10, v[156:159] offset:36864
	v_lshl_add_u64 v[10:11], v[198:199], 0, s[92:93]
	s_lshl_b32 s92, s26, 7
	v_add_f32_e32 v1, v64, v1
	v_lshl_add_u64 v[64:65], v[196:197], 0, s[92:93]
	global_load_dwordx4 v[10:13], v[10:11], off
	s_add_i32 s29, s27, 1
	global_load_dwordx4 v[160:163], v[64:65], off
	ds_read_b128 v[240:243], v195 offset:27648
	ds_read_b128 v[244:247], v195 offset:32256
	ds_read_b128 v[64:67], v92 offset:41472
	ds_read_b128 v[68:71], v92 offset:36864
	ds_read_b128 v[72:75], v92 offset:36896
	ds_read_b128 v[76:79], v92 offset:41504
	ds_read_b128 v[80:83], v92 offset:36928
	ds_read_b128 v[84:87], v92 offset:41536
	ds_read_b128 v[88:91], v92 offset:36960
	ds_read_b128 v[92:95], v92 offset:41568
	s_setprio 1
	v_cvt_pk_bf16_f32 v96, v166, v167
	v_cvt_pk_bf16_f32 v97, v210, v211
	v_cvt_pk_bf16_f32 v98, v212, v213
	v_cvt_pk_bf16_f32 v99, v214, v215
	s_waitcnt lgkmcnt(6)
	s_nop 0
	v_mfma_f32_32x32x16_bf16 v[16:31], v[68:71], v[96:99], v[16:31]
	v_mov_b32_e32 v184, v166
	v_add_f32_e32 v184, v184, v167
	v_add_f32_e32 v184, v184, v210
	v_add_f32_e32 v184, v184, v211
	s_nop 0
	v_mfma_f32_32x32x16_bf16 v[32:47], v[64:67], v[96:99], v[32:47]
	v_cvt_pk_bf16_f32 v68, v100, v101
	v_cvt_pk_bf16_f32 v69, v102, v103
	v_cvt_pk_bf16_f32 v70, v104, v105
	v_cvt_pk_bf16_f32 v71, v106, v107
	v_add_f32_e32 v184, v184, v212
	v_add_f32_e32 v184, v184, v213
	v_add_f32_e32 v184, v184, v214
	v_add_f32_e32 v184, v184, v215
	s_waitcnt lgkmcnt(5)
	v_mfma_f32_32x32x16_bf16 v[16:31], v[72:75], v[68:71], v[16:31]
	v_add_f32_e32 v184, v184, v100
	v_add_f32_e32 v184, v184, v101
	v_add_f32_e32 v184, v184, v102
	v_add_f32_e32 v184, v184, v103
	s_waitcnt lgkmcnt(4)
	v_mfma_f32_32x32x16_bf16 v[32:47], v[76:79], v[68:71], v[32:47]
	v_cvt_pk_bf16_f32 v64, v108, v109
	v_cvt_pk_bf16_f32 v65, v110, v111
	v_cvt_pk_bf16_f32 v66, v144, v145
	v_cvt_pk_bf16_f32 v67, v146, v147
	v_add_f32_e32 v184, v184, v104
	v_add_f32_e32 v184, v184, v105
	v_add_f32_e32 v184, v184, v106
	v_add_f32_e32 v184, v184, v107
	s_waitcnt lgkmcnt(3)
	v_mfma_f32_32x32x16_bf16 v[16:31], v[80:83], v[64:67], v[16:31]
	v_add_f32_e32 v184, v184, v108
	v_add_f32_e32 v184, v184, v109
	v_add_f32_e32 v184, v184, v110
	v_add_f32_e32 v184, v184, v111
	s_waitcnt lgkmcnt(2)
	v_mfma_f32_32x32x16_bf16 v[32:47], v[84:87], v[64:67], v[32:47]
	v_cvt_pk_bf16_f32 v68, v216, v217
	v_cvt_pk_bf16_f32 v69, v218, v219
	v_cvt_pk_bf16_f32 v70, v148, v149
	v_cvt_pk_bf16_f32 v71, v150, v151
	v_add_f32_e32 v184, v184, v144
	v_add_f32_e32 v184, v184, v145
	v_add_f32_e32 v184, v184, v146
	v_add_f32_e32 v184, v184, v147
	s_waitcnt lgkmcnt(1)
	v_mfma_f32_32x32x16_bf16 v[16:31], v[88:91], v[68:71], v[16:31]
	v_add_f32_e32 v184, v184, v216
	v_add_f32_e32 v184, v184, v217
	v_add_f32_e32 v184, v184, v218
	v_add_f32_e32 v184, v184, v219
	s_waitcnt lgkmcnt(0)
	v_mfma_f32_32x32x16_bf16 v[32:47], v[92:95], v[68:71], v[32:47]
	v_add_f32_e32 v184, v184, v148
	v_add_f32_e32 v184, v184, v149
	v_add_f32_e32 v184, v184, v150
	v_add_f32_e32 v184, v184, v151
	s_setprio 0
	ds_read_b128 v[68:71], v195 offset:27680
	ds_read_b128 v[76:79], v195 offset:32288
	ds_read_b128 v[80:83], v195 offset:27712
	ds_read_b128 v[84:87], v195 offset:27744
	ds_read_b128 v[88:91], v195 offset:32320
	ds_read_b128 v[92:95], v195 offset:32352
	s_cmp_lg_u32 s27, 4
	s_cselect_b32 s26, s29, 0
	s_waitcnt lgkmcnt(6)
	v_mfma_f32_32x32x16_bf16 v[144:159], v[240:243], v[180:183], v[48:63]
	v_exp_f32_e32 v166, v128
	v_exp_f32_e32 v167, v129
	v_exp_f32_e32 v185, v130
	v_exp_f32_e32 v186, v131
	s_waitcnt lgkmcnt(5)
	v_mfma_f32_32x32x16_bf16 v[96:111], v[244:247], v[180:183], v[48:63]
	v_exp_f32_e32 v128, v132
	v_exp_f32_e32 v129, v133
	v_exp_f32_e32 v130, v134
	v_exp_f32_e32 v131, v135
	v_mfma_f32_32x32x16_bf16 v[144:159], v[68:71], v[176:179], v[144:159]
	v_exp_f32_e32 v132, v136
	v_exp_f32_e32 v133, v137
	v_exp_f32_e32 v134, v138
	v_exp_f32_e32 v135, v139
	s_waitcnt lgkmcnt(4)
	v_mfma_f32_32x32x16_bf16 v[96:111], v[76:79], v[176:179], v[96:111]
	v_exp_f32_e32 v136, v140
	v_exp_f32_e32 v137, v141
	v_exp_f32_e32 v138, v142
	v_exp_f32_e32 v139, v143
	s_waitcnt lgkmcnt(3)
	v_mfma_f32_32x32x16_bf16 v[144:159], v[80:83], v[172:175], v[144:159]
	v_exp_f32_e32 v140, v112
	v_exp_f32_e32 v141, v113
	v_exp_f32_e32 v142, v114
	v_exp_f32_e32 v143, v115
	s_waitcnt lgkmcnt(1)
	v_mfma_f32_32x32x16_bf16 v[96:111], v[88:91], v[172:175], v[96:111]
	v_exp_f32_e32 v187, v116
	v_exp_f32_e32 v210, v117
	v_exp_f32_e32 v211, v118
	v_exp_f32_e32 v212, v119
	v_mfma_f32_32x32x16_bf16 v[144:159], v[84:87], v[168:171], v[144:159]
	v_exp_f32_e32 v116, v120
	v_exp_f32_e32 v117, v121
	v_exp_f32_e32 v118, v122
	v_exp_f32_e32 v119, v123
	s_waitcnt lgkmcnt(0)
	v_mfma_f32_32x32x16_bf16 v[96:111], v[92:95], v[168:171], v[96:111]
	v_exp_f32_e32 v120, v124
	v_exp_f32_e32 v121, v125
	v_exp_f32_e32 v122, v126
	v_exp_f32_e32 v123, v127
	s_cmp_gt_i32 s26, 2
	s_cselect_b32 s27, -3, 2
	s_add_i32 s27, s27, s26
	s_mulk_i32 s27, 0x2400
	s_waitcnt vmcnt(3)
	ds_write_b128 v208, v[2:5] offset:9216
	v_add_u32_e32 v2, s27, v208
	s_add_i32 s27, s26, 1
	s_cmp_lg_u32 s26, 4
	s_cselect_b32 s26, s27, 0
	s_add_i32 s27, s13, -5
	s_min_u32 s27, s27, s12
	s_lshl_b32 s92, s27, 13
	s_waitcnt vmcnt(2)
	ds_write_b128 v2, v[6:9] offset:36864
	v_lshl_add_u64 v[2:3], v[198:199], 0, s[92:93]
	s_lshl_b32 s92, s28, 7
	v_lshl_add_u64 v[4:5], v[196:197], 0, s[92:93]
	global_load_dwordx4 v[6:9], v[2:3], off
	s_nop 0
	global_load_dwordx4 v[2:5], v[4:5], off
	s_mul_i32 s28, s26, 0x2400
	s_add_i32 s29, s28, 0xffffdc00
	s_cmp_lg_u32 s26, 0
	s_cselect_b32 s29, s29, 0x9000
	v_add_u32_e32 v92, s29, v195
	ds_read_b128 v[64:67], v92 offset:36864
	ds_read_b128 v[68:71], v92 offset:36896
	ds_read_b128 v[72:75], v92 offset:41472
	ds_read_b128 v[76:79], v92 offset:41504
	ds_read_b128 v[80:83], v92 offset:36928
	ds_read_b128 v[84:87], v92 offset:36960
	ds_read_b128 v[88:91], v92 offset:41536
	ds_read_b128 v[92:95], v92 offset:41568
	s_setprio 3
	v_cvt_pk_bf16_f32 v112, v166, v167
	v_cvt_pk_bf16_f32 v113, v185, v186
	v_cvt_pk_bf16_f32 v114, v128, v129
	v_cvt_pk_bf16_f32 v115, v130, v131
	s_waitcnt lgkmcnt(7)
	s_nop 0
	v_mfma_f32_32x32x16_bf16 v[16:31], v[64:67], v[112:115], v[16:31]
	v_mov_b32_e32 v213, v166
	v_add_f32_e32 v213, v213, v167
	v_add_f32_e32 v213, v213, v185
	v_add_f32_e32 v213, v213, v186
	s_waitcnt lgkmcnt(5)
	v_mfma_f32_32x32x16_bf16 v[32:47], v[72:75], v[112:115], v[32:47]
	v_cvt_pk_bf16_f32 v64, v132, v133
	v_cvt_pk_bf16_f32 v65, v134, v135
	v_cvt_pk_bf16_f32 v66, v136, v137
	v_cvt_pk_bf16_f32 v67, v138, v139
	v_add_f32_e32 v213, v213, v128
	v_add_f32_e32 v213, v213, v129
	v_add_f32_e32 v213, v213, v130
	v_add_f32_e32 v213, v213, v131
	s_nop 0
	v_mfma_f32_32x32x16_bf16 v[16:31], v[68:71], v[64:67], v[16:31]
	v_add_f32_e32 v213, v213, v132
	v_add_f32_e32 v213, v213, v133
	v_add_f32_e32 v213, v213, v134
	v_add_f32_e32 v213, v213, v135
	s_waitcnt lgkmcnt(4)
	v_mfma_f32_32x32x16_bf16 v[32:47], v[76:79], v[64:67], v[32:47]
	v_cvt_pk_bf16_f32 v68, v140, v141
	v_cvt_pk_bf16_f32 v69, v142, v143
	v_cvt_pk_bf16_f32 v70, v187, v210
	v_cvt_pk_bf16_f32 v71, v211, v212
	v_add_f32_e32 v213, v213, v136
	v_add_f32_e32 v213, v213, v137
	v_add_f32_e32 v213, v213, v138
	v_add_f32_e32 v213, v213, v139
	s_waitcnt lgkmcnt(3)
	v_mfma_f32_32x32x16_bf16 v[16:31], v[80:83], v[68:71], v[16:31]
	v_add_f32_e32 v213, v213, v140
	v_add_f32_e32 v213, v213, v141
	v_add_f32_e32 v213, v213, v142
	v_add_f32_e32 v213, v213, v143
	s_waitcnt lgkmcnt(1)
	v_mfma_f32_32x32x16_bf16 v[32:47], v[88:91], v[68:71], v[32:47]
	v_cvt_pk_bf16_f32 v64, v116, v117
	v_cvt_pk_bf16_f32 v65, v118, v119
	v_cvt_pk_bf16_f32 v66, v120, v121
	v_cvt_pk_bf16_f32 v67, v122, v123
	v_add_f32_e32 v213, v213, v187
	v_add_f32_e32 v213, v213, v210
	v_add_f32_e32 v213, v213, v211
	v_add_f32_e32 v213, v213, v212
	s_nop 0
	v_mfma_f32_32x32x16_bf16 v[16:31], v[84:87], v[64:67], v[16:31]
	v_add_f32_e32 v213, v213, v116
	v_add_f32_e32 v213, v213, v117
	v_add_f32_e32 v213, v213, v118
	v_add_f32_e32 v213, v213, v119
	s_waitcnt lgkmcnt(0)
	v_mfma_f32_32x32x16_bf16 v[32:47], v[92:95], v[64:67], v[32:47]
	v_add_f32_e32 v213, v213, v120
	v_add_f32_e32 v213, v213, v121
	v_add_f32_e32 v213, v213, v122
	v_add_f32_e32 v213, v213, v123
	s_setprio 2
	s_waitcnt lgkmcnt(0)
	s_barrier
	ds_read_b128 v[240:243], v195
	ds_read_b128 v[244:247], v195 offset:4608
	ds_read_b128 v[116:119], v195 offset:32
	ds_read_b128 v[120:123], v195 offset:4640
	ds_read_b128 v[124:127], v195 offset:64
	ds_read_b128 v[128:131], v195 offset:4672
	ds_read_b128 v[132:135], v195 offset:96
	ds_read_b128 v[136:139], v195 offset:4704
	v_add_f32_e32 v1, v1, v184
	s_waitcnt lgkmcnt(6)
	v_mfma_f32_32x32x16_bf16 v[80:95], v[240:243], v[180:183], v[48:63]
	v_exp_f32_e32 v140, v144
	v_exp_f32_e32 v141, v145
	v_exp_f32_e32 v142, v146
	v_exp_f32_e32 v143, v147
	v_mfma_f32_32x32x16_bf16 v[64:79], v[244:247], v[180:183], v[48:63]
	v_exp_f32_e32 v144, v148
	v_exp_f32_e32 v145, v149
	v_exp_f32_e32 v146, v150
	v_exp_f32_e32 v147, v151
	s_waitcnt lgkmcnt(5)
	v_mfma_f32_32x32x16_bf16 v[80:95], v[116:119], v[176:179], v[80:95]
	v_exp_f32_e32 v148, v152
	v_exp_f32_e32 v149, v153
	v_exp_f32_e32 v150, v154
	v_exp_f32_e32 v151, v155
	s_waitcnt lgkmcnt(4)
	v_mfma_f32_32x32x16_bf16 v[64:79], v[120:123], v[176:179], v[64:79]
	v_exp_f32_e32 v152, v156
	v_exp_f32_e32 v153, v157
	v_exp_f32_e32 v154, v158
	v_exp_f32_e32 v155, v159
	s_waitcnt lgkmcnt(3)
	v_mfma_f32_32x32x16_bf16 v[80:95], v[124:127], v[172:175], v[80:95]
	v_exp_f32_e32 v156, v96
	v_exp_f32_e32 v157, v97
	v_exp_f32_e32 v158, v98
	v_exp_f32_e32 v159, v99
	s_waitcnt lgkmcnt(2)
	v_mfma_f32_32x32x16_bf16 v[64:79], v[128:131], v[172:175], v[64:79]
	v_exp_f32_e32 v166, v100
	v_exp_f32_e32 v167, v101
	v_exp_f32_e32 v184, v102
	v_exp_f32_e32 v185, v103
	s_waitcnt lgkmcnt(1)
	v_mfma_f32_32x32x16_bf16 v[80:95], v[132:135], v[168:171], v[80:95]
	v_exp_f32_e32 v186, v104
	v_exp_f32_e32 v187, v105
	v_exp_f32_e32 v210, v106
	v_exp_f32_e32 v211, v107
	s_waitcnt lgkmcnt(0)
	v_mfma_f32_32x32x16_bf16 v[64:79], v[136:139], v[168:171], v[64:79]
	v_exp_f32_e32 v212, v108
	v_exp_f32_e32 v214, v109
	v_exp_f32_e32 v215, v110
	v_exp_f32_e32 v216, v111
	s_cmp_gt_i32 s26, 2
	s_cselect_b32 s29, -3, 2
	s_add_i32 s29, s29, s26
	s_mulk_i32 s29, 0x2400
	s_waitcnt vmcnt(3)
	ds_write_b128 v208, v[10:13] offset:18432
	v_add_u32_e32 v10, s29, v208
	s_mov_b32 s29, 0x1da90000
	s_waitcnt vmcnt(2)
	ds_write_b128 v10, v[160:163] offset:36864
	v_add_co_u32_e32 v10, vcc, s29, v164
	s_lshl_b32 s92, s27, 7
	s_nop 0
	v_addc_co_u32_e32 v11, vcc, 0, v165, vcc
	global_load_dwordx4 v[128:131], v[10:11], off
	v_lshl_add_u64 v[10:11], v[196:197], 0, s[92:93]
	global_load_dwordx4 v[10:13], v[10:11], off
	v_add_u32_e32 v124, s28, v195
	ds_read_b128 v[240:243], v195 offset:9216
	ds_read_b128 v[244:247], v195 offset:13824
	ds_read_b128 v[96:99], v124 offset:41472
	ds_read_b128 v[100:103], v124 offset:36864
	ds_read_b128 v[104:107], v124 offset:36896
	ds_read_b128 v[108:111], v124 offset:41504
	ds_read_b128 v[112:115], v124 offset:36928
	ds_read_b128 v[116:119], v124 offset:41536
	ds_read_b128 v[120:123], v124 offset:36960
	ds_read_b128 v[124:127], v124 offset:41568
	v_add_f32_e32 v1, v1, v213
	s_add_i32 s28, s26, 1
	s_setprio 1
	v_cvt_pk_bf16_f32 v132, v140, v141
	v_cvt_pk_bf16_f32 v133, v142, v143
	v_cvt_pk_bf16_f32 v134, v144, v145
	v_cvt_pk_bf16_f32 v135, v146, v147
	s_waitcnt lgkmcnt(6)
	s_nop 0
	v_mfma_f32_32x32x16_bf16 v[16:31], v[100:103], v[132:135], v[16:31]
	v_mov_b32_e32 v160, v140
	v_add_f32_e32 v160, v160, v141
	v_add_f32_e32 v160, v160, v142
	v_add_f32_e32 v160, v160, v143
	s_nop 0
	v_mfma_f32_32x32x16_bf16 v[32:47], v[96:99], v[132:135], v[32:47]
	v_cvt_pk_bf16_f32 v100, v148, v149
	v_cvt_pk_bf16_f32 v101, v150, v151
	v_cvt_pk_bf16_f32 v102, v152, v153
	v_cvt_pk_bf16_f32 v103, v154, v155
	v_add_f32_e32 v160, v160, v144
	v_add_f32_e32 v160, v160, v145
	v_add_f32_e32 v160, v160, v146
	v_add_f32_e32 v160, v160, v147
	s_waitcnt lgkmcnt(5)
	v_mfma_f32_32x32x16_bf16 v[16:31], v[104:107], v[100:103], v[16:31]
	v_add_f32_e32 v160, v160, v148
	v_add_f32_e32 v160, v160, v149
	v_add_f32_e32 v160, v160, v150
	v_add_f32_e32 v160, v160, v151
	s_waitcnt lgkmcnt(4)
	v_mfma_f32_32x32x16_bf16 v[32:47], v[108:111], v[100:103], v[32:47]
	v_cvt_pk_bf16_f32 v96, v156, v157
	v_cvt_pk_bf16_f32 v97, v158, v159
	v_cvt_pk_bf16_f32 v98, v166, v167
	v_cvt_pk_bf16_f32 v99, v184, v185
	v_add_f32_e32 v160, v160, v152
	v_add_f32_e32 v160, v160, v153
	v_add_f32_e32 v160, v160, v154
	v_add_f32_e32 v160, v160, v155
	s_waitcnt lgkmcnt(3)
	v_mfma_f32_32x32x16_bf16 v[16:31], v[112:115], v[96:99], v[16:31]
	v_add_f32_e32 v160, v160, v156
	v_add_f32_e32 v160, v160, v157
	v_add_f32_e32 v160, v160, v158
	v_add_f32_e32 v160, v160, v159
	s_waitcnt lgkmcnt(2)
	v_mfma_f32_32x32x16_bf16 v[32:47], v[116:119], v[96:99], v[32:47]
	v_cvt_pk_bf16_f32 v100, v186, v187
	v_cvt_pk_bf16_f32 v101, v210, v211
	v_cvt_pk_bf16_f32 v102, v212, v214
	v_cvt_pk_bf16_f32 v103, v215, v216
	v_add_f32_e32 v160, v160, v166
	v_add_f32_e32 v160, v160, v167
	v_add_f32_e32 v160, v160, v184
	v_add_f32_e32 v160, v160, v185
	s_waitcnt lgkmcnt(1)
	v_mfma_f32_32x32x16_bf16 v[16:31], v[120:123], v[100:103], v[16:31]
	v_add_f32_e32 v160, v160, v186
	v_add_f32_e32 v160, v160, v187
	v_add_f32_e32 v160, v160, v210
	v_add_f32_e32 v160, v160, v211
	s_waitcnt lgkmcnt(0)
	v_mfma_f32_32x32x16_bf16 v[32:47], v[124:127], v[100:103], v[32:47]
	v_add_f32_e32 v160, v160, v212
	v_add_f32_e32 v160, v160, v214
	v_add_f32_e32 v160, v160, v215
	v_add_f32_e32 v160, v160, v216
	s_setprio 0
	ds_read_b128 v[132:135], v195 offset:9248
	ds_read_b128 v[140:143], v195 offset:13856
	ds_read_b128 v[144:147], v195 offset:9280
	ds_read_b128 v[148:151], v195 offset:9312
	ds_read_b128 v[152:155], v195 offset:13888
	ds_read_b128 v[156:159], v195 offset:13920
	s_cmp_lg_u32 s26, 4
	s_cselect_b32 s26, s28, 0
	s_waitcnt lgkmcnt(6)
	v_mfma_f32_32x32x16_bf16 v[112:127], v[240:243], v[180:183], v[48:63]
	v_exp_f32_e32 v161, v80
	v_exp_f32_e32 v162, v81
	v_exp_f32_e32 v163, v82
	v_exp_f32_e32 v164, v83
	s_waitcnt lgkmcnt(5)
	v_mfma_f32_32x32x16_bf16 v[96:111], v[244:247], v[180:183], v[48:63]
	v_exp_f32_e32 v165, v84
	v_exp_f32_e32 v166, v85
	v_exp_f32_e32 v167, v86
	v_exp_f32_e32 v184, v87
	v_mfma_f32_32x32x16_bf16 v[112:127], v[132:135], v[176:179], v[112:127]
	v_exp_f32_e32 v136, v88
	v_exp_f32_e32 v137, v89
	v_exp_f32_e32 v138, v90
	v_exp_f32_e32 v139, v91
	s_waitcnt lgkmcnt(4)
	v_mfma_f32_32x32x16_bf16 v[96:111], v[140:143], v[176:179], v[96:111]
	v_exp_f32_e32 v185, v92
	v_exp_f32_e32 v186, v93
	v_exp_f32_e32 v187, v94
	v_exp_f32_e32 v210, v95
	s_waitcnt lgkmcnt(3)
	v_mfma_f32_32x32x16_bf16 v[112:127], v[144:147], v[172:175], v[112:127]
	v_exp_f32_e32 v140, v64
	v_exp_f32_e32 v141, v65
	v_exp_f32_e32 v142, v66
	v_exp_f32_e32 v143, v67
	s_waitcnt lgkmcnt(1)
	v_mfma_f32_32x32x16_bf16 v[96:111], v[152:155], v[172:175], v[96:111]
	v_exp_f32_e32 v144, v68
	v_exp_f32_e32 v145, v69
	v_exp_f32_e32 v146, v70
	v_exp_f32_e32 v147, v71
	v_mfma_f32_32x32x16_bf16 v[112:127], v[148:151], v[168:171], v[112:127]
	v_exp_f32_e32 v152, v72
	v_exp_f32_e32 v153, v73
	v_exp_f32_e32 v154, v74
	v_exp_f32_e32 v155, v75
	s_waitcnt lgkmcnt(0)
	v_mfma_f32_32x32x16_bf16 v[96:111], v[156:159], v[168:171], v[96:111]
	v_exp_f32_e32 v148, v76
	v_exp_f32_e32 v149, v77
	v_exp_f32_e32 v150, v78
	v_exp_f32_e32 v151, v79
	s_cmp_gt_i32 s26, 2
	s_cselect_b32 s27, -3, 2
	s_add_i32 s27, s27, s26
	s_mulk_i32 s27, 0x2400
	s_waitcnt vmcnt(3)
	ds_write_b128 v208, v[6:9] offset:27648
	v_add_u32_e32 v6, s27, v208
	s_add_i32 s27, s26, 1
	s_cmp_lg_u32 s26, 4
	s_cselect_b32 s27, s27, 0
	s_add_i32 s26, s13, -3
	s_min_u32 s28, s26, s12
	s_lshl_b32 s92, s28, 13
	s_waitcnt vmcnt(2)
	ds_write_b128 v6, v[2:5] offset:36864
	v_lshl_add_u64 v[2:3], v[198:199], 0, s[92:93]
	global_load_dwordx4 v[6:9], v[2:3], off
	s_nop 0
	global_load_dwordx4 v[2:5], v[14:15], off offset:1024
	s_mul_i32 s29, s27, 0x2400
	s_add_i32 s34, s29, 0xffffdc00
	s_cmp_lg_u32 s27, 0
	s_cselect_b32 s34, s34, 0x9000
	v_add_u32_e32 v14, s34, v195
	ds_read_b128 v[64:67], v14 offset:36864
	ds_read_b128 v[68:71], v14 offset:36896
	ds_read_b128 v[72:75], v14 offset:41472
	ds_read_b128 v[76:79], v14 offset:41504
	ds_read_b128 v[80:83], v14 offset:36928
	ds_read_b128 v[84:87], v14 offset:36960
	ds_read_b128 v[88:91], v14 offset:41536
	ds_read_b128 v[92:95], v14 offset:41568
	s_setprio 3
	v_cvt_pk_bf16_f32 v132, v161, v162
	v_cvt_pk_bf16_f32 v133, v163, v164
	v_cvt_pk_bf16_f32 v134, v165, v166
	v_cvt_pk_bf16_f32 v135, v167, v184
	s_waitcnt lgkmcnt(7)
	s_nop 0
	v_mfma_f32_32x32x16_bf16 v[16:31], v[64:67], v[132:135], v[16:31]
	v_mov_b32_e32 v14, v161
	v_add_f32_e32 v14, v14, v162
	v_add_f32_e32 v14, v14, v163
	v_add_f32_e32 v14, v14, v164
	s_waitcnt lgkmcnt(5)
	v_mfma_f32_32x32x16_bf16 v[32:47], v[72:75], v[132:135], v[32:47]
	v_cvt_pk_bf16_f32 v64, v136, v137
	v_cvt_pk_bf16_f32 v65, v138, v139
	v_cvt_pk_bf16_f32 v66, v185, v186
	v_cvt_pk_bf16_f32 v67, v187, v210
	v_add_f32_e32 v14, v14, v165
	v_add_f32_e32 v14, v14, v166
	v_add_f32_e32 v14, v14, v167
	v_add_f32_e32 v14, v14, v184
	s_nop 0
	v_mfma_f32_32x32x16_bf16 v[16:31], v[68:71], v[64:67], v[16:31]
	v_add_f32_e32 v14, v14, v136
	v_add_f32_e32 v14, v14, v137
	v_add_f32_e32 v14, v14, v138
	v_add_f32_e32 v14, v14, v139
	s_waitcnt lgkmcnt(4)
	v_mfma_f32_32x32x16_bf16 v[32:47], v[76:79], v[64:67], v[32:47]
	v_cvt_pk_bf16_f32 v68, v140, v141
	v_cvt_pk_bf16_f32 v69, v142, v143
	v_cvt_pk_bf16_f32 v70, v144, v145
	v_cvt_pk_bf16_f32 v71, v146, v147
	v_add_f32_e32 v14, v14, v185
	v_add_f32_e32 v14, v14, v186
	v_add_f32_e32 v14, v14, v187
	v_add_f32_e32 v14, v14, v210
	s_waitcnt lgkmcnt(3)
	v_mfma_f32_32x32x16_bf16 v[16:31], v[80:83], v[68:71], v[16:31]
	v_add_f32_e32 v14, v14, v140
	v_add_f32_e32 v14, v14, v141
	v_add_f32_e32 v14, v14, v142
	v_add_f32_e32 v14, v14, v143
	s_waitcnt lgkmcnt(1)
	v_mfma_f32_32x32x16_bf16 v[32:47], v[88:91], v[68:71], v[32:47]
	v_cvt_pk_bf16_f32 v64, v152, v153
	v_cvt_pk_bf16_f32 v65, v154, v155
	v_cvt_pk_bf16_f32 v66, v148, v149
	v_cvt_pk_bf16_f32 v67, v150, v151
	v_add_f32_e32 v14, v14, v144
	v_add_f32_e32 v14, v14, v145
	v_add_f32_e32 v14, v14, v146
	v_add_f32_e32 v14, v14, v147
	s_nop 0
	v_mfma_f32_32x32x16_bf16 v[16:31], v[84:87], v[64:67], v[16:31]
	v_add_f32_e32 v14, v14, v152
	v_add_f32_e32 v14, v14, v153
	v_add_f32_e32 v14, v14, v154
	v_add_f32_e32 v14, v14, v155
	s_waitcnt lgkmcnt(0)
	v_mfma_f32_32x32x16_bf16 v[32:47], v[92:95], v[64:67], v[32:47]
	v_add_f32_e32 v14, v14, v148
	v_add_f32_e32 v14, v14, v149
	v_add_f32_e32 v14, v14, v150
	v_add_f32_e32 v14, v14, v151
	s_setprio 2
	s_waitcnt lgkmcnt(0)
	s_barrier
	ds_read_b128 v[240:243], v195 offset:18432
	ds_read_b128 v[244:247], v195 offset:23040
	ds_read_b128 v[136:139], v195 offset:18464
	ds_read_b128 v[140:143], v195 offset:23072
	ds_read_b128 v[144:147], v195 offset:18496
	ds_read_b128 v[148:151], v195 offset:23104
	ds_read_b128 v[152:155], v195 offset:18528
	ds_read_b128 v[156:159], v195 offset:23136
	v_add_f32_e32 v1, v1, v160
	s_waitcnt lgkmcnt(6)
	v_mfma_f32_32x32x16_bf16 v[80:95], v[240:243], v[180:183], v[48:63]
	v_exp_f32_e32 v160, v112
	v_exp_f32_e32 v161, v113
	v_exp_f32_e32 v162, v114
	v_exp_f32_e32 v163, v115
	v_mfma_f32_32x32x16_bf16 v[64:79], v[244:247], v[180:183], v[48:63]
	v_exp_f32_e32 v164, v116
	v_exp_f32_e32 v165, v117
	v_exp_f32_e32 v166, v118
	v_exp_f32_e32 v167, v119
	s_waitcnt lgkmcnt(5)
	v_mfma_f32_32x32x16_bf16 v[80:95], v[136:139], v[176:179], v[80:95]
	v_exp_f32_e32 v184, v120
	v_exp_f32_e32 v185, v121
	v_exp_f32_e32 v186, v122
	v_exp_f32_e32 v187, v123
	s_waitcnt lgkmcnt(4)
	v_mfma_f32_32x32x16_bf16 v[64:79], v[140:143], v[176:179], v[64:79]
	v_exp_f32_e32 v136, v124
	v_exp_f32_e32 v137, v125
	v_exp_f32_e32 v138, v126
	v_exp_f32_e32 v139, v127
	s_waitcnt lgkmcnt(3)
	v_mfma_f32_32x32x16_bf16 v[80:95], v[144:147], v[172:175], v[80:95]
	v_exp_f32_e32 v140, v96
	v_exp_f32_e32 v141, v97
	v_exp_f32_e32 v142, v98
	v_exp_f32_e32 v143, v99
	s_waitcnt lgkmcnt(2)
	v_mfma_f32_32x32x16_bf16 v[64:79], v[148:151], v[172:175], v[64:79]
	v_exp_f32_e32 v144, v100
	v_exp_f32_e32 v145, v101
	v_exp_f32_e32 v146, v102
	v_exp_f32_e32 v147, v103
	s_waitcnt lgkmcnt(1)
	v_mfma_f32_32x32x16_bf16 v[80:95], v[152:155], v[168:171], v[80:95]
	v_exp_f32_e32 v148, v104
	v_exp_f32_e32 v149, v105
	v_exp_f32_e32 v150, v106
	v_exp_f32_e32 v151, v107
	s_waitcnt lgkmcnt(0)
	v_mfma_f32_32x32x16_bf16 v[64:79], v[156:159], v[168:171], v[64:79]
	v_exp_f32_e32 v152, v108
	v_exp_f32_e32 v153, v109
	v_exp_f32_e32 v154, v110
	v_exp_f32_e32 v155, v111
	s_cmp_gt_i32 s27, 2
	s_cselect_b32 s34, -3, 2
	s_waitcnt vmcnt(3)
	ds_write_b128 v208, v[128:131]
	s_add_i32 s34, s34, s27
	v_add_u32_e32 v128, s29, v195
	s_add_i32 s29, s13, -2
	s_mulk_i32 s34, 0x2400
	s_min_u32 s29, s29, s12
	v_add_u32_e32 v15, s34, v208
	s_lshl_b32 s92, s29, 13
	s_waitcnt vmcnt(2)
	ds_write_b128 v15, v[10:13] offset:36864
	v_lshl_add_u64 v[10:11], v[198:199], 0, s[92:93]
	s_lshl_b32 s92, s28, 7
	v_add_f32_e32 v1, v1, v14
	global_load_dwordx4 v[10:13], v[10:11], off
	v_lshl_add_u64 v[14:15], v[196:197], 0, s[92:93]
	global_load_dwordx4 v[112:115], v[14:15], off
	ds_read_b128 v[240:243], v195 offset:27648
	ds_read_b128 v[244:247], v195 offset:32256
	ds_read_b128 v[96:99], v128 offset:41472
	ds_read_b128 v[100:103], v128 offset:36864
	ds_read_b128 v[104:107], v128 offset:36896
	ds_read_b128 v[108:111], v128 offset:41504
	ds_read_b128 v[116:119], v128 offset:36928
	ds_read_b128 v[120:123], v128 offset:41536
	ds_read_b128 v[124:127], v128 offset:36960
	ds_read_b128 v[128:131], v128 offset:41568
	s_add_i32 s34, s27, 1
	s_setprio 1
	v_cvt_pk_bf16_f32 v132, v160, v161
	v_cvt_pk_bf16_f32 v133, v162, v163
	v_cvt_pk_bf16_f32 v134, v164, v165
	v_cvt_pk_bf16_f32 v135, v166, v167
	s_waitcnt lgkmcnt(6)
	s_nop 0
	v_mfma_f32_32x32x16_bf16 v[16:31], v[100:103], v[132:135], v[16:31]
	v_mov_b32_e32 v14, v160
	v_add_f32_e32 v14, v14, v161
	v_add_f32_e32 v14, v14, v162
	v_add_f32_e32 v14, v14, v163
	s_nop 0
	v_mfma_f32_32x32x16_bf16 v[32:47], v[96:99], v[132:135], v[32:47]
	v_cvt_pk_bf16_f32 v100, v184, v185
	v_cvt_pk_bf16_f32 v101, v186, v187
	v_cvt_pk_bf16_f32 v102, v136, v137
	v_cvt_pk_bf16_f32 v103, v138, v139
	v_add_f32_e32 v14, v14, v164
	v_add_f32_e32 v14, v14, v165
	v_add_f32_e32 v14, v14, v166
	v_add_f32_e32 v14, v14, v167
	s_waitcnt lgkmcnt(5)
	v_mfma_f32_32x32x16_bf16 v[16:31], v[104:107], v[100:103], v[16:31]
	v_add_f32_e32 v14, v14, v184
	v_add_f32_e32 v14, v14, v185
	v_add_f32_e32 v14, v14, v186
	v_add_f32_e32 v14, v14, v187
	s_waitcnt lgkmcnt(4)
	v_mfma_f32_32x32x16_bf16 v[32:47], v[108:111], v[100:103], v[32:47]
	v_cvt_pk_bf16_f32 v96, v140, v141
	v_cvt_pk_bf16_f32 v97, v142, v143
	v_cvt_pk_bf16_f32 v98, v144, v145
	v_cvt_pk_bf16_f32 v99, v146, v147
	v_add_f32_e32 v14, v14, v136
	v_add_f32_e32 v14, v14, v137
	v_add_f32_e32 v14, v14, v138
	v_add_f32_e32 v14, v14, v139
	s_waitcnt lgkmcnt(3)
	v_mfma_f32_32x32x16_bf16 v[16:31], v[116:119], v[96:99], v[16:31]
	v_add_f32_e32 v14, v14, v140
	v_add_f32_e32 v14, v14, v141
	v_add_f32_e32 v14, v14, v142
	v_add_f32_e32 v14, v14, v143
	s_waitcnt lgkmcnt(2)
	v_mfma_f32_32x32x16_bf16 v[32:47], v[120:123], v[96:99], v[32:47]
	v_cvt_pk_bf16_f32 v100, v148, v149
	v_cvt_pk_bf16_f32 v101, v150, v151
	v_cvt_pk_bf16_f32 v102, v152, v153
	v_cvt_pk_bf16_f32 v103, v154, v155
	v_add_f32_e32 v14, v14, v144
	v_add_f32_e32 v14, v14, v145
	v_add_f32_e32 v14, v14, v146
	v_add_f32_e32 v14, v14, v147
	s_waitcnt lgkmcnt(1)
	v_mfma_f32_32x32x16_bf16 v[16:31], v[124:127], v[100:103], v[16:31]
	v_add_f32_e32 v14, v14, v148
	v_add_f32_e32 v14, v14, v149
	v_add_f32_e32 v14, v14, v150
	v_add_f32_e32 v14, v14, v151
	s_waitcnt lgkmcnt(0)
	v_mfma_f32_32x32x16_bf16 v[32:47], v[128:131], v[100:103], v[32:47]
	v_add_f32_e32 v14, v14, v152
	v_add_f32_e32 v14, v14, v153
	v_add_f32_e32 v14, v14, v154
	v_add_f32_e32 v14, v14, v155
	s_setprio 0
	ds_read_b128 v[116:119], v195 offset:27680
	ds_read_b128 v[124:127], v195 offset:32288
	ds_read_b128 v[128:131], v195 offset:27712
	ds_read_b128 v[132:135], v195 offset:27744
	ds_read_b128 v[136:139], v195 offset:32320
	ds_read_b128 v[140:143], v195 offset:32352
	s_cmp_lg_u32 s27, 4
	s_cselect_b32 s27, s34, 0
	s_waitcnt lgkmcnt(6)
	v_mfma_f32_32x32x16_bf16 v[152:167], v[240:243], v[180:183], v[48:63]
	v_exp_f32_e32 v15, v80
	v_exp_f32_e32 v144, v81
	v_exp_f32_e32 v145, v82
	v_exp_f32_e32 v146, v83
	s_waitcnt lgkmcnt(5)
	v_mfma_f32_32x32x16_bf16 v[96:111], v[244:247], v[180:183], v[48:63]
	v_exp_f32_e32 v147, v84
	v_exp_f32_e32 v148, v85
	v_exp_f32_e32 v149, v86
	v_exp_f32_e32 v150, v87
	v_mfma_f32_32x32x16_bf16 v[152:167], v[116:119], v[176:179], v[152:167]
	v_exp_f32_e32 v120, v88
	v_exp_f32_e32 v121, v89
	v_exp_f32_e32 v122, v90
	v_exp_f32_e32 v123, v91
	s_waitcnt lgkmcnt(4)
	v_mfma_f32_32x32x16_bf16 v[96:111], v[124:127], v[176:179], v[96:111]
	v_exp_f32_e32 v151, v92
	v_exp_f32_e32 v184, v93
	v_exp_f32_e32 v185, v94
	v_exp_f32_e32 v186, v95
	s_waitcnt lgkmcnt(3)
	v_mfma_f32_32x32x16_bf16 v[152:167], v[128:131], v[172:175], v[152:167]
	v_exp_f32_e32 v124, v64
	v_exp_f32_e32 v125, v65
	v_exp_f32_e32 v126, v66
	v_exp_f32_e32 v127, v67
	s_waitcnt lgkmcnt(1)
	v_mfma_f32_32x32x16_bf16 v[96:111], v[136:139], v[172:175], v[96:111]
	v_exp_f32_e32 v128, v68
	v_exp_f32_e32 v129, v69
	v_exp_f32_e32 v130, v70
	v_exp_f32_e32 v131, v71
	v_mfma_f32_32x32x16_bf16 v[152:167], v[132:135], v[168:171], v[152:167]
	v_exp_f32_e32 v136, v72
	v_exp_f32_e32 v137, v73
	v_exp_f32_e32 v138, v74
	v_exp_f32_e32 v139, v75
	s_waitcnt lgkmcnt(0)
	v_mfma_f32_32x32x16_bf16 v[96:111], v[140:143], v[168:171], v[96:111]
	v_exp_f32_e32 v132, v76
	v_exp_f32_e32 v133, v77
	v_exp_f32_e32 v134, v78
	v_exp_f32_e32 v135, v79
	s_cmp_gt_i32 s27, 2
	s_cselect_b32 s28, -3, 2
	s_add_i32 s28, s28, s27
	s_mulk_i32 s28, 0x2400
	s_waitcnt vmcnt(3)
	ds_write_b128 v208, v[6:9] offset:9216
	v_add_u32_e32 v6, s28, v208
	s_add_i32 s28, s27, 1
	s_cmp_lg_u32 s27, 4
	s_cselect_b32 s27, s28, 0
	s_add_i32 s28, s13, -1
	s_min_u32 s28, s28, s12
	s_lshl_b32 s92, s28, 13
	s_waitcnt vmcnt(2)
	ds_write_b128 v6, v[2:5] offset:36864
	v_lshl_add_u64 v[2:3], v[198:199], 0, s[92:93]
	s_lshl_b32 s92, s29, 7
	v_lshl_add_u64 v[4:5], v[196:197], 0, s[92:93]
	global_load_dwordx4 v[6:9], v[2:3], off
	s_nop 0
	global_load_dwordx4 v[2:5], v[4:5], off
	s_mul_i32 s29, s27, 0x2400
	s_add_i32 s34, s29, 0xffffdc00
	s_cmp_lg_u32 s27, 0
	s_cselect_b32 s34, s34, 0x9000
	v_add_u32_e32 v92, s34, v195
	ds_read_b128 v[64:67], v92 offset:36864
	ds_read_b128 v[68:71], v92 offset:36896
	ds_read_b128 v[72:75], v92 offset:41472
	ds_read_b128 v[76:79], v92 offset:41504
	ds_read_b128 v[80:83], v92 offset:36928
	ds_read_b128 v[84:87], v92 offset:36960
	ds_read_b128 v[88:91], v92 offset:41536
	ds_read_b128 v[92:95], v92 offset:41568
	s_setprio 3
	v_cvt_pk_bf16_f32 v116, v15, v144
	v_cvt_pk_bf16_f32 v117, v145, v146
	v_cvt_pk_bf16_f32 v118, v147, v148
	v_cvt_pk_bf16_f32 v119, v149, v150
	s_waitcnt lgkmcnt(7)
	s_nop 0
	v_mfma_f32_32x32x16_bf16 v[16:31], v[64:67], v[116:119], v[16:31]
	v_mov_b32_e32 v187, v15
	v_add_f32_e32 v187, v187, v144
	v_add_f32_e32 v187, v187, v145
	v_add_f32_e32 v187, v187, v146
	s_waitcnt lgkmcnt(5)
	v_mfma_f32_32x32x16_bf16 v[32:47], v[72:75], v[116:119], v[32:47]
	v_cvt_pk_bf16_f32 v64, v120, v121
	v_cvt_pk_bf16_f32 v65, v122, v123
	v_cvt_pk_bf16_f32 v66, v151, v184
	v_cvt_pk_bf16_f32 v67, v185, v186
	v_add_f32_e32 v187, v187, v147
	v_add_f32_e32 v187, v187, v148
	v_add_f32_e32 v187, v187, v149
	v_add_f32_e32 v187, v187, v150
	s_nop 0
	v_mfma_f32_32x32x16_bf16 v[16:31], v[68:71], v[64:67], v[16:31]
	v_add_f32_e32 v187, v187, v120
	v_add_f32_e32 v187, v187, v121
	v_add_f32_e32 v187, v187, v122
	v_add_f32_e32 v187, v187, v123
	s_waitcnt lgkmcnt(4)
	v_mfma_f32_32x32x16_bf16 v[32:47], v[76:79], v[64:67], v[32:47]
	v_cvt_pk_bf16_f32 v68, v124, v125
	v_cvt_pk_bf16_f32 v69, v126, v127
	v_cvt_pk_bf16_f32 v70, v128, v129
	v_cvt_pk_bf16_f32 v71, v130, v131
	v_add_f32_e32 v187, v187, v151
	v_add_f32_e32 v187, v187, v184
	v_add_f32_e32 v187, v187, v185
	v_add_f32_e32 v187, v187, v186
	s_waitcnt lgkmcnt(3)
	v_mfma_f32_32x32x16_bf16 v[16:31], v[80:83], v[68:71], v[16:31]
	v_add_f32_e32 v187, v187, v124
	v_add_f32_e32 v187, v187, v125
	v_add_f32_e32 v187, v187, v126
	v_add_f32_e32 v187, v187, v127
	s_waitcnt lgkmcnt(1)
	v_mfma_f32_32x32x16_bf16 v[32:47], v[88:91], v[68:71], v[32:47]
	v_cvt_pk_bf16_f32 v64, v136, v137
	v_cvt_pk_bf16_f32 v65, v138, v139
	v_cvt_pk_bf16_f32 v66, v132, v133
	v_cvt_pk_bf16_f32 v67, v134, v135
	v_add_f32_e32 v187, v187, v128
	v_add_f32_e32 v187, v187, v129
	v_add_f32_e32 v187, v187, v130
	v_add_f32_e32 v187, v187, v131
	s_nop 0
	v_mfma_f32_32x32x16_bf16 v[16:31], v[84:87], v[64:67], v[16:31]
	v_add_f32_e32 v187, v187, v136
	v_add_f32_e32 v187, v187, v137
	v_add_f32_e32 v187, v187, v138
	v_add_f32_e32 v187, v187, v139
	s_waitcnt lgkmcnt(0)
	v_mfma_f32_32x32x16_bf16 v[32:47], v[92:95], v[64:67], v[32:47]
	v_add_f32_e32 v187, v187, v132
	v_add_f32_e32 v187, v187, v133
	v_add_f32_e32 v187, v187, v134
	v_add_f32_e32 v187, v187, v135
	s_setprio 2
	s_waitcnt lgkmcnt(0)
	s_barrier
	ds_read_b128 v[240:243], v195
	ds_read_b128 v[244:247], v195 offset:4608
	ds_read_b128 v[72:75], v195 offset:32
	ds_read_b128 v[76:79], v195 offset:4640
	ds_read_b128 v[80:83], v195 offset:64
	ds_read_b128 v[84:87], v195 offset:4672
	ds_read_b128 v[88:91], v195 offset:96
	ds_read_b128 v[92:95], v195 offset:4704
	v_add_f32_e32 v1, v1, v14
	s_waitcnt lgkmcnt(6)
	v_mfma_f32_32x32x16_bf16 v[136:151], v[240:243], v[180:183], v[48:63]
	v_exp_f32_e32 v14, v152
	v_exp_f32_e32 v15, v153
	v_exp_f32_e32 v116, v154
	v_exp_f32_e32 v117, v155
	v_mfma_f32_32x32x16_bf16 v[120:135], v[244:247], v[180:183], v[48:63]
	v_exp_f32_e32 v118, v156
	v_exp_f32_e32 v119, v157
	v_exp_f32_e32 v184, v158
	v_exp_f32_e32 v185, v159
	s_waitcnt lgkmcnt(5)
	v_mfma_f32_32x32x16_bf16 v[136:151], v[72:75], v[176:179], v[136:151]
	v_exp_f32_e32 v186, v160
	v_exp_f32_e32 v210, v161
	v_exp_f32_e32 v211, v162
	v_exp_f32_e32 v212, v163
	s_waitcnt lgkmcnt(4)
	v_mfma_f32_32x32x16_bf16 v[120:135], v[76:79], v[176:179], v[120:135]
	v_exp_f32_e32 v160, v164
	v_exp_f32_e32 v161, v165
	v_exp_f32_e32 v162, v166
	v_exp_f32_e32 v163, v167
	s_waitcnt lgkmcnt(3)
	v_mfma_f32_32x32x16_bf16 v[136:151], v[80:83], v[172:175], v[136:151]
	v_exp_f32_e32 v164, v96
	v_exp_f32_e32 v165, v97
	v_exp_f32_e32 v166, v98
	v_exp_f32_e32 v167, v99
	s_waitcnt lgkmcnt(2)
	v_mfma_f32_32x32x16_bf16 v[120:135], v[84:87], v[172:175], v[120:135]
	v_exp_f32_e32 v96, v100
	v_exp_f32_e32 v97, v101
	v_exp_f32_e32 v98, v102
	v_exp_f32_e32 v99, v103
	s_waitcnt lgkmcnt(1)
	v_mfma_f32_32x32x16_bf16 v[136:151], v[88:91], v[168:171], v[136:151]
	v_exp_f32_e32 v100, v104
	v_exp_f32_e32 v101, v105
	v_exp_f32_e32 v102, v106
	v_exp_f32_e32 v103, v107
	s_waitcnt lgkmcnt(0)
	v_mfma_f32_32x32x16_bf16 v[120:135], v[92:95], v[168:171], v[120:135]
	v_exp_f32_e32 v104, v108
	v_exp_f32_e32 v105, v109
	v_exp_f32_e32 v106, v110
	v_exp_f32_e32 v107, v111
	s_cmp_gt_i32 s27, 2
	s_cselect_b32 s34, -3, 2
	s_add_i32 s34, s34, s27
	s_mulk_i32 s34, 0x2400
	v_add_u32_e32 v88, s29, v195
	s_min_u32 s29, s13, s12
	s_waitcnt vmcnt(3)
	ds_write_b128 v208, v[10:13] offset:18432
	v_add_u32_e32 v10, s34, v208
	s_lshl_b32 s92, s29, 13
	s_waitcnt vmcnt(2)
	ds_write_b128 v10, v[112:115] offset:36864
	v_lshl_add_u64 v[10:11], v[198:199], 0, s[92:93]
	s_lshl_b32 s92, s28, 7
	global_load_dwordx4 v[152:155], v[10:11], off
	v_lshl_add_u64 v[10:11], v[196:197], 0, s[92:93]
	global_load_dwordx4 v[156:159], v[10:11], off
	ds_read_b128 v[240:243], v195 offset:9216
	ds_read_b128 v[244:247], v195 offset:13824
	ds_read_b128 v[10:13], v88 offset:41472
	ds_read_b128 v[64:67], v88 offset:36864
	ds_read_b128 v[68:71], v88 offset:36896
	ds_read_b128 v[72:75], v88 offset:41504
	ds_read_b128 v[76:79], v88 offset:36928
	ds_read_b128 v[80:83], v88 offset:41536
	ds_read_b128 v[84:87], v88 offset:36960
	ds_read_b128 v[88:91], v88 offset:41568
	v_add_f32_e32 v1, v1, v187
	s_setprio 1
	v_mov_b32_e32 v109, v136
	v_cvt_pk_bf16_f32 v92, v14, v15
	v_cvt_pk_bf16_f32 v93, v116, v117
	v_cvt_pk_bf16_f32 v94, v118, v119
	v_cvt_pk_bf16_f32 v95, v184, v185
	s_waitcnt lgkmcnt(6)
	s_nop 0
	v_mfma_f32_32x32x16_bf16 v[16:31], v[64:67], v[92:95], v[16:31]
	v_max3_f32 v109, v109, v137, v138
	v_max3_f32 v109, v109, v139, v140
	v_mov_b32_e32 v108, v14
	v_add_f32_e32 v108, v108, v15
	v_add_f32_e32 v108, v108, v116
	v_add_f32_e32 v108, v108, v117
	s_nop 0
	v_mfma_f32_32x32x16_bf16 v[32:47], v[10:13], v[92:95], v[32:47]
	v_cvt_pk_bf16_f32 v64, v186, v210
	v_cvt_pk_bf16_f32 v65, v211, v212
	v_cvt_pk_bf16_f32 v66, v160, v161
	v_cvt_pk_bf16_f32 v67, v162, v163
	v_max3_f32 v109, v109, v141, v142
	v_max3_f32 v109, v109, v143, v144
	v_add_f32_e32 v108, v108, v118
	v_add_f32_e32 v108, v108, v119
	v_add_f32_e32 v108, v108, v184
	v_add_f32_e32 v108, v108, v185
	s_waitcnt lgkmcnt(5)
	v_mfma_f32_32x32x16_bf16 v[16:31], v[68:71], v[64:67], v[16:31]
	v_max3_f32 v109, v109, v145, v146
	v_max3_f32 v109, v109, v147, v148
	v_add_f32_e32 v108, v108, v186
	v_add_f32_e32 v108, v108, v210
	v_add_f32_e32 v108, v108, v211
	v_add_f32_e32 v108, v108, v212
	s_waitcnt lgkmcnt(4)
	v_mfma_f32_32x32x16_bf16 v[32:47], v[72:75], v[64:67], v[32:47]
	v_cvt_pk_bf16_f32 v10, v164, v165
	v_cvt_pk_bf16_f32 v11, v166, v167
	v_cvt_pk_bf16_f32 v12, v96, v97
	v_cvt_pk_bf16_f32 v13, v98, v99
	v_max3_f32 v109, v109, v149, v150
	v_max3_f32 v109, v109, v151, v120
	v_add_f32_e32 v108, v108, v160
	v_add_f32_e32 v108, v108, v161
	v_add_f32_e32 v108, v108, v162
	v_add_f32_e32 v108, v108, v163
	s_waitcnt lgkmcnt(3)
	v_mfma_f32_32x32x16_bf16 v[16:31], v[76:79], v[10:13], v[16:31]
	v_max3_f32 v109, v109, v121, v122
	v_max3_f32 v109, v109, v123, v124
	v_add_f32_e32 v108, v108, v164
	v_add_f32_e32 v108, v108, v165
	v_add_f32_e32 v108, v108, v166
	v_add_f32_e32 v108, v108, v167
	s_waitcnt lgkmcnt(2)
	v_mfma_f32_32x32x16_bf16 v[32:47], v[80:83], v[10:13], v[32:47]
	v_cvt_pk_bf16_f32 v64, v100, v101
	v_cvt_pk_bf16_f32 v65, v102, v103
	v_cvt_pk_bf16_f32 v66, v104, v105
	v_cvt_pk_bf16_f32 v67, v106, v107
	v_max3_f32 v109, v109, v125, v126
	v_max3_f32 v109, v109, v127, v128
	v_add_f32_e32 v108, v108, v96
	v_add_f32_e32 v108, v108, v97
	v_add_f32_e32 v108, v108, v98
	v_add_f32_e32 v108, v108, v99
	s_waitcnt lgkmcnt(1)
	v_mfma_f32_32x32x16_bf16 v[16:31], v[84:87], v[64:67], v[16:31]
	v_max3_f32 v109, v109, v129, v130
	v_max3_f32 v109, v109, v131, v132
	v_add_f32_e32 v108, v108, v100
	v_add_f32_e32 v108, v108, v101
	v_add_f32_e32 v108, v108, v102
	v_add_f32_e32 v108, v108, v103
	s_waitcnt lgkmcnt(0)
	v_mfma_f32_32x32x16_bf16 v[32:47], v[88:91], v[64:67], v[32:47]
	v_max3_f32 v109, v109, v133, v134
	v_max3_f32 v109, v109, v135, v135
	v_add_f32_e32 v108, v108, v104
	v_add_f32_e32 v108, v108, v105
	v_add_f32_e32 v108, v108, v106
	v_add_f32_e32 v108, v108, v107
	s_setprio 0
	ds_read_b128 v[164:167], v195 offset:9248
	ds_read_b128 v[160:163], v195 offset:13856
	ds_read_b128 v[74:77], v195 offset:9280
	ds_read_b128 v[66:69], v195 offset:9312
	ds_read_b128 v[70:73], v195 offset:13888
	ds_read_b128 v[10:13], v195 offset:13920
	v_add_f32_e32 v64, v1, v108
	v_mov_b32_e32 v1, v109
	s_nop 1
	v_permlane32_swap_b32_e32 v109, v1
	v_max_f32_e32 v1, v1, v1
	v_max_f32_e32 v14, v109, v109
	v_max_f32_e32 v1, v14, v1
	v_cmp_lt_f32_e32 vcc, s52, v1
	s_cbranch_vccz .LBB0_663
	v_max_f32_e32 v1, v1, v1
	v_max_f32_e32 v14, 0, v1
	v_add_f32_e32 v209, v209, v14
	v_xor_b32_e32 v48, 0x80000000, v209
	v_pk_add_f32 v[136:137], v[136:137], v[14:15] op_sel_hi:[1,0] neg_lo:[0,1] neg_hi:[0,1]
	v_pk_add_f32 v[120:121], v[120:121], v[14:15] op_sel_hi:[1,0] neg_lo:[0,1] neg_hi:[0,1]
	v_pk_add_f32 v[138:139], v[138:139], v[14:15] op_sel_hi:[1,0] neg_lo:[0,1] neg_hi:[0,1]
	v_pk_add_f32 v[122:123], v[122:123], v[14:15] op_sel_hi:[1,0] neg_lo:[0,1] neg_hi:[0,1]
	v_pk_add_f32 v[140:141], v[140:141], v[14:15] op_sel_hi:[1,0] neg_lo:[0,1] neg_hi:[0,1]
	v_pk_add_f32 v[124:125], v[124:125], v[14:15] op_sel_hi:[1,0] neg_lo:[0,1] neg_hi:[0,1]
	v_pk_add_f32 v[142:143], v[142:143], v[14:15] op_sel_hi:[1,0] neg_lo:[0,1] neg_hi:[0,1]
	v_pk_add_f32 v[126:127], v[126:127], v[14:15] op_sel_hi:[1,0] neg_lo:[0,1] neg_hi:[0,1]
	v_pk_add_f32 v[144:145], v[144:145], v[14:15] op_sel_hi:[1,0] neg_lo:[0,1] neg_hi:[0,1]
	v_pk_add_f32 v[128:129], v[128:129], v[14:15] op_sel_hi:[1,0] neg_lo:[0,1] neg_hi:[0,1]
	v_pk_add_f32 v[146:147], v[146:147], v[14:15] op_sel_hi:[1,0] neg_lo:[0,1] neg_hi:[0,1]
	v_pk_add_f32 v[130:131], v[130:131], v[14:15] op_sel_hi:[1,0] neg_lo:[0,1] neg_hi:[0,1]
	v_pk_add_f32 v[148:149], v[148:149], v[14:15] op_sel_hi:[1,0] neg_lo:[0,1] neg_hi:[0,1]
	v_pk_add_f32 v[132:133], v[132:133], v[14:15] op_sel_hi:[1,0] neg_lo:[0,1] neg_hi:[0,1]
	v_pk_add_f32 v[150:151], v[150:151], v[14:15] op_sel_hi:[1,0] neg_lo:[0,1] neg_hi:[0,1]
	v_pk_add_f32 v[134:135], v[134:135], v[14:15] op_sel_hi:[1,0] neg_lo:[0,1] neg_hi:[0,1]
	v_exp_f32_e64 v14, -v14
	v_mov_b32_e32 v49, v48
	v_mov_b32_e32 v50, v48
	v_mov_b32_e32 v51, v48
	v_mov_b32_e32 v52, v48
	v_mov_b32_e32 v53, v48
	v_mov_b32_e32 v54, v48
	v_mov_b32_e32 v55, v48
	v_mov_b32_e32 v56, v48
	v_mov_b32_e32 v57, v48
	v_mov_b32_e32 v58, v48
	v_mov_b32_e32 v59, v48
	v_mov_b32_e32 v60, v48
	v_mov_b32_e32 v61, v48
	v_mov_b32_e32 v62, v48
	v_mov_b32_e32 v63, v48
	s_nop 11
	v_pk_mul_f32 v[30:31], v[30:31], v[14:15] op_sel_hi:[1,0]
	v_pk_mul_f32 v[28:29], v[28:29], v[14:15] op_sel_hi:[1,0]
	v_pk_mul_f32 v[26:27], v[26:27], v[14:15] op_sel_hi:[1,0]
	v_pk_mul_f32 v[24:25], v[24:25], v[14:15] op_sel_hi:[1,0]
	v_pk_mul_f32 v[22:23], v[22:23], v[14:15] op_sel_hi:[1,0]
	v_pk_mul_f32 v[20:21], v[20:21], v[14:15] op_sel_hi:[1,0]
	v_pk_mul_f32 v[18:19], v[18:19], v[14:15] op_sel_hi:[1,0]
	v_pk_mul_f32 v[16:17], v[16:17], v[14:15] op_sel_hi:[1,0]
	v_pk_mul_f32 v[46:47], v[46:47], v[14:15] op_sel_hi:[1,0]
	v_pk_mul_f32 v[44:45], v[44:45], v[14:15] op_sel_hi:[1,0]
	v_pk_mul_f32 v[42:43], v[42:43], v[14:15] op_sel_hi:[1,0]
	v_pk_mul_f32 v[40:41], v[40:41], v[14:15] op_sel_hi:[1,0]
	v_pk_mul_f32 v[38:39], v[38:39], v[14:15] op_sel_hi:[1,0]
	v_pk_mul_f32 v[36:37], v[36:37], v[14:15] op_sel_hi:[1,0]
	v_pk_mul_f32 v[34:35], v[34:35], v[14:15] op_sel_hi:[1,0]
	v_pk_mul_f32 v[32:33], v[32:33], v[14:15] op_sel_hi:[1,0]
	v_mul_f32_e32 v64, v64, v14

.LBB0_694:
	s_and_b64 vcc, exec, s[12:13]
	s_cbranch_vccz .LBB0_705
	v_mov_b32_e32 v1, v222
	v_mov_b32_e32 v53, v0
	v_readfirstlane_b32 s1, v1
	s_ashr_i32 s2, s1, 8
	s_lshr_b32 s1, s1, 1
	s_add_i32 s12, s2, s23
	s_and_b32 s29, s1, 0x60
	s_add_i32 s1, s12, s24
	s_mul_hi_i32 s2, s1, 0x4100
	s_mulk_i32 s1, 0x4100
	s_add_u32 s1, s1, s63
	s_addc_u32 s2, s2, s22
	s_or_b32 s1, s1, s29
	s_add_u32 s22, s96, s19
	v_and_b32_e32 v182, 31, v1
	v_mov_b32_e32 v3, s2
	s_addc_u32 s23, s97, s18
	s_add_i32 s2, s63, 0x100
	v_or_b32_e32 v2, s1, v182
	s_lshr_b32 s2, s2, 6
	v_bfe_u32 v200, v1, 5, 1
	v_lshlrev_b64 v[2:3], 7, v[2:3]
	s_add_i32 s1, s63, 0xffffff80
	s_min_u32 s2, s2, 0x104
	v_lshl_add_u64 v[2:3], s[30:31], 0, v[2:3]
	v_lshlrev_b32_e32 v52, 4, v200
	s_ashr_i32 s1, s1, 6
	s_add_i32 s2, s2, 4
	v_ashrrev_i32_e32 v54, 3, v1
	v_lshl_add_u64 v[2:3], v[2:3], 0, v[52:53]
	s_add_u32 s24, s42, s19
	v_ashrrev_i32_e32 v55, 31, v54
	global_load_dwordx4 v[164:167], v[2:3], off
	global_load_dwordx4 v[160:163], v[2:3], off offset:32
	global_load_dwordx4 v[156:159], v[2:3], off offset:64
	global_load_dwordx4 v[152:155], v[2:3], off offset:96
	s_addc_u32 s25, s43, s18
	v_lshlrev_b64 v[2:3], 7, v[54:55]
	v_lshlrev_b32_e32 v1, 4, v1
	v_and_b32_e32 v56, 0x70, v1
	v_mov_b32_e32 v57, v0
	v_lshl_add_u64 v[2:3], s[24:25], 0, v[2:3]
	v_lshl_add_u64 v[198:199], v[2:3], 0, v[56:57]
	v_mov_b64_e32 v[4:5], s[22:23]
	v_add_co_u32_e32 v44, vcc, s3, v198
	v_mad_i64_i32 v[4:5], s[18:19], v54, s55, v[4:5]
	v_mov_b32_e32 v14, v0
	v_mov_b32_e32 v15, v0
	v_addc_co_u32_e32 v45, vcc, 0, v199, vcc
	v_lshl_add_u64 v[196:197], v[4:5], 0, v[56:57]
	v_mov_b32_e32 v1, v0
	v_mov_b32_e32 v2, v0
	v_mov_b32_e32 v3, v0
	v_mov_b32_e32 v4, v0
	v_mov_b32_e32 v5, v0
	v_mov_b32_e32 v6, v0
	v_mov_b32_e32 v7, v0
	v_mov_b32_e32 v8, v0
	v_mov_b32_e32 v9, v0
	v_mov_b32_e32 v10, v0
	v_mov_b32_e32 v11, v0
	v_mov_b32_e32 v12, v0
	v_mov_b32_e32 v13, v0
	v_mov_b64_e32 v[30:31], v[14:15]
	v_add_co_u32_e32 v48, vcc, s59, v198
	v_mov_b64_e32 v[28:29], v[12:13]
	v_mov_b64_e32 v[26:27], v[10:11]
	v_mov_b64_e32 v[24:25], v[8:9]
	v_mov_b64_e32 v[22:23], v[6:7]
	v_mov_b64_e32 v[20:21], v[4:5]
	v_mov_b64_e32 v[18:19], v[2:3]
	v_mov_b64_e32 v[16:17], v[0:1]
	v_addc_co_u32_e32 v49, vcc, 0, v199, vcc
	global_load_dwordx4 v[32:35], v[198:199], off
	global_load_dwordx4 v[36:39], v[196:197], off
	global_load_dwordx4 v[40:43], v[196:197], off offset:128
	s_nop 0
	global_load_dwordx4 v[44:47], v[44:45], off
	s_nop 0
	global_load_dwordx4 v[48:51], v[48:49], off
	v_mul_u32_u24_e32 v53, 0x90, v182
	v_mad_u64_u32 v[194:195], s[18:19], v54, s60, v[56:57]
	v_add3_u32 v201, 0, v53, v52
	v_add_co_u32_e32 v52, vcc, s33, v198
	v_add_u32_e32 v203, 0, v194
	s_nop 0
	v_addc_co_u32_e32 v53, vcc, 0, v199, vcc
	global_load_dwordx4 v[64:67], v[196:197], off offset:256
	global_load_dwordx4 v[68:71], v[52:53], off
	s_max_i32 s1, s1, 4
	s_cmp_gt_i32 s73, 1
	s_cselect_b32 s2, s2, 8
	s_cselect_b32 s18, s1, 4
	s_sub_i32 s1, s2, s18
	s_add_i32 s92, s1, -1
	s_add_i32 s13, s18, -4
	s_min_i32 s2, s92, 4
	s_barrier
	s_waitcnt vmcnt(5)
	ds_write_b128 v203, v[36:39] offset:36864
	s_waitcnt vmcnt(4)
	ds_write_b128 v203, v[40:43] offset:46080
	ds_write_b128 v203, v[32:35]
	s_waitcnt vmcnt(3)
	ds_write_b128 v203, v[44:47] offset:9216
	s_waitcnt vmcnt(2)
	ds_write_b128 v203, v[48:51] offset:18432
	s_waitcnt lgkmcnt(0)
	s_barrier
	ds_read_b128 v[48:51], v201
	ds_read_b128 v[52:55], v201 offset:32
	s_waitcnt lgkmcnt(1)
	v_mfma_f32_32x32x16_bf16 v[32:47], v[48:51], v[164:167], v[16:31]
	ds_read_b128 v[48:51], v201 offset:4608
	ds_read_b128 v[56:59], v201 offset:4640
	s_min_i32 s19, s92, 3
	s_cmp_gt_i32 s1, 4
	s_cselect_b32 s28, s13, 0
	s_lshl_b32 s22, s19, 6
	s_add_i32 s24, s2, s28
	s_ashr_i32 s23, s22, 31
	s_waitcnt lgkmcnt(1)
	v_mfma_f32_32x32x16_bf16 v[16:31], v[48:51], v[164:167], v[16:31]
	ds_read_b128 v[48:51], v201 offset:64
	s_ashr_i32 s25, s24, 31
	s_mov_b32 s34, 1
	v_or_b32_e32 v150, s63, v182
	s_waitcnt lgkmcnt(1)
	v_mfma_f32_32x32x16_bf16 v[16:31], v[56:59], v[160:163], v[16:31]
	v_mfma_f32_32x32x16_bf16 v[32:47], v[52:55], v[160:163], v[32:47]
	ds_read_b128 v[52:55], v201 offset:4672
	ds_read_b128 v[56:59], v201 offset:96
	s_waitcnt lgkmcnt(1)
	v_mfma_f32_32x32x16_bf16 v[16:31], v[52:55], v[156:159], v[16:31]
	v_lshl_add_u64 v[52:53], s[22:23], 1, v[196:197]
	s_lshl_b64 s[22:23], s[24:25], 13
	v_lshl_add_u64 v[54:55], v[198:199], 0, s[22:23]
	v_mfma_f32_32x32x16_bf16 v[32:47], v[48:51], v[156:159], v[32:47]
	ds_read_b128 v[48:51], v201 offset:4704
	global_load_dwordx4 v[168:171], v[54:55], off
	global_load_dwordx4 v[172:175], v[52:53], off
	s_waitcnt lgkmcnt(1)
	v_mfma_f32_32x32x16_bf16 v[32:47], v[56:59], v[152:155], v[32:47]
	s_waitcnt lgkmcnt(0)
	v_mfma_f32_32x32x16_bf16 v[16:31], v[48:51], v[152:155], v[16:31]
	v_max3_f32 v48, v32, v33, v34
	s_nop 0
	v_max3_f32 v48, v48, v35, v36
	s_nop 0
	v_max3_f32 v48, v48, v37, v38
	s_nop 0
	v_max3_f32 v48, v48, v39, v40
	s_nop 0
	v_max3_f32 v48, v48, v41, v42
	s_nop 0
	v_max3_f32 v48, v48, v43, v44
	s_nop 0
	v_max3_f32 v48, v48, v45, v46
	s_nop 0
	v_max3_f32 v48, v48, v47, v16
	s_nop 0
	v_max3_f32 v48, v48, v17, v18
	s_nop 0
	v_max3_f32 v48, v48, v19, v20
	s_nop 0
	v_max3_f32 v48, v48, v21, v22
	s_nop 0
	v_max3_f32 v48, v48, v23, v24
	s_nop 0
	v_max3_f32 v48, v48, v25, v26
	s_nop 0
	v_max3_f32 v48, v48, v27, v28
	s_nop 0
	v_max3_f32 v48, v48, v29, v30
	s_nop 0
	v_max3_f32 v48, v48, v31, v31
	s_setprio 0
	ds_read_b128 v[72:75], v201 offset:9216
	ds_read_b128 v[76:79], v201 offset:9248
	ds_read_b128 v[120:123], v201 offset:13824
	ds_read_b128 v[124:127], v201 offset:13856
	ds_read_b128 v[128:131], v201 offset:9280
	ds_read_b128 v[132:135], v201 offset:9312
	ds_read_b128 v[136:139], v201 offset:13888
	ds_read_b128 v[142:145], v201 offset:13920
	v_mov_b32_e32 v49, v48
	s_nop 1
	v_permlane32_swap_b32_e32 v48, v49
	v_max_f32_e32 v49, v49, v49
	v_max_f32_e32 v48, v48, v48
	v_max_f32_e32 v49, v48, v49
	v_add_f32_e32 v195, 0, v49
	v_xor_b32_e32 v48, 0x80000000, v195
	v_sub_f32_e32 v32, v32, v49
	v_sub_f32_e32 v16, v16, v49
	v_sub_f32_e32 v33, v33, v49
	v_sub_f32_e32 v17, v17, v49
	v_sub_f32_e32 v34, v34, v49
	v_sub_f32_e32 v18, v18, v49
	v_sub_f32_e32 v35, v35, v49
	v_sub_f32_e32 v19, v19, v49
	v_sub_f32_e32 v36, v36, v49
	v_sub_f32_e32 v20, v20, v49
	v_sub_f32_e32 v37, v37, v49
	v_sub_f32_e32 v21, v21, v49
	v_sub_f32_e32 v38, v38, v49
	v_sub_f32_e32 v22, v22, v49
	v_sub_f32_e32 v39, v39, v49
	v_sub_f32_e32 v23, v23, v49
	v_sub_f32_e32 v40, v40, v49
	v_sub_f32_e32 v24, v24, v49
	v_sub_f32_e32 v41, v41, v49
	v_sub_f32_e32 v25, v25, v49
	v_sub_f32_e32 v42, v42, v49
	v_sub_f32_e32 v26, v26, v49
	v_sub_f32_e32 v43, v43, v49
	v_sub_f32_e32 v27, v27, v49
	v_sub_f32_e32 v44, v44, v49
	v_sub_f32_e32 v28, v28, v49
	v_sub_f32_e32 v45, v45, v49
	v_sub_f32_e32 v29, v29, v49
	v_sub_f32_e32 v46, v46, v49
	v_sub_f32_e32 v30, v30, v49
	v_sub_f32_e32 v47, v47, v49
	v_sub_f32_e32 v31, v31, v49
	v_mov_b32_e32 v49, v48
	v_mov_b32_e32 v50, v48
	v_mov_b32_e32 v51, v48
	v_mov_b32_e32 v52, v48
	v_mov_b32_e32 v53, v48
	v_mov_b32_e32 v54, v48
	v_mov_b32_e32 v55, v48
	v_mov_b32_e32 v56, v48
	v_mov_b32_e32 v57, v48
	v_mov_b32_e32 v58, v48
	v_mov_b32_e32 v59, v48
	v_mov_b32_e32 v60, v48
	v_mov_b32_e32 v61, v48
	v_mov_b32_e32 v62, v48
	v_mov_b32_e32 v63, v48
	s_waitcnt lgkmcnt(7)
	s_nop 4
	v_mfma_f32_32x32x16_bf16 v[96:111], v[72:75], v[164:167], v[48:63]
	v_exp_f32_e32 v116, v32
	v_exp_f32_e32 v117, v33
	v_exp_f32_e32 v118, v34
	v_exp_f32_e32 v119, v35
	s_nop 0
	s_waitcnt lgkmcnt(5)
	s_nop 4
	v_mfma_f32_32x32x16_bf16 v[80:95], v[120:123], v[164:167], v[48:63]
	v_exp_f32_e32 v112, v36
	v_exp_f32_e32 v113, v37
	v_exp_f32_e32 v114, v38
	v_exp_f32_e32 v115, v39
	s_nop 0
	v_mfma_f32_32x32x16_bf16 v[96:111], v[76:79], v[160:163], v[96:111]
	v_exp_f32_e32 v208, v40
	v_exp_f32_e32 v207, v41
	v_exp_f32_e32 v206, v42
	v_exp_f32_e32 v205, v43
	s_nop 0
	s_waitcnt lgkmcnt(4)
	v_mfma_f32_32x32x16_bf16 v[80:95], v[124:127], v[160:163], v[80:95]
	v_exp_f32_e32 v204, v44
	v_exp_f32_e32 v187, v45
	v_exp_f32_e32 v186, v46
	v_exp_f32_e32 v185, v47
	s_nop 0
	s_waitcnt lgkmcnt(3)
	v_mfma_f32_32x32x16_bf16 v[96:111], v[128:131], v[156:159], v[96:111]
	v_exp_f32_e32 v177, v16
	v_exp_f32_e32 v176, v17
	v_exp_f32_e32 v149, v18
	v_exp_f32_e32 v148, v19
	s_nop 0
	s_waitcnt lgkmcnt(1)
	v_mfma_f32_32x32x16_bf16 v[80:95], v[136:139], v[156:159], v[80:95]
	v_exp_f32_e32 v147, v20
	v_exp_f32_e32 v146, v21
	v_exp_f32_e32 v141, v22
	v_exp_f32_e32 v140, v23
	s_nop 0
	v_mfma_f32_32x32x16_bf16 v[96:111], v[132:135], v[152:155], v[96:111]
	v_exp_f32_e32 v123, v24
	v_exp_f32_e32 v122, v25
	v_exp_f32_e32 v121, v26
	v_exp_f32_e32 v120, v27
	s_nop 0
	s_waitcnt lgkmcnt(0)
	v_mfma_f32_32x32x16_bf16 v[80:95], v[142:145], v[152:155], v[80:95]
	v_exp_f32_e32 v127, v28
	v_exp_f32_e32 v126, v29
	v_exp_f32_e32 v125, v30
	v_exp_f32_e32 v124, v31
	s_nop 0
	v_or_b32_e32 v202, s29, v150
	s_cmp_lt_i32 s1, 9
	s_waitcnt vmcnt(2)
	ds_write_b128 v203, v[68:71] offset:27648
	ds_write_b128 v203, v[64:67] offset:55296
	s_cbranch_scc1 .LBB0_706
	v_lshlrev_b32_e32 v183, 2, v200
	v_sub_u32_e32 v16, v183, v202
	v_add_u32_e32 v184, 0xffffff00, v16
	v_mov_b64_e32 v[30:31], v[14:15]
	v_mov_b64_e32 v[46:47], v[14:15]
	s_or_b32 s19, s18, 1
	v_mov_b32_e32 v64, 0
	s_mov_b32 s77, 8
	s_mov_b32 s45, 1
	v_mov_b64_e32 v[28:29], v[12:13]
	v_mov_b64_e32 v[26:27], v[10:11]
	v_mov_b64_e32 v[24:25], v[8:9]
	v_mov_b64_e32 v[22:23], v[6:7]
	v_mov_b64_e32 v[20:21], v[4:5]
	v_mov_b64_e32 v[18:19], v[2:3]
	v_mov_b64_e32 v[16:17], v[0:1]
	v_mov_b64_e32 v[44:45], v[12:13]
	v_mov_b64_e32 v[42:43], v[10:11]
	v_mov_b64_e32 v[40:41], v[8:9]
	v_mov_b64_e32 v[38:39], v[6:7]
	v_mov_b64_e32 v[36:37], v[4:5]
	v_mov_b64_e32 v[34:35], v[2:3]
	v_mov_b64_e32 v[32:33], v[0:1]
.LBB0_697:
	s_add_i32 s22, s45, s18
	s_ashr_i32 s23, s22, 31
	s_lshl_b64 s[24:25], s[22:23], 13
	s_lshl_b32 s22, s22, 6
	v_lshl_add_u64 v[2:3], v[198:199], 0, s[24:25]
	s_sub_i32 s24, s22, 64
	s_ashr_i32 s25, s24, 31
	v_lshl_add_u64 v[4:5], s[24:25], 1, v[196:197]
	global_load_dwordx4 v[6:9], v[2:3], off
	s_nop 0
	global_load_dwordx4 v[2:5], v[4:5], off
	s_mul_i32 s2, s34, 0x2400
	s_add_i32 s23, s2, 0xffffdc00
	s_cmp_lg_u32 s34, 0
	s_cselect_b32 s23, s23, 0x9000
	v_add_u32_e32 v1, s23, v201
	ds_read_b128 v[10:13], v1 offset:36864
	ds_read_b128 v[66:69], v1 offset:36896
	ds_read_b128 v[70:73], v1 offset:41472
	ds_read_b128 v[74:77], v1 offset:41504
	ds_read_b128 v[128:131], v1 offset:36928
	ds_read_b128 v[132:135], v1 offset:36960
	ds_read_b128 v[136:139], v1 offset:41536
	ds_read_b128 v[142:145], v1 offset:41568
	s_setprio 3
	v_cvt_pk_bf16_f32 v178, v116, v117
	v_cvt_pk_bf16_f32 v179, v118, v119
	v_cvt_pk_bf16_f32 v180, v112, v113
	v_cvt_pk_bf16_f32 v181, v114, v115
	s_waitcnt lgkmcnt(7)
	s_nop 0
	v_mfma_f32_32x32x16_bf16 v[16:31], v[10:13], v[178:181], v[16:31]
	v_mov_b32_e32 v1, v116
	v_add_f32_e32 v1, v1, v117
	v_add_f32_e32 v1, v1, v118
	v_add_f32_e32 v1, v1, v119
	s_waitcnt lgkmcnt(5)
	v_mfma_f32_32x32x16_bf16 v[32:47], v[70:73], v[178:181], v[32:47]
	v_cvt_pk_bf16_f32 v10, v208, v207
	v_cvt_pk_bf16_f32 v11, v206, v205
	v_cvt_pk_bf16_f32 v12, v204, v187
	v_cvt_pk_bf16_f32 v13, v186, v185
	v_add_f32_e32 v1, v1, v112
	v_add_f32_e32 v1, v1, v113
	v_add_f32_e32 v1, v1, v114
	v_add_f32_e32 v1, v1, v115
	s_nop 0
	v_mfma_f32_32x32x16_bf16 v[16:31], v[66:69], v[10:13], v[16:31]
	v_add_f32_e32 v1, v1, v208
	v_add_f32_e32 v1, v1, v207
	v_add_f32_e32 v1, v1, v206
	v_add_f32_e32 v1, v1, v205
	s_waitcnt lgkmcnt(4)
	v_mfma_f32_32x32x16_bf16 v[32:47], v[74:77], v[10:13], v[32:47]
	v_cvt_pk_bf16_f32 v66, v177, v176
	v_cvt_pk_bf16_f32 v67, v149, v148
	v_cvt_pk_bf16_f32 v68, v147, v146
	v_cvt_pk_bf16_f32 v69, v141, v140
	v_add_f32_e32 v1, v1, v204
	v_add_f32_e32 v1, v1, v187
	v_add_f32_e32 v1, v1, v186
	v_add_f32_e32 v1, v1, v185
	s_waitcnt lgkmcnt(3)
	v_mfma_f32_32x32x16_bf16 v[16:31], v[128:131], v[66:69], v[16:31]
	v_add_f32_e32 v1, v1, v177
	v_add_f32_e32 v1, v1, v176
	v_add_f32_e32 v1, v1, v149
	v_add_f32_e32 v1, v1, v148
	s_waitcnt lgkmcnt(1)
	v_mfma_f32_32x32x16_bf16 v[32:47], v[136:139], v[66:69], v[32:47]
	v_cvt_pk_bf16_f32 v10, v123, v122
	v_cvt_pk_bf16_f32 v11, v121, v120
	v_cvt_pk_bf16_f32 v12, v127, v126
	v_cvt_pk_bf16_f32 v13, v125, v124
	v_add_f32_e32 v1, v1, v147
	v_add_f32_e32 v1, v1, v146
	v_add_f32_e32 v1, v1, v141
	v_add_f32_e32 v1, v1, v140
	s_nop 0
	v_mfma_f32_32x32x16_bf16 v[16:31], v[132:135], v[10:13], v[16:31]
	v_add_f32_e32 v1, v1, v123
	v_add_f32_e32 v1, v1, v122
	v_add_f32_e32 v1, v1, v121
	v_add_f32_e32 v1, v1, v120
	s_waitcnt lgkmcnt(0)
	v_mfma_f32_32x32x16_bf16 v[32:47], v[142:145], v[10:13], v[32:47]
	v_add_f32_e32 v1, v1, v127
	v_add_f32_e32 v1, v1, v126
	v_add_f32_e32 v1, v1, v125
	v_add_f32_e32 v1, v1, v124
	s_setprio 2
	s_waitcnt lgkmcnt(0)
	s_barrier
	ds_read_b128 v[240:243], v201 offset:18432
	ds_read_b128 v[244:247], v201 offset:23040
	ds_read_b128 v[66:69], v201 offset:18464
	ds_read_b128 v[76:79], v201 offset:23072
	ds_read_b128 v[144:147], v201 offset:18496
	ds_read_b128 v[176:179], v201 offset:18528
	ds_read_b128 v[204:207], v201 offset:23104
	ds_read_b128 v[208:211], v201 offset:23136
	s_waitcnt lgkmcnt(6)
	v_mfma_f32_32x32x16_bf16 v[128:143], v[240:243], v[164:167], v[48:63]
	v_exp_f32_e32 v148, v96
	v_exp_f32_e32 v149, v97
	v_exp_f32_e32 v150, v98
	v_exp_f32_e32 v151, v99
	s_waitcnt lgkmcnt(5)
	v_mfma_f32_32x32x16_bf16 v[112:127], v[244:247], v[164:167], v[48:63]
	v_exp_f32_e32 v96, v100
	v_exp_f32_e32 v97, v101
	v_exp_f32_e32 v98, v102
	v_exp_f32_e32 v99, v103
	v_mfma_f32_32x32x16_bf16 v[128:143], v[66:69], v[160:163], v[128:143]
	v_exp_f32_e32 v100, v104
	v_exp_f32_e32 v101, v105
	v_exp_f32_e32 v102, v106
	v_exp_f32_e32 v103, v107
	s_waitcnt lgkmcnt(4)
	v_mfma_f32_32x32x16_bf16 v[112:127], v[76:79], v[160:163], v[112:127]
	v_exp_f32_e32 v71, v108
	v_exp_f32_e32 v72, v109
	v_exp_f32_e32 v73, v110
	v_exp_f32_e32 v74, v111
	s_waitcnt lgkmcnt(3)
	v_mfma_f32_32x32x16_bf16 v[128:143], v[144:147], v[156:159], v[128:143]
	v_exp_f32_e32 v75, v80
	v_exp_f32_e32 v76, v81
	v_exp_f32_e32 v77, v82
	v_exp_f32_e32 v78, v83
	s_waitcnt lgkmcnt(1)
	v_mfma_f32_32x32x16_bf16 v[112:127], v[204:207], v[156:159], v[112:127]
	v_exp_f32_e32 v14, v84
	v_exp_f32_e32 v15, v85
	v_exp_f32_e32 v65, v86
	v_exp_f32_e32 v66, v87
	v_mfma_f32_32x32x16_bf16 v[128:143], v[176:179], v[152:155], v[128:143]
	v_exp_f32_e32 v67, v88
	v_exp_f32_e32 v68, v89
	v_exp_f32_e32 v69, v90
	v_exp_f32_e32 v70, v91
	s_waitcnt lgkmcnt(0)
	v_mfma_f32_32x32x16_bf16 v[112:127], v[208:211], v[152:155], v[112:127]
	v_exp_f32_e32 v79, v92
	v_exp_f32_e32 v80, v93
	v_exp_f32_e32 v81, v94
	v_exp_f32_e32 v82, v95
	s_cmp_lt_u32 s45, 3
	s_cbranch_scc1 .LBB0_699
	s_add_i32 s23, s19, s45
	v_lshl_add_u32 v10, s23, 6, v184
	v_add_u32_e32 v11, 0xffffff7f, v10
	v_cmp_lt_u32_e32 vcc, s53, v11
	v_add_u32_e32 v11, 0xffffff9f, v10
	s_nop 7
	s_nop 3
	s_nop 0
	v_cndmask_b32_e32 v128, v233, v128, vcc
	v_cmp_lt_u32_e32 vcc, s53, v11
	v_add_u32_e32 v11, 0xffffff80, v10
	s_nop 0
	v_cndmask_b32_e32 v112, v233, v112, vcc
	v_cmp_lt_u32_e32 vcc, s53, v11
	v_add_u32_e32 v11, 0xffffffa0, v10
	s_nop 0
	v_cndmask_b32_e32 v129, v233, v129, vcc
	v_cmp_lt_u32_e32 vcc, s53, v11
	v_add_u32_e32 v11, 0xffffff81, v10
	s_nop 0
	v_cndmask_b32_e32 v113, v233, v113, vcc
	v_cmp_lt_u32_e32 vcc, s53, v11
	v_add_u32_e32 v11, 0xffffffa1, v10
	s_nop 0
	v_cndmask_b32_e32 v130, v233, v130, vcc
	v_cmp_lt_u32_e32 vcc, s53, v11
	v_add_u32_e32 v11, 0xffffff82, v10
	s_nop 0
	v_cndmask_b32_e32 v114, v233, v114, vcc
	v_cmp_lt_u32_e32 vcc, s53, v11
	v_add_u32_e32 v11, 0xffffffa2, v10
	s_nop 0
	v_cndmask_b32_e32 v131, v233, v131, vcc
	v_cmp_lt_u32_e32 vcc, s53, v11
	v_add_u32_e32 v11, 0xffffff87, v10
	s_nop 0
	v_cndmask_b32_e32 v115, v233, v115, vcc
	v_cmp_lt_u32_e32 vcc, s53, v11
	v_add_u32_e32 v11, 0xffffffa7, v10
	s_nop 0
	v_cndmask_b32_e32 v132, v233, v132, vcc
	v_cmp_lt_u32_e32 vcc, s53, v11
	v_add_u32_e32 v11, 0xffffff88, v10
	s_nop 0
	v_cndmask_b32_e32 v116, v233, v116, vcc
	v_cmp_lt_u32_e32 vcc, s53, v11
	v_add_u32_e32 v11, 0xffffffa8, v10
	s_nop 0
	v_cndmask_b32_e32 v133, v233, v133, vcc
	v_cmp_lt_u32_e32 vcc, s53, v11
	v_add_u32_e32 v11, 0xffffff89, v10
	s_nop 0
	v_cndmask_b32_e32 v117, v233, v117, vcc
	v_cmp_lt_u32_e32 vcc, s53, v11
	v_add_u32_e32 v11, 0xffffffa9, v10
	s_nop 0
	v_cndmask_b32_e32 v134, v233, v134, vcc
	v_cmp_lt_u32_e32 vcc, s53, v11
	v_add_u32_e32 v11, 0xffffff8a, v10
	s_nop 0
	v_cndmask_b32_e32 v118, v233, v118, vcc
	v_cmp_lt_u32_e32 vcc, s53, v11
	v_add_u32_e32 v11, 0xffffffaa, v10
	s_nop 0
	v_cndmask_b32_e32 v135, v233, v135, vcc
	v_cmp_lt_u32_e32 vcc, s53, v11
	v_add_u32_e32 v11, 0xffffff8f, v10
	s_nop 0
	v_cndmask_b32_e32 v119, v233, v119, vcc
	v_cmp_lt_u32_e32 vcc, s53, v11
	v_add_u32_e32 v11, 0xffffffaf, v10
	s_nop 0
	v_cndmask_b32_e32 v136, v233, v136, vcc
	v_cmp_lt_u32_e32 vcc, s53, v11
	v_add_u32_e32 v11, 0xffffff90, v10
	s_nop 0
	v_cndmask_b32_e32 v120, v233, v120, vcc
	v_cmp_lt_u32_e32 vcc, s53, v11
	v_add_u32_e32 v11, 0xffffffb0, v10
	s_nop 0
	v_cndmask_b32_e32 v137, v233, v137, vcc
	v_cmp_lt_u32_e32 vcc, s53, v11
	v_add_u32_e32 v11, 0xffffff91, v10
	s_nop 0
	v_cndmask_b32_e32 v121, v233, v121, vcc
	v_cmp_lt_u32_e32 vcc, s53, v11
	v_add_u32_e32 v11, 0xffffffb1, v10
	s_nop 0
	v_cndmask_b32_e32 v138, v233, v138, vcc
	v_cmp_lt_u32_e32 vcc, s53, v11
	v_add_u32_e32 v11, 0xffffff92, v10
	s_nop 0
	v_cndmask_b32_e32 v122, v233, v122, vcc
	v_cmp_lt_u32_e32 vcc, s53, v11
	v_add_u32_e32 v11, 0xffffffb2, v10
	s_nop 0
	v_cndmask_b32_e32 v139, v233, v139, vcc
	v_cmp_lt_u32_e32 vcc, s53, v11
	v_add_u32_e32 v11, 0xffffff97, v10
	s_nop 0
	v_cndmask_b32_e32 v123, v233, v123, vcc
	v_cmp_lt_u32_e32 vcc, s53, v11
	v_add_u32_e32 v11, 0xffffffb7, v10
	s_nop 0
	v_cndmask_b32_e32 v140, v233, v140, vcc
	v_cmp_lt_u32_e32 vcc, s53, v11
	v_add_u32_e32 v11, 0xffffff98, v10
	s_nop 0
	v_cndmask_b32_e32 v124, v233, v124, vcc
	v_cmp_lt_u32_e32 vcc, s53, v11
	v_add_u32_e32 v11, 0xffffffb8, v10
	s_nop 0
	v_cndmask_b32_e32 v141, v233, v141, vcc
	v_cmp_lt_u32_e32 vcc, s53, v11
	v_add_u32_e32 v11, 0xffffff99, v10
	s_nop 0
	v_cndmask_b32_e32 v125, v233, v125, vcc
	v_cmp_lt_u32_e32 vcc, s53, v11
	v_add_u32_e32 v11, 0xffffffb9, v10
	s_nop 0
	v_cndmask_b32_e32 v142, v233, v142, vcc
	v_cmp_lt_u32_e32 vcc, s53, v11
	v_add_u32_e32 v11, 0xffffff9a, v10
	v_add_u32_e32 v10, 0xffffffba, v10
	v_cndmask_b32_e32 v126, v233, v126, vcc
	v_cmp_lt_u32_e32 vcc, s53, v11
	s_nop 1
	v_cndmask_b32_e32 v143, v233, v143, vcc
	v_cmp_lt_u32_e32 vcc, s53, v10
	s_nop 1
	v_cndmask_b32_e32 v127, v233, v127, vcc
.LBB0_699:
	s_cmp_gt_i32 s34, 2
	s_cselect_b32 s23, -3, 2
	s_add_i32 s87, s45, 5
	s_add_i32 s23, s23, s34
	s_add_i32 s26, s87, s13
	s_mulk_i32 s23, 0x2400
	s_ashr_i32 s27, s26, 31
	v_add_u32_e32 v10, s23, v203
	s_lshl_b64 vcc, s[26:27], 13
	s_waitcnt vmcnt(3)
	ds_write_b128 v203, v[168:171]
	s_waitcnt vmcnt(2)
	ds_write_b128 v10, v[172:175] offset:36864
	v_lshl_add_u64 v[10:11], v[198:199], 0, vcc
	s_ashr_i32 s23, s22, 31
	global_load_dwordx4 v[144:147], v[10:11], off
	v_lshl_add_u64 v[10:11], s[22:23], 1, v[196:197]
	global_load_dwordx4 v[10:13], v[10:11], off
	v_add_u32_e32 v83, s2, v201
	ds_read_b128 v[240:243], v201 offset:27648
	ds_read_b128 v[244:247], v201 offset:32256
	ds_read_b128 v[84:87], v83 offset:41472
	ds_read_b128 v[88:91], v83 offset:36864
	ds_read_b128 v[92:95], v83 offset:36896
	ds_read_b128 v[104:107], v83 offset:41504
	ds_read_b128 v[108:111], v83 offset:36928
	ds_read_b128 v[170:173], v83 offset:41536
	ds_read_b128 v[174:177], v83 offset:36960
	ds_read_b128 v[178:181], v83 offset:41568
	s_setprio 1
	v_cvt_pk_bf16_f32 v204, v148, v149
	v_cvt_pk_bf16_f32 v205, v150, v151
	v_cvt_pk_bf16_f32 v206, v96, v97
	v_cvt_pk_bf16_f32 v207, v98, v99
	s_waitcnt lgkmcnt(6)
	s_nop 0
	v_mfma_f32_32x32x16_bf16 v[16:31], v[88:91], v[204:207], v[16:31]
	v_mov_b32_e32 v168, v148
	v_add_f32_e32 v168, v168, v149
	v_add_f32_e32 v168, v168, v150
	v_add_f32_e32 v168, v168, v151
	s_nop 0
	v_mfma_f32_32x32x16_bf16 v[32:47], v[84:87], v[204:207], v[32:47]
	v_cvt_pk_bf16_f32 v88, v100, v101
	v_cvt_pk_bf16_f32 v89, v102, v103
	v_cvt_pk_bf16_f32 v90, v71, v72
	v_cvt_pk_bf16_f32 v91, v73, v74
	v_add_f32_e32 v168, v168, v96
	v_add_f32_e32 v168, v168, v97
	v_add_f32_e32 v168, v168, v98
	v_add_f32_e32 v168, v168, v99
	s_waitcnt lgkmcnt(5)
	v_mfma_f32_32x32x16_bf16 v[16:31], v[92:95], v[88:91], v[16:31]
	v_add_f32_e32 v168, v168, v100
	v_add_f32_e32 v168, v168, v101
	v_add_f32_e32 v168, v168, v102
	v_add_f32_e32 v168, v168, v103
	s_waitcnt lgkmcnt(4)
	v_mfma_f32_32x32x16_bf16 v[32:47], v[104:107], v[88:91], v[32:47]
	v_cvt_pk_bf16_f32 v84, v75, v76
	v_cvt_pk_bf16_f32 v85, v77, v78
	v_cvt_pk_bf16_f32 v86, v14, v15
	v_cvt_pk_bf16_f32 v87, v65, v66
	v_add_f32_e32 v168, v168, v71
	v_add_f32_e32 v168, v168, v72
	v_add_f32_e32 v168, v168, v73
	v_add_f32_e32 v168, v168, v74
	s_waitcnt lgkmcnt(3)
	v_mfma_f32_32x32x16_bf16 v[16:31], v[108:111], v[84:87], v[16:31]
	v_add_f32_e32 v168, v168, v75
	v_add_f32_e32 v168, v168, v76
	v_add_f32_e32 v168, v168, v77
	v_add_f32_e32 v168, v168, v78
	s_waitcnt lgkmcnt(2)
	v_mfma_f32_32x32x16_bf16 v[32:47], v[170:173], v[84:87], v[32:47]
	v_cvt_pk_bf16_f32 v72, v67, v68
	v_cvt_pk_bf16_f32 v73, v69, v70
	v_cvt_pk_bf16_f32 v74, v79, v80
	v_cvt_pk_bf16_f32 v75, v81, v82
	v_add_f32_e32 v168, v168, v14
	v_add_f32_e32 v168, v168, v15
	v_add_f32_e32 v168, v168, v65
	v_add_f32_e32 v168, v168, v66
	s_waitcnt lgkmcnt(1)
	v_mfma_f32_32x32x16_bf16 v[16:31], v[174:177], v[72:75], v[16:31]
	v_add_f32_e32 v168, v168, v67
	v_add_f32_e32 v168, v168, v68
	v_add_f32_e32 v168, v168, v69
	v_add_f32_e32 v168, v168, v70
	s_waitcnt lgkmcnt(0)
	v_mfma_f32_32x32x16_bf16 v[32:47], v[178:181], v[72:75], v[32:47]
	v_add_f32_e32 v168, v168, v79
	v_add_f32_e32 v168, v168, v80
	v_add_f32_e32 v168, v168, v81
	v_add_f32_e32 v168, v168, v82
	s_setprio 0
	ds_read_b128 v[70:73], v201 offset:27680
	ds_read_b128 v[170:173], v201 offset:32288
	ds_read_b128 v[174:177], v201 offset:27712
	ds_read_b128 v[178:181], v201 offset:27744
	ds_read_b128 v[204:207], v201 offset:32320
	ds_read_b128 v[208:211], v201 offset:32352
	s_waitcnt lgkmcnt(6)
	v_mfma_f32_32x32x16_bf16 v[96:111], v[240:243], v[164:167], v[48:63]
	v_exp_f32_e32 v148, v128
	v_exp_f32_e32 v149, v129
	v_exp_f32_e32 v150, v130
	v_exp_f32_e32 v151, v131
	s_waitcnt lgkmcnt(5)
	v_mfma_f32_32x32x16_bf16 v[80:95], v[244:247], v[164:167], v[48:63]
	v_exp_f32_e32 v128, v132
	v_exp_f32_e32 v129, v133
	v_exp_f32_e32 v130, v134
	v_exp_f32_e32 v131, v135
	v_mfma_f32_32x32x16_bf16 v[96:111], v[70:73], v[160:163], v[96:111]
	v_exp_f32_e32 v132, v136
	v_exp_f32_e32 v133, v137
	v_exp_f32_e32 v134, v138
	v_exp_f32_e32 v135, v139
	s_waitcnt lgkmcnt(4)
	v_mfma_f32_32x32x16_bf16 v[80:95], v[170:173], v[160:163], v[80:95]
	v_exp_f32_e32 v71, v140
	v_exp_f32_e32 v72, v141
	v_exp_f32_e32 v73, v142
	v_exp_f32_e32 v74, v143
	s_waitcnt lgkmcnt(3)
	v_mfma_f32_32x32x16_bf16 v[96:111], v[174:177], v[156:159], v[96:111]
	v_exp_f32_e32 v75, v112
	v_exp_f32_e32 v76, v113
	v_exp_f32_e32 v77, v114
	v_exp_f32_e32 v78, v115
	s_waitcnt lgkmcnt(1)
	v_mfma_f32_32x32x16_bf16 v[80:95], v[204:207], v[156:159], v[80:95]
	v_exp_f32_e32 v14, v116
	v_exp_f32_e32 v15, v117
	v_exp_f32_e32 v65, v118
	v_exp_f32_e32 v66, v119
	v_mfma_f32_32x32x16_bf16 v[96:111], v[178:181], v[152:155], v[96:111]
	v_exp_f32_e32 v67, v120
	v_exp_f32_e32 v68, v121
	v_exp_f32_e32 v69, v122
	v_exp_f32_e32 v70, v123
	s_waitcnt lgkmcnt(0)
	v_mfma_f32_32x32x16_bf16 v[80:95], v[208:211], v[152:155], v[80:95]
	v_exp_f32_e32 v79, v124
	v_exp_f32_e32 v112, v125
	v_exp_f32_e32 v113, v126
	v_exp_f32_e32 v114, v127
	s_cmp_lt_u32 s45, 2
	s_cbranch_scc1 .LBB0_701
	s_add_i32 s2, s22, 0x80
	v_add_u32_e32 v115, s2, v184
	v_add_u32_e32 v116, 0xffffff7f, v115
	v_cmp_lt_u32_e32 vcc, s53, v116
	v_add_u32_e32 v116, 0xffffff9f, v115
	s_nop 7
	s_nop 3
	s_nop 0
	v_cndmask_b32_e32 v96, v233, v96, vcc
	v_cmp_lt_u32_e32 vcc, s53, v116
	v_add_u32_e32 v116, 0xffffff80, v115
	s_nop 0
	v_cndmask_b32_e32 v80, v233, v80, vcc
	v_cmp_lt_u32_e32 vcc, s53, v116
	v_add_u32_e32 v116, 0xffffffa0, v115
	s_nop 0
	v_cndmask_b32_e32 v97, v233, v97, vcc
	v_cmp_lt_u32_e32 vcc, s53, v116
	v_add_u32_e32 v116, 0xffffff81, v115
	s_nop 0
	v_cndmask_b32_e32 v81, v233, v81, vcc
	v_cmp_lt_u32_e32 vcc, s53, v116
	v_add_u32_e32 v116, 0xffffffa1, v115
	s_nop 0
	v_cndmask_b32_e32 v98, v233, v98, vcc
	v_cmp_lt_u32_e32 vcc, s53, v116
	v_add_u32_e32 v116, 0xffffff82, v115
	s_nop 0
	v_cndmask_b32_e32 v82, v233, v82, vcc
	v_cmp_lt_u32_e32 vcc, s53, v116
	v_add_u32_e32 v116, 0xffffffa2, v115
	s_nop 0
	v_cndmask_b32_e32 v99, v233, v99, vcc
	v_cmp_lt_u32_e32 vcc, s53, v116
	v_add_u32_e32 v116, 0xffffff87, v115
	s_nop 0
	v_cndmask_b32_e32 v83, v233, v83, vcc
	v_cmp_lt_u32_e32 vcc, s53, v116
	v_add_u32_e32 v116, 0xffffffa7, v115
	s_nop 0
	v_cndmask_b32_e32 v100, v233, v100, vcc
	v_cmp_lt_u32_e32 vcc, s53, v116
	v_add_u32_e32 v116, 0xffffff88, v115
	s_nop 0
	v_cndmask_b32_e32 v84, v233, v84, vcc
	v_cmp_lt_u32_e32 vcc, s53, v116
	v_add_u32_e32 v116, 0xffffffa8, v115
	s_nop 0
	v_cndmask_b32_e32 v101, v233, v101, vcc
	v_cmp_lt_u32_e32 vcc, s53, v116
	v_add_u32_e32 v116, 0xffffff89, v115
	s_nop 0
	v_cndmask_b32_e32 v85, v233, v85, vcc
	v_cmp_lt_u32_e32 vcc, s53, v116
	v_add_u32_e32 v116, 0xffffffa9, v115
	s_nop 0
	v_cndmask_b32_e32 v102, v233, v102, vcc
	v_cmp_lt_u32_e32 vcc, s53, v116
	v_add_u32_e32 v116, 0xffffff8a, v115
	s_nop 0
	v_cndmask_b32_e32 v86, v233, v86, vcc
	v_cmp_lt_u32_e32 vcc, s53, v116
	v_add_u32_e32 v116, 0xffffffaa, v115
	s_nop 0
	v_cndmask_b32_e32 v103, v233, v103, vcc
	v_cmp_lt_u32_e32 vcc, s53, v116
	v_add_u32_e32 v116, 0xffffff8f, v115
	s_nop 0
	v_cndmask_b32_e32 v87, v233, v87, vcc
	v_cmp_lt_u32_e32 vcc, s53, v116
	v_add_u32_e32 v116, 0xffffffaf, v115
	s_nop 0
	v_cndmask_b32_e32 v104, v233, v104, vcc
	v_cmp_lt_u32_e32 vcc, s53, v116
	v_add_u32_e32 v116, 0xffffff90, v115
	s_nop 0
	v_cndmask_b32_e32 v88, v233, v88, vcc
	v_cmp_lt_u32_e32 vcc, s53, v116
	v_add_u32_e32 v116, 0xffffffb0, v115
	s_nop 0
	v_cndmask_b32_e32 v105, v233, v105, vcc
	v_cmp_lt_u32_e32 vcc, s53, v116
	v_add_u32_e32 v116, 0xffffff91, v115
	s_nop 0
	v_cndmask_b32_e32 v89, v233, v89, vcc
	v_cmp_lt_u32_e32 vcc, s53, v116
	v_add_u32_e32 v116, 0xffffffb1, v115
	s_nop 0
	v_cndmask_b32_e32 v106, v233, v106, vcc
	v_cmp_lt_u32_e32 vcc, s53, v116
	v_add_u32_e32 v116, 0xffffff92, v115
	s_nop 0
	v_cndmask_b32_e32 v90, v233, v90, vcc
	v_cmp_lt_u32_e32 vcc, s53, v116
	v_add_u32_e32 v116, 0xffffffb2, v115
	s_nop 0
	v_cndmask_b32_e32 v107, v233, v107, vcc
	v_cmp_lt_u32_e32 vcc, s53, v116
	v_add_u32_e32 v116, 0xffffff97, v115
	s_nop 0
	v_cndmask_b32_e32 v91, v233, v91, vcc
	v_cmp_lt_u32_e32 vcc, s53, v116
	v_add_u32_e32 v116, 0xffffffb7, v115
	s_nop 0
	v_cndmask_b32_e32 v108, v233, v108, vcc
	v_cmp_lt_u32_e32 vcc, s53, v116
	v_add_u32_e32 v116, 0xffffff98, v115
	s_nop 0
	v_cndmask_b32_e32 v92, v233, v92, vcc
	v_cmp_lt_u32_e32 vcc, s53, v116
	v_add_u32_e32 v116, 0xffffffb8, v115
	s_nop 0
	v_cndmask_b32_e32 v109, v233, v109, vcc
	v_cmp_lt_u32_e32 vcc, s53, v116
	v_add_u32_e32 v116, 0xffffff99, v115
	s_nop 0
	v_cndmask_b32_e32 v93, v233, v93, vcc
	v_cmp_lt_u32_e32 vcc, s53, v116
	v_add_u32_e32 v116, 0xffffffb9, v115
	s_nop 0
	v_cndmask_b32_e32 v110, v233, v110, vcc
	v_cmp_lt_u32_e32 vcc, s53, v116
	v_add_u32_e32 v116, 0xffffff9a, v115
	v_add_u32_e32 v115, 0xffffffba, v115
	v_cndmask_b32_e32 v94, v233, v94, vcc
	v_cmp_lt_u32_e32 vcc, s53, v116
	s_nop 1
	v_cndmask_b32_e32 v111, v233, v111, vcc
	v_cmp_lt_u32_e32 vcc, s53, v115
	s_nop 1
	v_cndmask_b32_e32 v95, v233, v95, vcc
.LBB0_701:
	s_add_i32 s2, s34, 1
	s_cmp_lg_u32 s34, 4
	s_cselect_b32 s2, s2, 0
	s_cmp_gt_i32 s2, 2
	s_cselect_b32 s23, -3, 2
	s_add_i32 s23, s23, s2
	s_mulk_i32 s23, 0x2400
	s_waitcnt vmcnt(3)
	ds_write_b128 v203, v[6:9] offset:9216
	v_add_u32_e32 v6, s23, v203
	s_add_i32 s23, s2, 1
	s_cmp_lg_u32 s2, 4
	s_cselect_b32 s23, s23, 0
	s_add_i32 s2, s45, 6
	s_add_i32 s34, s2, s13
	s_ashr_i32 s35, s34, 31
	s_lshl_b32 s26, s26, 6
	s_lshl_b64 vcc, s[34:35], 13
	s_ashr_i32 s27, s26, 31
	s_waitcnt vmcnt(2)
	ds_write_b128 v6, v[2:5] offset:36864
	v_lshl_add_u64 v[2:3], v[198:199], 0, vcc
	v_lshl_add_u64 v[6:7], s[26:27], 1, v[196:197]
	global_load_dwordx4 v[2:5], v[2:3], off
	s_mul_i32 s25, s23, 0x2400
	global_load_dwordx4 v[6:9], v[6:7], off
	s_add_i32 s26, s25, 0xffffdc00
	s_cmp_lg_u32 s23, 0
	s_cselect_b32 s26, s26, 0x9000
	v_add_f32_e32 v1, v64, v1
	v_add_u32_e32 v64, s26, v201
	v_add_f32_e32 v1, v1, v168
	ds_read_b128 v[116:119], v64 offset:41472
	ds_read_b128 v[120:123], v64 offset:36864
	ds_read_b128 v[124:127], v64 offset:36896
	ds_read_b128 v[136:139], v64 offset:41504
	ds_read_b128 v[140:143], v64 offset:36928
	ds_read_b128 v[168:171], v64 offset:41536
	ds_read_b128 v[172:175], v64 offset:36960
	ds_read_b128 v[176:179], v64 offset:41568
	s_setprio 3
	v_cvt_pk_bf16_f32 v204, v148, v149
	v_cvt_pk_bf16_f32 v205, v150, v151
	v_cvt_pk_bf16_f32 v206, v128, v129
	v_cvt_pk_bf16_f32 v207, v130, v131
	s_waitcnt lgkmcnt(6)
	s_nop 0
	v_mfma_f32_32x32x16_bf16 v[16:31], v[120:123], v[204:207], v[16:31]
	v_mov_b32_e32 v180, v148
	v_add_f32_e32 v180, v180, v149
	v_add_f32_e32 v180, v180, v150
	v_add_f32_e32 v180, v180, v151
	s_nop 0
	v_mfma_f32_32x32x16_bf16 v[32:47], v[116:119], v[204:207], v[32:47]
	v_cvt_pk_bf16_f32 v120, v132, v133
	v_cvt_pk_bf16_f32 v121, v134, v135
	v_cvt_pk_bf16_f32 v122, v71, v72
	v_cvt_pk_bf16_f32 v123, v73, v74
	v_add_f32_e32 v180, v180, v128
	v_add_f32_e32 v180, v180, v129
	v_add_f32_e32 v180, v180, v130
	v_add_f32_e32 v180, v180, v131
	s_waitcnt lgkmcnt(5)
	v_mfma_f32_32x32x16_bf16 v[16:31], v[124:127], v[120:123], v[16:31]
	v_add_f32_e32 v180, v180, v132
	v_add_f32_e32 v180, v180, v133
	v_add_f32_e32 v180, v180, v134
	v_add_f32_e32 v180, v180, v135
	s_waitcnt lgkmcnt(4)
	v_mfma_f32_32x32x16_bf16 v[32:47], v[136:139], v[120:123], v[32:47]
	v_cvt_pk_bf16_f32 v116, v75, v76
	v_cvt_pk_bf16_f32 v117, v77, v78
	v_cvt_pk_bf16_f32 v118, v14, v15
	v_cvt_pk_bf16_f32 v119, v65, v66
	v_add_f32_e32 v180, v180, v71
	v_add_f32_e32 v180, v180, v72
	v_add_f32_e32 v180, v180, v73
	v_add_f32_e32 v180, v180, v74
	s_waitcnt lgkmcnt(3)
	v_mfma_f32_32x32x16_bf16 v[16:31], v[140:143], v[116:119], v[16:31]
	v_add_f32_e32 v180, v180, v75
	v_add_f32_e32 v180, v180, v76
	v_add_f32_e32 v180, v180, v77
	v_add_f32_e32 v180, v180, v78
	s_waitcnt lgkmcnt(2)
	v_mfma_f32_32x32x16_bf16 v[32:47], v[168:171], v[116:119], v[32:47]
	v_cvt_pk_bf16_f32 v72, v67, v68
	v_cvt_pk_bf16_f32 v73, v69, v70
	v_cvt_pk_bf16_f32 v74, v79, v112
	v_cvt_pk_bf16_f32 v75, v113, v114
	v_add_f32_e32 v180, v180, v14
	v_add_f32_e32 v180, v180, v15
	v_add_f32_e32 v180, v180, v65
	v_add_f32_e32 v180, v180, v66
	s_waitcnt lgkmcnt(1)
	v_mfma_f32_32x32x16_bf16 v[16:31], v[172:175], v[72:75], v[16:31]
	v_add_f32_e32 v180, v180, v67
	v_add_f32_e32 v180, v180, v68
	v_add_f32_e32 v180, v180, v69
	v_add_f32_e32 v180, v180, v70
	s_waitcnt lgkmcnt(0)
	v_mfma_f32_32x32x16_bf16 v[32:47], v[176:179], v[72:75], v[32:47]
	v_add_f32_e32 v180, v180, v79
	v_add_f32_e32 v180, v180, v112
	v_add_f32_e32 v180, v180, v113
	v_add_f32_e32 v180, v180, v114
	s_setprio 2
	s_waitcnt lgkmcnt(0)
	s_barrier
	ds_read_b128 v[240:243], v201
	ds_read_b128 v[244:247], v201 offset:4608
	ds_read_b128 v[128:131], v201 offset:32
	ds_read_b128 v[136:139], v201 offset:4640
	ds_read_b128 v[172:175], v201 offset:64
	ds_read_b128 v[176:179], v201 offset:96
	ds_read_b128 v[204:207], v201 offset:4672
	ds_read_b128 v[208:211], v201 offset:4704
	s_waitcnt lgkmcnt(6)
	v_mfma_f32_32x32x16_bf16 v[64:79], v[240:243], v[164:167], v[48:63]
	v_exp_f32_e32 v168, v96
	v_exp_f32_e32 v169, v97
	v_exp_f32_e32 v170, v98
	v_exp_f32_e32 v171, v99
	s_waitcnt lgkmcnt(5)
	v_mfma_f32_32x32x16_bf16 v[112:127], v[244:247], v[164:167], v[48:63]
	v_exp_f32_e32 v140, v100
	v_exp_f32_e32 v141, v101
	v_exp_f32_e32 v142, v102
	v_exp_f32_e32 v143, v103
	v_mfma_f32_32x32x16_bf16 v[64:79], v[128:131], v[160:163], v[64:79]
	v_exp_f32_e32 v148, v104
	v_exp_f32_e32 v149, v105
	v_exp_f32_e32 v150, v106
	v_exp_f32_e32 v151, v107
	s_waitcnt lgkmcnt(4)
	v_mfma_f32_32x32x16_bf16 v[112:127], v[136:139], v[160:163], v[112:127]
	v_exp_f32_e32 v132, v108
	v_exp_f32_e32 v133, v109
	v_exp_f32_e32 v134, v110
	v_exp_f32_e32 v135, v111
	s_waitcnt lgkmcnt(3)
	v_mfma_f32_32x32x16_bf16 v[64:79], v[172:175], v[156:159], v[64:79]
	v_exp_f32_e32 v136, v80
	v_exp_f32_e32 v137, v81
	v_exp_f32_e32 v138, v82
	v_exp_f32_e32 v139, v83
	s_waitcnt lgkmcnt(1)
	v_mfma_f32_32x32x16_bf16 v[112:127], v[204:207], v[156:159], v[112:127]
	v_exp_f32_e32 v128, v84
	v_exp_f32_e32 v129, v85
	v_exp_f32_e32 v130, v86
	v_exp_f32_e32 v131, v87
	v_mfma_f32_32x32x16_bf16 v[64:79], v[176:179], v[152:155], v[64:79]
	v_exp_f32_e32 v84, v88
	v_exp_f32_e32 v85, v89
	v_exp_f32_e32 v86, v90
	v_exp_f32_e32 v87, v91
	s_waitcnt lgkmcnt(0)
	v_mfma_f32_32x32x16_bf16 v[112:127], v[208:211], v[152:155], v[112:127]
	v_exp_f32_e32 v88, v92
	v_exp_f32_e32 v89, v93
	v_exp_f32_e32 v90, v94
	v_exp_f32_e32 v91, v95
	v_sub_u32_e32 v14, s24, v202
	v_add_u32_e32 v14, v14, v183
	v_add_u32_e32 v15, 0xffffff7f, v14
	v_cmp_lt_u32_e32 vcc, s53, v15
	v_add_u32_e32 v15, 0xffffff9f, v14
	s_cmp_gt_i32 s23, 2
	v_cndmask_b32_e32 v80, v233, v64, vcc
	v_cmp_lt_u32_e32 vcc, s53, v15
	v_add_u32_e32 v64, 0xffffff80, v14
	s_cselect_b32 s24, -3, 2
	v_cndmask_b32_e32 v15, v233, v112, vcc
	v_cmp_lt_u32_e32 vcc, s53, v64
	v_add_u32_e32 v64, 0xffffffa0, v14
	s_add_i32 s24, s24, s23
	v_cndmask_b32_e32 v81, v233, v65, vcc
	v_cmp_lt_u32_e32 vcc, s53, v64
	v_add_u32_e32 v64, 0xffffff81, v14
	s_mulk_i32 s24, 0x2400
	v_cndmask_b32_e32 v100, v233, v113, vcc
	v_cmp_lt_u32_e32 vcc, s53, v64
	v_add_u32_e32 v64, 0xffffffa1, v14
	s_add_i32 s27, s77, s18
	v_cndmask_b32_e32 v82, v233, v66, vcc
	v_cmp_lt_u32_e32 vcc, s53, v64
	v_add_u32_e32 v64, 0xffffff82, v14
	s_nop 7
	s_nop 3
	s_waitcnt vmcnt(3)
	ds_write_b128 v203, v[144:147] offset:18432
	v_cndmask_b32_e32 v101, v233, v114, vcc
	v_cmp_lt_u32_e32 vcc, s53, v64
	v_add_u32_e32 v64, 0xffffffa2, v14
	s_lshl_b32 s34, s34, 6
	v_cndmask_b32_e32 v83, v233, v67, vcc
	v_cmp_lt_u32_e32 vcc, s53, v64
	v_add_u32_e32 v64, 0xffffff87, v14
	s_ashr_i32 s35, s34, 31
	v_cndmask_b32_e32 v102, v233, v115, vcc
	v_cmp_lt_u32_e32 vcc, s53, v64
	v_add_u32_e32 v64, 0xffffffa7, v14
	v_add_f32_e32 v1, v1, v180
	v_cndmask_b32_e32 v105, v233, v68, vcc
	v_cmp_lt_u32_e32 vcc, s53, v64
	v_add_u32_e32 v64, 0xffffff88, v14
	v_add_u32_e32 v68, 0xffffff9a, v14
	v_cndmask_b32_e32 v103, v233, v116, vcc
	v_cmp_lt_u32_e32 vcc, s53, v64
	v_add_u32_e32 v64, 0xffffffa8, v14
	s_add_i32 s26, s23, 1
	v_cndmask_b32_e32 v107, v233, v69, vcc
	v_cmp_lt_u32_e32 vcc, s53, v64
	v_add_u32_e32 v64, 0xffffff89, v14
	s_nop 0
	v_cndmask_b32_e32 v104, v233, v117, vcc
	v_cmp_lt_u32_e32 vcc, s53, v64
	v_add_u32_e32 v64, 0xffffffa9, v14
	s_nop 0
	v_cndmask_b32_e32 v109, v233, v70, vcc
	v_cmp_lt_u32_e32 vcc, s53, v64
	v_add_u32_e32 v64, 0xffffff8a, v14
	s_nop 0
	v_cndmask_b32_e32 v106, v233, v118, vcc
	v_cmp_lt_u32_e32 vcc, s53, v64
	v_add_u32_e32 v64, 0xffffffaa, v14
	s_nop 0
	v_cndmask_b32_e32 v111, v233, v71, vcc
	v_cmp_lt_u32_e32 vcc, s53, v64
	v_add_u32_e32 v64, 0xffffff8f, v14
	s_nop 0
	v_cndmask_b32_e32 v108, v233, v119, vcc
	v_cmp_lt_u32_e32 vcc, s53, v64
	v_add_u32_e32 v64, 0xffffffaf, v14
	s_nop 0
	v_cndmask_b32_e32 v113, v233, v72, vcc
	v_cmp_lt_u32_e32 vcc, s53, v64
	v_add_u32_e32 v64, 0xffffff90, v14
	s_nop 0
	v_cndmask_b32_e32 v110, v233, v120, vcc
	v_cmp_lt_u32_e32 vcc, s53, v64
	v_add_u32_e32 v64, 0xffffffb0, v14
	s_nop 0
	v_cndmask_b32_e32 v115, v233, v73, vcc
	v_cmp_lt_u32_e32 vcc, s53, v64
	v_add_u32_e32 v64, 0xffffff91, v14
	s_nop 0
	v_cndmask_b32_e32 v112, v233, v121, vcc
	v_cmp_lt_u32_e32 vcc, s53, v64
	v_add_u32_e32 v64, 0xffffffb1, v14
	s_nop 0
	v_cndmask_b32_e32 v117, v233, v74, vcc
	v_cmp_lt_u32_e32 vcc, s53, v64
	v_add_u32_e32 v64, 0xffffff92, v14
	s_nop 0
	v_cndmask_b32_e32 v114, v233, v122, vcc
	v_cmp_lt_u32_e32 vcc, s53, v64
	v_add_u32_e32 v64, 0xffffffb2, v14
	s_nop 0
	v_cndmask_b32_e32 v119, v233, v75, vcc
	v_cmp_lt_u32_e32 vcc, s53, v64
	v_add_u32_e32 v64, 0xffffff97, v14
	s_nop 0
	v_cndmask_b32_e32 v116, v233, v123, vcc
	v_cmp_lt_u32_e32 vcc, s53, v64
	v_add_u32_e32 v64, 0xffffffb7, v14
	s_nop 0
	v_cndmask_b32_e32 v121, v233, v76, vcc
	v_cmp_lt_u32_e32 vcc, s53, v64
	v_add_u32_e32 v64, 0xffffff98, v14
	s_nop 0
	v_cndmask_b32_e32 v118, v233, v124, vcc
	v_cmp_lt_u32_e32 vcc, s53, v64
	v_add_u32_e32 v64, 0xffffffb8, v14
	s_nop 0
	v_cndmask_b32_e32 v123, v233, v77, vcc
	v_cmp_lt_u32_e32 vcc, s53, v64
	v_add_u32_e32 v64, 0xffffff99, v14
	s_nop 0
	v_cndmask_b32_e32 v120, v233, v125, vcc
	v_cmp_lt_u32_e32 vcc, s53, v64
	v_add_u32_e32 v64, 0xffffffb9, v14
	v_add_u32_e32 v14, 0xffffffba, v14
	v_cndmask_b32_e32 v125, v233, v78, vcc
	v_cmp_lt_u32_e32 vcc, s53, v64
	s_nop 1
	v_cndmask_b32_e32 v122, v233, v126, vcc
	v_cmp_lt_u32_e32 vcc, s53, v14
	v_add_u32_e32 v14, s24, v203
	s_add_i32 s24, s27, -4
	s_waitcnt vmcnt(2)
	ds_write_b128 v14, v[10:13] offset:36864
	v_add_u32_e32 v14, s25, v201
	s_ashr_i32 s25, s24, 31
	v_cndmask_b32_e32 v124, v233, v127, vcc
	s_lshl_b64 vcc, s[24:25], 13
	v_lshl_add_u64 v[10:11], v[198:199], 0, vcc
	global_load_dwordx4 v[96:99], v[10:11], off
	v_lshl_add_u64 v[10:11], s[34:35], 1, v[196:197]
	global_load_dwordx4 v[10:13], v[10:11], off
	ds_read_b128 v[240:243], v201 offset:9216
	ds_read_b128 v[244:247], v201 offset:13824
	ds_read_b128 v[64:67], v14 offset:41472
	ds_read_b128 v[70:73], v14 offset:36864
	ds_read_b128 v[74:77], v14 offset:36896
	ds_read_b128 v[92:95], v14 offset:41504
	ds_read_b128 v[144:147], v14 offset:36928
	ds_read_b128 v[172:175], v14 offset:41536
	ds_read_b128 v[176:179], v14 offset:36960
	ds_read_b128 v[204:207], v14 offset:41568
	s_setprio 1
	v_cvt_pk_bf16_f32 v208, v168, v169
	v_cvt_pk_bf16_f32 v209, v170, v171
	v_cvt_pk_bf16_f32 v210, v140, v141
	v_cvt_pk_bf16_f32 v211, v142, v143
	s_waitcnt lgkmcnt(6)
	s_nop 0
	v_mfma_f32_32x32x16_bf16 v[16:31], v[70:73], v[208:211], v[16:31]
	v_mov_b32_e32 v14, v168
	v_add_f32_e32 v14, v14, v169
	v_add_f32_e32 v14, v14, v170
	v_add_f32_e32 v14, v14, v171
	s_nop 0
	v_mfma_f32_32x32x16_bf16 v[32:47], v[64:67], v[208:211], v[32:47]
	v_cvt_pk_bf16_f32 v70, v148, v149
	v_cvt_pk_bf16_f32 v71, v150, v151
	v_cvt_pk_bf16_f32 v72, v132, v133
	v_cvt_pk_bf16_f32 v73, v134, v135
	v_add_f32_e32 v14, v14, v140
	v_add_f32_e32 v14, v14, v141
	v_add_f32_e32 v14, v14, v142
	v_add_f32_e32 v14, v14, v143
	s_waitcnt lgkmcnt(5)
	v_mfma_f32_32x32x16_bf16 v[16:31], v[74:77], v[70:73], v[16:31]
	v_add_f32_e32 v14, v14, v148
	v_add_f32_e32 v14, v14, v149
	v_add_f32_e32 v14, v14, v150
	v_add_f32_e32 v14, v14, v151
	s_waitcnt lgkmcnt(4)
	v_mfma_f32_32x32x16_bf16 v[32:47], v[92:95], v[70:73], v[32:47]
	v_cvt_pk_bf16_f32 v64, v136, v137
	v_cvt_pk_bf16_f32 v65, v138, v139
	v_cvt_pk_bf16_f32 v66, v128, v129
	v_cvt_pk_bf16_f32 v67, v130, v131
	v_add_f32_e32 v14, v14, v132
	v_add_f32_e32 v14, v14, v133
	v_add_f32_e32 v14, v14, v134
	v_add_f32_e32 v14, v14, v135
	s_waitcnt lgkmcnt(3)
	v_mfma_f32_32x32x16_bf16 v[16:31], v[144:147], v[64:67], v[16:31]
	v_add_f32_e32 v14, v14, v136
	v_add_f32_e32 v14, v14, v137
	v_add_f32_e32 v14, v14, v138
	v_add_f32_e32 v14, v14, v139
	s_waitcnt lgkmcnt(2)
	v_mfma_f32_32x32x16_bf16 v[32:47], v[172:175], v[64:67], v[32:47]
	v_cvt_pk_bf16_f32 v70, v84, v85
	v_cvt_pk_bf16_f32 v71, v86, v87
	v_cvt_pk_bf16_f32 v72, v88, v89
	v_cvt_pk_bf16_f32 v73, v90, v91
	v_add_f32_e32 v14, v14, v128
	v_add_f32_e32 v14, v14, v129
	v_add_f32_e32 v14, v14, v130
	v_add_f32_e32 v14, v14, v131
	s_waitcnt lgkmcnt(1)
	v_mfma_f32_32x32x16_bf16 v[16:31], v[176:179], v[70:73], v[16:31]
	v_add_f32_e32 v14, v14, v84
	v_add_f32_e32 v14, v14, v85
	v_add_f32_e32 v14, v14, v86
	v_add_f32_e32 v14, v14, v87
	s_waitcnt lgkmcnt(0)
	v_mfma_f32_32x32x16_bf16 v[32:47], v[204:207], v[70:73], v[32:47]
	v_add_f32_e32 v14, v14, v88
	v_add_f32_e32 v14, v14, v89
	v_add_f32_e32 v14, v14, v90
	v_add_f32_e32 v14, v14, v91
	s_setprio 0
	ds_read_b128 v[130:133], v201 offset:9248
	ds_read_b128 v[168:171], v201 offset:13856
	ds_read_b128 v[172:175], v201 offset:9280
	ds_read_b128 v[176:179], v201 offset:13888
	ds_read_b128 v[204:207], v201 offset:9312
	ds_read_b128 v[208:211], v201 offset:13920
	v_cmp_lt_u32_e32 vcc, s53, v68
	s_cmp_lg_u32 s23, 4
	s_cselect_b32 s23, s26, 0
	v_cndmask_b32_e32 v135, v233, v79, vcc
	s_waitcnt lgkmcnt(6)
	v_mfma_f32_32x32x16_bf16 v[64:79], v[240:243], v[164:167], v[48:63]
	v_exp_f32_e32 v148, v80
	v_exp_f32_e32 v149, v81
	v_exp_f32_e32 v150, v82
	v_exp_f32_e32 v151, v83
	v_mfma_f32_32x32x16_bf16 v[80:95], v[244:247], v[164:167], v[48:63]
	v_exp_f32_e32 v142, v105
	v_exp_f32_e32 v143, v107
	v_exp_f32_e32 v144, v109
	v_exp_f32_e32 v147, v111
	s_waitcnt lgkmcnt(5)
	v_mfma_f32_32x32x16_bf16 v[64:79], v[130:133], v[160:163], v[64:79]
	v_exp_f32_e32 v136, v113
	v_exp_f32_e32 v137, v115
	v_exp_f32_e32 v138, v117
	v_exp_f32_e32 v140, v119
	s_waitcnt lgkmcnt(4)
	v_mfma_f32_32x32x16_bf16 v[80:95], v[168:171], v[160:163], v[80:95]
	v_exp_f32_e32 v130, v121
	v_exp_f32_e32 v131, v123
	v_exp_f32_e32 v133, v125
	v_exp_f32_e32 v134, v135
	s_waitcnt lgkmcnt(3)
	v_mfma_f32_32x32x16_bf16 v[64:79], v[172:175], v[156:159], v[64:79]
	v_exp_f32_e32 v125, v15
	v_exp_f32_e32 v126, v100
	v_exp_f32_e32 v127, v101
	v_exp_f32_e32 v128, v102
	s_waitcnt lgkmcnt(2)
	v_mfma_f32_32x32x16_bf16 v[80:95], v[176:179], v[156:159], v[80:95]
	v_exp_f32_e32 v117, v103
	v_exp_f32_e32 v119, v104
	v_exp_f32_e32 v121, v106
	v_exp_f32_e32 v123, v108
	s_waitcnt lgkmcnt(1)
	v_mfma_f32_32x32x16_bf16 v[64:79], v[204:207], v[152:155], v[64:79]
	v_exp_f32_e32 v108, v110
	v_exp_f32_e32 v109, v112
	v_exp_f32_e32 v111, v114
	v_exp_f32_e32 v113, v116
	s_waitcnt lgkmcnt(0)
	v_mfma_f32_32x32x16_bf16 v[80:95], v[208:211], v[152:155], v[80:95]
	v_exp_f32_e32 v110, v118
	v_exp_f32_e32 v112, v120
	v_exp_f32_e32 v114, v122
	v_exp_f32_e32 v115, v124
	s_cmp_gt_i32 s23, 2
	v_sub_u32_e32 v15, s22, v202
	s_cselect_b32 s22, -3, 2
	s_add_i32 s22, s22, s23
	s_mulk_i32 s22, 0x2400
	s_nop 7
	s_nop 3
	s_waitcnt vmcnt(3)
	ds_write_b128 v203, v[2:5] offset:27648
	v_add_u32_e32 v2, s22, v203
	s_add_i32 s22, s23, 1
	s_cmp_lg_u32 s23, 4
	s_cselect_b32 s25, s22, 0
	s_add_i32 s26, s45, 8
	s_min_i32 s22, s26, s92
	s_cmp_gt_i32 s22, 3
	s_cselect_b32 s23, s13, 0
	s_add_i32 s34, s23, s22
	s_ashr_i32 s35, s34, 31
	s_lshl_b64 s[22:23], s[34:35], 13
	s_waitcnt vmcnt(2)
	ds_write_b128 v2, v[6:9] offset:36864
	v_lshl_add_u64 v[2:3], v[198:199], 0, s[22:23]
	s_lshl_b32 s22, s24, 6
	s_ashr_i32 s23, s22, 31
	v_lshl_add_u64 v[6:7], s[22:23], 1, v[196:197]
	global_load_dwordx4 v[2:5], v[2:3], off
	v_add_u32_e32 v168, v15, v183
	global_load_dwordx4 v[6:9], v[6:7], off
	v_add_u32_e32 v15, 0xffffff7f, v168
	v_cmp_lt_u32_e32 vcc, s53, v15
	v_add_u32_e32 v15, 0xffffff9f, v168
	s_mul_i32 s22, s25, 0x2400
	v_cndmask_b32_e32 v101, v233, v64, vcc
	v_cmp_lt_u32_e32 vcc, s53, v15
	v_add_u32_e32 v64, 0xffffff80, v168
	s_add_i32 s23, s22, 0xffffdc00
	v_cndmask_b32_e32 v15, v233, v80, vcc
	v_cmp_lt_u32_e32 vcc, s53, v64
	v_add_u32_e32 v64, 0xffffffa0, v168
	s_cmp_lg_u32 s25, 0
	v_cndmask_b32_e32 v80, v233, v65, vcc
	v_cmp_lt_u32_e32 vcc, s53, v64
	v_add_u32_e32 v64, 0xffffff81, v168
	v_add_u32_e32 v65, 0xffffffba, v168
	v_cndmask_b32_e32 v100, v233, v81, vcc
	v_cmp_lt_u32_e32 vcc, s53, v64
	v_add_u32_e32 v64, 0xffffffa1, v168
	s_cselect_b32 s23, s23, 0x9000
	v_cndmask_b32_e32 v81, v233, v66, vcc
	v_cmp_lt_u32_e32 vcc, s53, v64
	v_add_u32_e32 v64, 0xffffff82, v168
	s_nop 0
	v_cndmask_b32_e32 v102, v233, v82, vcc
	v_cmp_lt_u32_e32 vcc, s53, v64
	v_add_u32_e32 v64, 0xffffffa2, v168
	s_nop 0
	v_cndmask_b32_e32 v82, v233, v67, vcc
	v_cmp_lt_u32_e32 vcc, s53, v64
	v_add_u32_e32 v64, 0xffffff87, v168
	s_nop 0
	v_cndmask_b32_e32 v103, v233, v83, vcc
	v_cmp_lt_u32_e32 vcc, s53, v64
	v_add_u32_e32 v64, 0xffffffa7, v168
	v_add_u32_e32 v83, s23, v201
	v_cndmask_b32_e32 v106, v233, v68, vcc
	v_cmp_lt_u32_e32 vcc, s53, v64
	v_add_u32_e32 v64, 0xffffff88, v168
	s_nop 0
	v_cndmask_b32_e32 v104, v233, v84, vcc
	v_cmp_lt_u32_e32 vcc, s53, v64
	v_add_u32_e32 v64, 0xffffffa8, v168
	s_nop 0
	v_cndmask_b32_e32 v116, v233, v69, vcc
	v_cmp_lt_u32_e32 vcc, s53, v64
	v_add_u32_e32 v64, 0xffffff89, v168
	s_nop 0
	v_cndmask_b32_e32 v105, v233, v85, vcc
	v_cmp_lt_u32_e32 vcc, s53, v64
	v_add_u32_e32 v64, 0xffffffa9, v168
	s_nop 0
	v_cndmask_b32_e32 v120, v233, v70, vcc
	v_cmp_lt_u32_e32 vcc, s53, v64
	v_add_u32_e32 v64, 0xffffff8a, v168
	s_nop 0
	v_cndmask_b32_e32 v107, v233, v86, vcc
	v_cmp_lt_u32_e32 vcc, s53, v64
	v_add_u32_e32 v64, 0xffffffaa, v168
	s_nop 0
	v_cndmask_b32_e32 v124, v233, v71, vcc
	v_cmp_lt_u32_e32 vcc, s53, v64
	v_add_u32_e32 v64, 0xffffff8f, v168
	s_nop 0
	v_cndmask_b32_e32 v118, v233, v87, vcc
	v_cmp_lt_u32_e32 vcc, s53, v64
	v_add_u32_e32 v64, 0xffffffaf, v168
	s_nop 0
	v_cndmask_b32_e32 v129, v233, v72, vcc
	v_cmp_lt_u32_e32 vcc, s53, v64
	v_add_u32_e32 v64, 0xffffff90, v168
	s_nop 0
	v_cndmask_b32_e32 v122, v233, v88, vcc
	v_cmp_lt_u32_e32 vcc, s53, v64
	v_add_u32_e32 v64, 0xffffffb0, v168
	s_nop 0
	v_cndmask_b32_e32 v135, v233, v73, vcc
	v_cmp_lt_u32_e32 vcc, s53, v64
	v_add_u32_e32 v64, 0xffffff91, v168
	s_nop 0
	v_cndmask_b32_e32 v132, v233, v89, vcc
	v_cmp_lt_u32_e32 vcc, s53, v64
	v_add_u32_e32 v64, 0xffffffb1, v168
	s_nop 0
	v_cndmask_b32_e32 v141, v233, v74, vcc
	v_cmp_lt_u32_e32 vcc, s53, v64
	v_add_u32_e32 v64, 0xffffff92, v168
	s_nop 0
	v_cndmask_b32_e32 v139, v233, v90, vcc
	v_cmp_lt_u32_e32 vcc, s53, v64
	v_add_u32_e32 v64, 0xffffffb2, v168
	s_nop 0
	v_cndmask_b32_e32 v175, v233, v75, vcc
	v_cmp_lt_u32_e32 vcc, s53, v64
	v_add_u32_e32 v64, 0xffffff97, v168
	s_nop 0
	v_cndmask_b32_e32 v145, v233, v91, vcc
	v_cmp_lt_u32_e32 vcc, s53, v64
	v_add_u32_e32 v64, 0xffffffb7, v168
	s_nop 0
	v_cndmask_b32_e32 v177, v233, v76, vcc
	v_cmp_lt_u32_e32 vcc, s53, v64
	v_add_u32_e32 v64, 0xffffff98, v168
	s_nop 0
	v_cndmask_b32_e32 v146, v233, v92, vcc
	v_cmp_lt_u32_e32 vcc, s53, v64
	v_add_u32_e32 v64, 0xffffffb8, v168
	s_nop 0
	v_cndmask_b32_e32 v179, v233, v77, vcc
	v_cmp_lt_u32_e32 vcc, s53, v64
	v_add_u32_e32 v64, 0xffffff99, v168
	s_nop 0
	v_cndmask_b32_e32 v176, v233, v93, vcc
	v_cmp_lt_u32_e32 vcc, s53, v64
	v_add_u32_e32 v64, 0xffffffb9, v168
	s_nop 0
	v_cndmask_b32_e32 v181, v233, v78, vcc
	v_cmp_lt_u32_e32 vcc, s53, v64
	v_add_u32_e32 v64, 0xffffff9a, v168
	s_nop 0
	v_cndmask_b32_e32 v178, v233, v94, vcc
	v_cmp_lt_u32_e32 vcc, s53, v65
	s_nop 1
	v_cndmask_b32_e32 v180, v233, v95, vcc
	v_cmp_lt_u32_e32 vcc, s53, v64
	s_nop 1
	v_cndmask_b32_e32 v185, v233, v79, vcc
	ds_read_b128 v[64:67], v83 offset:41472
	ds_read_b128 v[68:71], v83 offset:36864
	ds_read_b128 v[72:75], v83 offset:36896
	ds_read_b128 v[76:79], v83 offset:41504
	ds_read_b128 v[84:87], v83 offset:36928
	ds_read_b128 v[88:91], v83 offset:41536
	ds_read_b128 v[92:95], v83 offset:36960
	ds_read_b128 v[168:171], v83 offset:41568
	s_setprio 3
	v_cvt_pk_bf16_f32 v204, v148, v149
	v_cvt_pk_bf16_f32 v205, v150, v151
	v_cvt_pk_bf16_f32 v206, v142, v143
	v_cvt_pk_bf16_f32 v207, v144, v147
	s_waitcnt lgkmcnt(6)
	s_nop 0
	v_mfma_f32_32x32x16_bf16 v[16:31], v[68:71], v[204:207], v[16:31]
	v_mov_b32_e32 v186, v148
	v_add_f32_e32 v186, v186, v149
	v_add_f32_e32 v186, v186, v150
	v_add_f32_e32 v186, v186, v151
	s_nop 0
	v_mfma_f32_32x32x16_bf16 v[32:47], v[64:67], v[204:207], v[32:47]
	v_cvt_pk_bf16_f32 v68, v136, v137
	v_cvt_pk_bf16_f32 v69, v138, v140
	v_cvt_pk_bf16_f32 v70, v130, v131
	v_cvt_pk_bf16_f32 v71, v133, v134
	v_add_f32_e32 v186, v186, v142
	v_add_f32_e32 v186, v186, v143
	v_add_f32_e32 v186, v186, v144
	v_add_f32_e32 v186, v186, v147
	s_waitcnt lgkmcnt(5)
	v_mfma_f32_32x32x16_bf16 v[16:31], v[72:75], v[68:71], v[16:31]
	v_add_f32_e32 v186, v186, v136
	v_add_f32_e32 v186, v186, v137
	v_add_f32_e32 v186, v186, v138
	v_add_f32_e32 v186, v186, v140
	s_waitcnt lgkmcnt(4)
	v_mfma_f32_32x32x16_bf16 v[32:47], v[76:79], v[68:71], v[32:47]
	v_cvt_pk_bf16_f32 v64, v125, v126
	v_cvt_pk_bf16_f32 v65, v127, v128
	v_cvt_pk_bf16_f32 v66, v117, v119
	v_cvt_pk_bf16_f32 v67, v121, v123
	v_add_f32_e32 v186, v186, v130
	v_add_f32_e32 v186, v186, v131
	v_add_f32_e32 v186, v186, v133
	v_add_f32_e32 v186, v186, v134
	s_waitcnt lgkmcnt(3)
	v_mfma_f32_32x32x16_bf16 v[16:31], v[84:87], v[64:67], v[16:31]
	v_add_f32_e32 v186, v186, v125
	v_add_f32_e32 v186, v186, v126
	v_add_f32_e32 v186, v186, v127
	v_add_f32_e32 v186, v186, v128
	s_waitcnt lgkmcnt(2)
	v_mfma_f32_32x32x16_bf16 v[32:47], v[88:91], v[64:67], v[32:47]
	v_cvt_pk_bf16_f32 v68, v108, v109
	v_cvt_pk_bf16_f32 v69, v111, v113
	v_cvt_pk_bf16_f32 v70, v110, v112
	v_cvt_pk_bf16_f32 v71, v114, v115
	v_add_f32_e32 v186, v186, v117
	v_add_f32_e32 v186, v186, v119
	v_add_f32_e32 v186, v186, v121
	v_add_f32_e32 v186, v186, v123
	s_waitcnt lgkmcnt(1)
	v_mfma_f32_32x32x16_bf16 v[16:31], v[92:95], v[68:71], v[16:31]
	v_add_f32_e32 v186, v186, v108
	v_add_f32_e32 v186, v186, v109
	v_add_f32_e32 v186, v186, v111
	v_add_f32_e32 v186, v186, v113
	s_waitcnt lgkmcnt(0)
	v_mfma_f32_32x32x16_bf16 v[32:47], v[168:171], v[68:71], v[32:47]
	v_add_f32_e32 v186, v186, v110
	v_add_f32_e32 v186, v186, v112
	v_add_f32_e32 v186, v186, v114
	v_add_f32_e32 v186, v186, v115
	s_setprio 2
	s_waitcnt lgkmcnt(0)
	s_barrier
	ds_read_b128 v[240:243], v201 offset:18432
	ds_read_b128 v[244:247], v201 offset:23040
	ds_read_b128 v[112:115], v201 offset:18464
	ds_read_b128 v[204:207], v201 offset:23072
	ds_read_b128 v[208:211], v201 offset:18496
	ds_read_b128 v[212:215], v201 offset:23104
	ds_read_b128 v[216:219], v201 offset:18528
	ds_read_b128 v[236:239], v201 offset:23136
	v_add_f32_e32 v1, v1, v14
	s_waitcnt lgkmcnt(6)
	v_mfma_f32_32x32x16_bf16 v[64:79], v[240:243], v[164:167], v[48:63]
	v_exp_f32_e32 v171, v101
	v_exp_f32_e32 v172, v80
	v_exp_f32_e32 v173, v81
	v_exp_f32_e32 v174, v82
	v_mfma_f32_32x32x16_bf16 v[80:95], v[244:247], v[164:167], v[48:63]
	v_exp_f32_e32 v151, v106
	v_exp_f32_e32 v168, v116
	v_exp_f32_e32 v169, v120
	v_exp_f32_e32 v170, v124
	s_waitcnt lgkmcnt(5)
	v_mfma_f32_32x32x16_bf16 v[64:79], v[112:115], v[160:163], v[64:79]
	v_exp_f32_e32 v147, v129
	v_exp_f32_e32 v148, v135
	v_exp_f32_e32 v149, v141
	v_exp_f32_e32 v150, v175
	s_waitcnt lgkmcnt(4)
	v_mfma_f32_32x32x16_bf16 v[80:95], v[204:207], v[160:163], v[80:95]
	v_exp_f32_e32 v141, v177
	v_exp_f32_e32 v142, v179
	v_exp_f32_e32 v143, v181
	v_exp_f32_e32 v144, v185
	s_waitcnt lgkmcnt(3)
	v_mfma_f32_32x32x16_bf16 v[64:79], v[208:211], v[156:159], v[64:79]
	v_exp_f32_e32 v135, v15
	v_exp_f32_e32 v136, v100
	v_exp_f32_e32 v137, v102
	v_exp_f32_e32 v138, v103
	s_waitcnt lgkmcnt(2)
	v_mfma_f32_32x32x16_bf16 v[80:95], v[212:215], v[156:159], v[80:95]
	v_exp_f32_e32 v128, v104
	v_exp_f32_e32 v129, v105
	v_exp_f32_e32 v130, v107
	v_exp_f32_e32 v131, v118
	s_waitcnt lgkmcnt(1)
	v_mfma_f32_32x32x16_bf16 v[64:79], v[216:219], v[152:155], v[64:79]
	v_exp_f32_e32 v118, v122
	v_exp_f32_e32 v119, v132
	v_exp_f32_e32 v120, v139
	v_exp_f32_e32 v121, v145
	s_waitcnt lgkmcnt(0)
	v_mfma_f32_32x32x16_bf16 v[80:95], v[236:239], v[152:155], v[80:95]
	v_exp_f32_e32 v122, v146
	v_exp_f32_e32 v123, v176
	v_exp_f32_e32 v124, v178
	v_exp_f32_e32 v125, v180
	s_add_i32 s87, s87, s18
	v_lshl_add_u32 v14, s87, 6, v184
	v_add_u32_e32 v15, 0xffffff7f, v14
	v_cmp_lt_u32_e32 vcc, s53, v15
	v_add_u32_e32 v15, 0xffffff9f, v14
	s_cmp_gt_i32 s25, 2
	v_cndmask_b32_e32 v101, v233, v64, vcc
	v_cmp_lt_u32_e32 vcc, s53, v15
	v_add_u32_e32 v64, 0xffffff80, v14
	s_cselect_b32 s23, -3, 2
	v_cndmask_b32_e32 v15, v233, v80, vcc
	v_cmp_lt_u32_e32 vcc, s53, v64
	v_add_u32_e32 v64, 0xffffffa0, v14
	s_add_i32 s23, s23, s25
	v_cndmask_b32_e32 v80, v233, v65, vcc
	v_cmp_lt_u32_e32 vcc, s53, v64
	v_add_u32_e32 v64, 0xffffff81, v14
	s_mulk_i32 s23, 0x2400
	v_cndmask_b32_e32 v100, v233, v81, vcc
	v_cmp_lt_u32_e32 vcc, s53, v64
	v_add_u32_e32 v64, 0xffffffa1, v14
	s_nop 7
	s_nop 3
	s_waitcnt vmcnt(3)
	ds_write_b128 v203, v[96:99]
	v_cndmask_b32_e32 v81, v233, v66, vcc
	v_cmp_lt_u32_e32 vcc, s53, v64
	v_add_u32_e32 v64, 0xffffff82, v14
	s_add_i32 s24, s25, 1
	v_cndmask_b32_e32 v102, v233, v82, vcc
	v_cmp_lt_u32_e32 vcc, s53, v64
	v_add_u32_e32 v64, 0xffffffa2, v14
	v_add_f32_e32 v1, v1, v186
	v_cndmask_b32_e32 v82, v233, v67, vcc
	v_cmp_lt_u32_e32 vcc, s53, v64
	v_add_u32_e32 v64, 0xffffff87, v14
	s_nop 0
	v_cndmask_b32_e32 v103, v233, v83, vcc
	v_cmp_lt_u32_e32 vcc, s53, v64
	v_add_u32_e32 v64, 0xffffffa7, v14
	s_nop 0
	v_cndmask_b32_e32 v106, v233, v68, vcc
	v_cmp_lt_u32_e32 vcc, s53, v64
	v_add_u32_e32 v64, 0xffffff88, v14
	v_add_u32_e32 v68, 0xffffff9a, v14
	v_cndmask_b32_e32 v104, v233, v84, vcc
	v_cmp_lt_u32_e32 vcc, s53, v64
	v_add_u32_e32 v64, 0xffffffa8, v14
	s_nop 0
	v_cndmask_b32_e32 v108, v233, v69, vcc
	v_cmp_lt_u32_e32 vcc, s53, v64
	v_add_u32_e32 v64, 0xffffff89, v14
	s_nop 0
	v_cndmask_b32_e32 v105, v233, v85, vcc
	v_cmp_lt_u32_e32 vcc, s53, v64
	v_add_u32_e32 v64, 0xffffffa9, v14
	s_nop 0
	v_cndmask_b32_e32 v110, v233, v70, vcc
	v_cmp_lt_u32_e32 vcc, s53, v64
	v_add_u32_e32 v64, 0xffffff8a, v14
	s_nop 0
	v_cndmask_b32_e32 v107, v233, v86, vcc
	v_cmp_lt_u32_e32 vcc, s53, v64
	v_add_u32_e32 v64, 0xffffffaa, v14
	s_nop 0
	v_cndmask_b32_e32 v112, v233, v71, vcc
	v_cmp_lt_u32_e32 vcc, s53, v64
	v_add_u32_e32 v64, 0xffffff8f, v14
	s_nop 0
	v_cndmask_b32_e32 v109, v233, v87, vcc
	v_cmp_lt_u32_e32 vcc, s53, v64
	v_add_u32_e32 v64, 0xffffffaf, v14
	s_nop 0
	v_cndmask_b32_e32 v114, v233, v72, vcc
	v_cmp_lt_u32_e32 vcc, s53, v64
	v_add_u32_e32 v64, 0xffffff90, v14
	s_nop 0
	v_cndmask_b32_e32 v111, v233, v88, vcc
	v_cmp_lt_u32_e32 vcc, s53, v64
	v_add_u32_e32 v64, 0xffffffb0, v14
	s_nop 0
	v_cndmask_b32_e32 v116, v233, v73, vcc
	v_cmp_lt_u32_e32 vcc, s53, v64
	v_add_u32_e32 v64, 0xffffff91, v14
	s_nop 0
	v_cndmask_b32_e32 v113, v233, v89, vcc
	v_cmp_lt_u32_e32 vcc, s53, v64
	v_add_u32_e32 v64, 0xffffffb1, v14
	s_nop 0
	v_cndmask_b32_e32 v126, v233, v74, vcc
	v_cmp_lt_u32_e32 vcc, s53, v64
	v_add_u32_e32 v64, 0xffffff92, v14
	s_nop 0
	v_cndmask_b32_e32 v115, v233, v90, vcc
	v_cmp_lt_u32_e32 vcc, s53, v64
	v_add_u32_e32 v64, 0xffffffb2, v14
	s_nop 0
	v_cndmask_b32_e32 v132, v233, v75, vcc
	v_cmp_lt_u32_e32 vcc, s53, v64
	v_add_u32_e32 v64, 0xffffff97, v14
	s_nop 0
	v_cndmask_b32_e32 v117, v233, v91, vcc
	v_cmp_lt_u32_e32 vcc, s53, v64
	v_add_u32_e32 v64, 0xffffffb7, v14
	s_nop 0
	v_cndmask_b32_e32 v134, v233, v76, vcc
	v_cmp_lt_u32_e32 vcc, s53, v64
	v_add_u32_e32 v64, 0xffffff98, v14
	s_nop 0
	v_cndmask_b32_e32 v127, v233, v92, vcc
	v_cmp_lt_u32_e32 vcc, s53, v64
	v_add_u32_e32 v64, 0xffffffb8, v14
	s_nop 0
	v_cndmask_b32_e32 v140, v233, v77, vcc
	v_cmp_lt_u32_e32 vcc, s53, v64
	v_add_u32_e32 v64, 0xffffff99, v14
	s_nop 0
	v_cndmask_b32_e32 v133, v233, v93, vcc
	v_cmp_lt_u32_e32 vcc, s53, v64
	v_add_u32_e32 v64, 0xffffffb9, v14
	v_add_u32_e32 v14, 0xffffffba, v14
	v_cndmask_b32_e32 v146, v233, v78, vcc
	v_cmp_lt_u32_e32 vcc, s53, v64
	s_nop 1
	v_cndmask_b32_e32 v139, v233, v94, vcc
	v_cmp_lt_u32_e32 vcc, s53, v14
	v_add_u32_e32 v14, s23, v203
	s_waitcnt vmcnt(2)
	ds_write_b128 v14, v[10:13] offset:36864
	v_add_u32_e32 v14, s22, v201
	s_add_i32 s22, s45, 9
	s_min_i32 s22, s22, s92
	s_cmp_gt_i32 s22, 3
	s_cselect_b32 s23, s13, 0
	s_add_i32 s22, s23, s22
	s_ashr_i32 s23, s22, 31
	v_cndmask_b32_e32 v145, v233, v95, vcc
	s_lshl_b64 vcc, s[22:23], 13
	s_lshl_b32 s34, s34, 6
	v_lshl_add_u64 v[10:11], v[198:199], 0, vcc
	s_ashr_i32 s35, s34, 31
	global_load_dwordx4 v[96:99], v[10:11], off
	v_lshl_add_u64 v[10:11], s[34:35], 1, v[196:197]
	global_load_dwordx4 v[10:13], v[10:11], off
	ds_read_b128 v[240:243], v201 offset:27648
	ds_read_b128 v[244:247], v201 offset:32256
	ds_read_b128 v[64:67], v14 offset:41472
	ds_read_b128 v[70:73], v14 offset:36864
	ds_read_b128 v[74:77], v14 offset:36896
	ds_read_b128 v[84:87], v14 offset:41504
	ds_read_b128 v[88:91], v14 offset:36928
	ds_read_b128 v[92:95], v14 offset:41536
	ds_read_b128 v[176:179], v14 offset:36960
	ds_read_b128 v[204:207], v14 offset:41568
	s_setprio 1
	v_cvt_pk_bf16_f32 v208, v171, v172
	v_cvt_pk_bf16_f32 v209, v173, v174
	v_cvt_pk_bf16_f32 v210, v151, v168
	v_cvt_pk_bf16_f32 v211, v169, v170
	s_waitcnt lgkmcnt(6)
	s_nop 0
	v_mfma_f32_32x32x16_bf16 v[16:31], v[70:73], v[208:211], v[16:31]
	v_mov_b32_e32 v14, v171
	v_add_f32_e32 v14, v14, v172
	v_add_f32_e32 v14, v14, v173
	v_add_f32_e32 v14, v14, v174
	s_nop 0
	v_mfma_f32_32x32x16_bf16 v[32:47], v[64:67], v[208:211], v[32:47]
	v_cvt_pk_bf16_f32 v70, v147, v148
	v_cvt_pk_bf16_f32 v71, v149, v150
	v_cvt_pk_bf16_f32 v72, v141, v142
	v_cvt_pk_bf16_f32 v73, v143, v144
	v_add_f32_e32 v14, v14, v151
	v_add_f32_e32 v14, v14, v168
	v_add_f32_e32 v14, v14, v169
	v_add_f32_e32 v14, v14, v170
	s_waitcnt lgkmcnt(5)
	v_mfma_f32_32x32x16_bf16 v[16:31], v[74:77], v[70:73], v[16:31]
	v_add_f32_e32 v14, v14, v147
	v_add_f32_e32 v14, v14, v148
	v_add_f32_e32 v14, v14, v149
	v_add_f32_e32 v14, v14, v150
	s_waitcnt lgkmcnt(4)
	v_mfma_f32_32x32x16_bf16 v[32:47], v[84:87], v[70:73], v[32:47]
	v_cvt_pk_bf16_f32 v64, v135, v136
	v_cvt_pk_bf16_f32 v65, v137, v138
	v_cvt_pk_bf16_f32 v66, v128, v129
	v_cvt_pk_bf16_f32 v67, v130, v131
	v_add_f32_e32 v14, v14, v141
	v_add_f32_e32 v14, v14, v142
	v_add_f32_e32 v14, v14, v143
	v_add_f32_e32 v14, v14, v144
	s_waitcnt lgkmcnt(3)
	v_mfma_f32_32x32x16_bf16 v[16:31], v[88:91], v[64:67], v[16:31]
	v_add_f32_e32 v14, v14, v135
	v_add_f32_e32 v14, v14, v136
	v_add_f32_e32 v14, v14, v137
	v_add_f32_e32 v14, v14, v138
	s_waitcnt lgkmcnt(2)
	v_mfma_f32_32x32x16_bf16 v[32:47], v[92:95], v[64:67], v[32:47]
	v_cvt_pk_bf16_f32 v70, v118, v119
	v_cvt_pk_bf16_f32 v71, v120, v121
	v_cvt_pk_bf16_f32 v72, v122, v123
	v_cvt_pk_bf16_f32 v73, v124, v125
	v_add_f32_e32 v14, v14, v128
	v_add_f32_e32 v14, v14, v129
	v_add_f32_e32 v14, v14, v130
	v_add_f32_e32 v14, v14, v131
	s_waitcnt lgkmcnt(1)
	v_mfma_f32_32x32x16_bf16 v[16:31], v[176:179], v[70:73], v[16:31]
	v_add_f32_e32 v14, v14, v118
	v_add_f32_e32 v14, v14, v119
	v_add_f32_e32 v14, v14, v120
	v_add_f32_e32 v14, v14, v121
	s_waitcnt lgkmcnt(0)
	v_mfma_f32_32x32x16_bf16 v[32:47], v[204:207], v[70:73], v[32:47]
	v_add_f32_e32 v14, v14, v122
	v_add_f32_e32 v14, v14, v123
	v_add_f32_e32 v14, v14, v124
	v_add_f32_e32 v14, v14, v125
	s_setprio 0
	ds_read_b128 v[122:125], v201 offset:27680
	ds_read_b128 v[174:177], v201 offset:32288
	ds_read_b128 v[178:181], v201 offset:27712
	ds_read_b128 v[204:207], v201 offset:32320
	ds_read_b128 v[208:211], v201 offset:27744
	ds_read_b128 v[212:215], v201 offset:32352
	v_cmp_lt_u32_e32 vcc, s53, v68
	s_cmp_lg_u32 s25, 4
	s_cselect_b32 s23, s24, 0
	v_cndmask_b32_e32 v131, v233, v79, vcc
	s_waitcnt lgkmcnt(6)
	v_mfma_f32_32x32x16_bf16 v[64:79], v[240:243], v[164:167], v[48:63]
	v_exp_f32_e32 v169, v101
	v_exp_f32_e32 v170, v80
	v_exp_f32_e32 v171, v81
	v_exp_f32_e32 v172, v82
	v_mfma_f32_32x32x16_bf16 v[80:95], v[244:247], v[164:167], v[48:63]
	v_exp_f32_e32 v147, v106
	v_exp_f32_e32 v148, v108
	v_exp_f32_e32 v149, v110
	v_exp_f32_e32 v150, v112
	s_waitcnt lgkmcnt(5)
	v_mfma_f32_32x32x16_bf16 v[64:79], v[122:125], v[160:163], v[64:79]
	v_exp_f32_e32 v138, v114
	v_exp_f32_e32 v141, v116
	v_exp_f32_e32 v142, v126
	v_exp_f32_e32 v143, v132
	s_waitcnt lgkmcnt(4)
	v_mfma_f32_32x32x16_bf16 v[80:95], v[174:177], v[160:163], v[80:95]
	v_exp_f32_e32 v128, v134
	v_exp_f32_e32 v129, v140
	v_exp_f32_e32 v130, v146
	v_exp_f32_e32 v135, v131
	s_waitcnt lgkmcnt(3)
	v_mfma_f32_32x32x16_bf16 v[64:79], v[178:181], v[156:159], v[64:79]
	v_exp_f32_e32 v122, v15
	v_exp_f32_e32 v123, v100
	v_exp_f32_e32 v124, v102
	v_exp_f32_e32 v125, v103
	s_waitcnt lgkmcnt(2)
	v_mfma_f32_32x32x16_bf16 v[80:95], v[204:207], v[156:159], v[80:95]
	v_exp_f32_e32 v118, v104
	v_exp_f32_e32 v119, v105
	v_exp_f32_e32 v120, v107
	v_exp_f32_e32 v121, v109
	s_waitcnt lgkmcnt(1)
	v_mfma_f32_32x32x16_bf16 v[64:79], v[208:211], v[152:155], v[64:79]
	v_exp_f32_e32 v107, v111
	v_exp_f32_e32 v108, v113
	v_exp_f32_e32 v109, v115
	v_exp_f32_e32 v110, v117
	s_waitcnt lgkmcnt(0)
	v_mfma_f32_32x32x16_bf16 v[80:95], v[212:215], v[152:155], v[80:95]
	v_exp_f32_e32 v111, v127
	v_exp_f32_e32 v113, v133
	v_exp_f32_e32 v114, v139
	v_exp_f32_e32 v115, v145
	s_add_i32 s2, s2, s18
	s_cmp_gt_i32 s23, 2
	v_lshl_add_u32 v127, s2, 6, v184
	s_cselect_b32 s2, -3, 2
	s_add_i32 s2, s2, s23
	s_mulk_i32 s2, 0x2400
	s_nop 7
	s_nop 3
	s_waitcnt vmcnt(3)
	ds_write_b128 v203, v[2:5] offset:9216
	v_add_u32_e32 v2, s2, v203
	s_add_i32 s2, s23, 1
	s_cmp_lg_u32 s23, 4
	s_cselect_b32 s2, s2, 0
	s_add_i32 s23, s45, 10
	s_min_i32 s23, s23, s92
	s_cmp_gt_i32 s23, 3
	s_cselect_b32 s24, s13, 0
	s_add_i32 s24, s24, s23
	s_ashr_i32 s25, s24, 31
	s_lshl_b32 s22, s22, 6
	s_lshl_b64 s[34:35], s[24:25], 13
	s_ashr_i32 s23, s22, 31
	s_waitcnt vmcnt(2)
	ds_write_b128 v2, v[6:9] offset:36864
	v_lshl_add_u64 v[2:3], v[198:199], 0, s[34:35]
	v_lshl_add_u64 v[6:7], s[22:23], 1, v[196:197]
	global_load_dwordx4 v[2:5], v[2:3], off
	v_add_u32_e32 v15, 0xffffff7f, v127
	global_load_dwordx4 v[6:9], v[6:7], off
	v_cmp_lt_u32_e32 vcc, s53, v15
	v_add_u32_e32 v15, 0xffffff9f, v127
	s_mul_i32 s22, s2, 0x2400
	v_cndmask_b32_e32 v101, v233, v64, vcc
	v_cmp_lt_u32_e32 vcc, s53, v15
	v_add_u32_e32 v64, 0xffffff80, v127
	s_add_i32 s23, s22, 0xffffdc00
	v_cndmask_b32_e32 v15, v233, v80, vcc
	v_cmp_lt_u32_e32 vcc, s53, v64
	v_add_u32_e32 v64, 0xffffffa0, v127
	s_cmp_lg_u32 s2, 0
	v_cndmask_b32_e32 v80, v233, v65, vcc
	v_cmp_lt_u32_e32 vcc, s53, v64
	v_add_u32_e32 v64, 0xffffff81, v127
	v_add_u32_e32 v65, 0xffffffba, v127
	v_cndmask_b32_e32 v100, v233, v81, vcc
	v_cmp_lt_u32_e32 vcc, s53, v64
	v_add_u32_e32 v64, 0xffffffa1, v127
	s_cselect_b32 s23, s23, 0x9000
	v_cndmask_b32_e32 v81, v233, v66, vcc
	v_cmp_lt_u32_e32 vcc, s53, v64
	v_add_u32_e32 v64, 0xffffff82, v127
	s_nop 0
	v_cndmask_b32_e32 v102, v233, v82, vcc
	v_cmp_lt_u32_e32 vcc, s53, v64
	v_add_u32_e32 v64, 0xffffffa2, v127
	s_nop 0
	v_cndmask_b32_e32 v82, v233, v67, vcc
	v_cmp_lt_u32_e32 vcc, s53, v64
	v_add_u32_e32 v64, 0xffffff87, v127
	s_nop 0
	v_cndmask_b32_e32 v103, v233, v83, vcc
	v_cmp_lt_u32_e32 vcc, s53, v64
	v_add_u32_e32 v64, 0xffffffa7, v127
	v_add_u32_e32 v83, s23, v201
	v_cndmask_b32_e32 v106, v233, v68, vcc
	v_cmp_lt_u32_e32 vcc, s53, v64
	v_add_u32_e32 v64, 0xffffff88, v127
	s_nop 0
	v_cndmask_b32_e32 v104, v233, v84, vcc
	v_cmp_lt_u32_e32 vcc, s53, v64
	v_add_u32_e32 v64, 0xffffffa8, v127
	s_nop 0
	v_cndmask_b32_e32 v116, v233, v69, vcc
	v_cmp_lt_u32_e32 vcc, s53, v64
	v_add_u32_e32 v64, 0xffffff89, v127
	s_nop 0
	v_cndmask_b32_e32 v105, v233, v85, vcc
	v_cmp_lt_u32_e32 vcc, s53, v64
	v_add_u32_e32 v64, 0xffffffa9, v127
	s_nop 0
	v_cndmask_b32_e32 v117, v233, v70, vcc
	v_cmp_lt_u32_e32 vcc, s53, v64
	v_add_u32_e32 v64, 0xffffff8a, v127
	s_nop 0
	v_cndmask_b32_e32 v112, v233, v86, vcc
	v_cmp_lt_u32_e32 vcc, s53, v64
	v_add_u32_e32 v64, 0xffffffaa, v127
	s_nop 0
	v_cndmask_b32_e32 v126, v233, v71, vcc
	v_cmp_lt_u32_e32 vcc, s53, v64
	v_add_u32_e32 v64, 0xffffff8f, v127
	s_nop 0
	v_cndmask_b32_e32 v131, v233, v87, vcc
	v_cmp_lt_u32_e32 vcc, s53, v64
	v_add_u32_e32 v64, 0xffffffaf, v127
	s_nop 0
	v_cndmask_b32_e32 v134, v233, v72, vcc
	v_cmp_lt_u32_e32 vcc, s53, v64
	v_add_u32_e32 v64, 0xffffff90, v127
	s_nop 0
	v_cndmask_b32_e32 v132, v233, v88, vcc
	v_cmp_lt_u32_e32 vcc, s53, v64
	v_add_u32_e32 v64, 0xffffffb0, v127
	s_nop 0
	v_cndmask_b32_e32 v137, v233, v73, vcc
	v_cmp_lt_u32_e32 vcc, s53, v64
	v_add_u32_e32 v64, 0xffffff91, v127
	s_nop 0
	v_cndmask_b32_e32 v133, v233, v89, vcc
	v_cmp_lt_u32_e32 vcc, s53, v64
	v_add_u32_e32 v64, 0xffffffb1, v127
	s_nop 0
	v_cndmask_b32_e32 v140, v233, v74, vcc
	v_cmp_lt_u32_e32 vcc, s53, v64
	v_add_u32_e32 v64, 0xffffff92, v127
	s_nop 0
	v_cndmask_b32_e32 v136, v233, v90, vcc
	v_cmp_lt_u32_e32 vcc, s53, v64
	v_add_u32_e32 v64, 0xffffffb2, v127
	s_nop 0
	v_cndmask_b32_e32 v145, v233, v75, vcc
	v_cmp_lt_u32_e32 vcc, s53, v64
	v_add_u32_e32 v64, 0xffffff97, v127
	s_nop 0
	v_cndmask_b32_e32 v139, v233, v91, vcc
	v_cmp_lt_u32_e32 vcc, s53, v64
	v_add_u32_e32 v64, 0xffffffb7, v127
	s_nop 0
	v_cndmask_b32_e32 v151, v233, v76, vcc
	v_cmp_lt_u32_e32 vcc, s53, v64
	v_add_u32_e32 v64, 0xffffff98, v127
	s_nop 0
	v_cndmask_b32_e32 v144, v233, v92, vcc
	v_cmp_lt_u32_e32 vcc, s53, v64
	v_add_u32_e32 v64, 0xffffffb8, v127
	s_nop 0
	v_cndmask_b32_e32 v173, v233, v77, vcc
	v_cmp_lt_u32_e32 vcc, s53, v64
	v_add_u32_e32 v64, 0xffffff99, v127
	s_nop 0
	v_cndmask_b32_e32 v146, v233, v93, vcc
	v_cmp_lt_u32_e32 vcc, s53, v64
	v_add_u32_e32 v64, 0xffffffb9, v127
	s_nop 0
	v_cndmask_b32_e32 v175, v233, v78, vcc
	v_cmp_lt_u32_e32 vcc, s53, v64
	v_add_u32_e32 v64, 0xffffff9a, v127
	s_nop 0
	v_cndmask_b32_e32 v168, v233, v94, vcc
	v_cmp_lt_u32_e32 vcc, s53, v65
	s_nop 1
	v_cndmask_b32_e32 v174, v233, v95, vcc
	v_cmp_lt_u32_e32 vcc, s53, v64
	s_nop 1
	v_cndmask_b32_e32 v180, v233, v79, vcc
	ds_read_b128 v[64:67], v83 offset:41472
	ds_read_b128 v[68:71], v83 offset:36864
	ds_read_b128 v[72:75], v83 offset:36896
	ds_read_b128 v[76:79], v83 offset:41504
	ds_read_b128 v[84:87], v83 offset:36928
	ds_read_b128 v[88:91], v83 offset:41536
	ds_read_b128 v[92:95], v83 offset:36960
	ds_read_b128 v[176:179], v83 offset:41568
	s_setprio 3
	v_cvt_pk_bf16_f32 v204, v169, v170
	v_cvt_pk_bf16_f32 v205, v171, v172
	v_cvt_pk_bf16_f32 v206, v147, v148
	v_cvt_pk_bf16_f32 v207, v149, v150
	s_waitcnt lgkmcnt(6)
	s_nop 0
	v_mfma_f32_32x32x16_bf16 v[16:31], v[68:71], v[204:207], v[16:31]
	v_mov_b32_e32 v230, v169
	v_add_f32_e32 v230, v230, v170
	v_add_f32_e32 v230, v230, v171
	v_add_f32_e32 v230, v230, v172
	s_nop 0
	v_mfma_f32_32x32x16_bf16 v[32:47], v[64:67], v[204:207], v[32:47]
	v_cvt_pk_bf16_f32 v68, v138, v141
	v_cvt_pk_bf16_f32 v69, v142, v143
	v_cvt_pk_bf16_f32 v70, v128, v129
	v_cvt_pk_bf16_f32 v71, v130, v135
	v_add_f32_e32 v230, v230, v147
	v_add_f32_e32 v230, v230, v148
	v_add_f32_e32 v230, v230, v149
	v_add_f32_e32 v230, v230, v150
	s_waitcnt lgkmcnt(5)
	v_mfma_f32_32x32x16_bf16 v[16:31], v[72:75], v[68:71], v[16:31]
	v_add_f32_e32 v230, v230, v138
	v_add_f32_e32 v230, v230, v141
	v_add_f32_e32 v230, v230, v142
	v_add_f32_e32 v230, v230, v143
	s_waitcnt lgkmcnt(4)
	v_mfma_f32_32x32x16_bf16 v[32:47], v[76:79], v[68:71], v[32:47]
	v_cvt_pk_bf16_f32 v64, v122, v123
	v_cvt_pk_bf16_f32 v65, v124, v125
	v_cvt_pk_bf16_f32 v66, v118, v119
	v_cvt_pk_bf16_f32 v67, v120, v121
	v_add_f32_e32 v230, v230, v128
	v_add_f32_e32 v230, v230, v129
	v_add_f32_e32 v230, v230, v130
	v_add_f32_e32 v230, v230, v135
	s_waitcnt lgkmcnt(3)
	v_mfma_f32_32x32x16_bf16 v[16:31], v[84:87], v[64:67], v[16:31]
	v_add_f32_e32 v230, v230, v122
	v_add_f32_e32 v230, v230, v123
	v_add_f32_e32 v230, v230, v124
	v_add_f32_e32 v230, v230, v125
	s_waitcnt lgkmcnt(2)
	v_mfma_f32_32x32x16_bf16 v[32:47], v[88:91], v[64:67], v[32:47]
	v_cvt_pk_bf16_f32 v68, v107, v108
	v_cvt_pk_bf16_f32 v69, v109, v110
	v_cvt_pk_bf16_f32 v70, v111, v113
	v_cvt_pk_bf16_f32 v71, v114, v115
	v_add_f32_e32 v230, v230, v118
	v_add_f32_e32 v230, v230, v119
	v_add_f32_e32 v230, v230, v120
	v_add_f32_e32 v230, v230, v121
	s_waitcnt lgkmcnt(1)
	v_mfma_f32_32x32x16_bf16 v[16:31], v[92:95], v[68:71], v[16:31]
	v_add_f32_e32 v230, v230, v107
	v_add_f32_e32 v230, v230, v108
	v_add_f32_e32 v230, v230, v109
	v_add_f32_e32 v230, v230, v110
	s_waitcnt lgkmcnt(0)
	v_mfma_f32_32x32x16_bf16 v[32:47], v[176:179], v[68:71], v[32:47]
	v_add_f32_e32 v230, v230, v111
	v_add_f32_e32 v230, v230, v113
	v_add_f32_e32 v230, v230, v114
	v_add_f32_e32 v230, v230, v115
	s_setprio 2
	s_waitcnt lgkmcnt(0)
	s_barrier
	ds_read_b128 v[240:243], v201
	ds_read_b128 v[244:247], v201 offset:4608
	ds_read_b128 v[118:121], v201 offset:32
	ds_read_b128 v[176:179], v201 offset:4640
	ds_read_b128 v[206:209], v201 offset:64
	ds_read_b128 v[210:213], v201 offset:4672
	ds_read_b128 v[214:217], v201 offset:96
	ds_read_b128 v[218:221], v201 offset:4704
	v_add_f32_e32 v169, v1, v14
	s_waitcnt lgkmcnt(6)
	v_mfma_f32_32x32x16_bf16 v[64:79], v[240:243], v[164:167], v[48:63]
	v_exp_f32_e32 v185, v101
	v_exp_f32_e32 v186, v80
	v_exp_f32_e32 v187, v81
	v_exp_f32_e32 v204, v82
	v_mfma_f32_32x32x16_bf16 v[80:95], v[244:247], v[164:167], v[48:63]
	v_exp_f32_e32 v127, v106
	v_exp_f32_e32 v128, v116
	v_exp_f32_e32 v129, v117
	v_exp_f32_e32 v130, v126
	s_waitcnt lgkmcnt(5)
	v_mfma_f32_32x32x16_bf16 v[64:79], v[118:121], v[160:163], v[64:79]
	v_exp_f32_e32 v123, v134
	v_exp_f32_e32 v124, v137
	v_exp_f32_e32 v125, v140
	v_exp_f32_e32 v126, v145
	s_waitcnt lgkmcnt(4)
	v_mfma_f32_32x32x16_bf16 v[80:95], v[176:179], v[160:163], v[80:95]
	v_exp_f32_e32 v119, v151
	v_exp_f32_e32 v120, v173
	v_exp_f32_e32 v121, v175
	v_exp_f32_e32 v122, v180
	s_waitcnt lgkmcnt(3)
	v_mfma_f32_32x32x16_bf16 v[64:79], v[206:209], v[156:159], v[64:79]
	v_exp_f32_e32 v111, v15
	v_exp_f32_e32 v116, v100
	v_exp_f32_e32 v117, v102
	v_exp_f32_e32 v118, v103
	s_waitcnt lgkmcnt(2)
	v_mfma_f32_32x32x16_bf16 v[80:95], v[210:213], v[156:159], v[80:95]
	v_exp_f32_e32 v107, v104
	v_exp_f32_e32 v108, v105
	v_exp_f32_e32 v109, v112
	v_exp_f32_e32 v110, v131
	s_waitcnt lgkmcnt(1)
	v_mfma_f32_32x32x16_bf16 v[64:79], v[214:217], v[152:155], v[64:79]
	v_exp_f32_e32 v103, v132
	v_exp_f32_e32 v104, v133
	v_exp_f32_e32 v105, v136
	v_exp_f32_e32 v106, v139
	s_waitcnt lgkmcnt(0)
	v_mfma_f32_32x32x16_bf16 v[80:95], v[218:221], v[152:155], v[80:95]
	v_exp_f32_e32 v1, v144
	v_exp_f32_e32 v100, v146
	v_exp_f32_e32 v101, v168
	v_exp_f32_e32 v102, v174
	v_lshl_add_u32 v131, s27, 6, v184
	v_add_u32_e32 v14, 0xffffff7f, v131
	v_cmp_lt_u32_e32 vcc, s53, v14
	v_add_u32_e32 v14, 0xffffff9f, v131
	v_add_u32_e32 v15, 0xffffff80, v131
	v_cndmask_b32_e32 v112, v233, v64, vcc
	v_cmp_lt_u32_e32 vcc, s53, v14
	v_add_u32_e32 v64, 0xffffff81, v131
	s_cmp_gt_i32 s2, 2
	v_cndmask_b32_e32 v14, v233, v80, vcc
	v_cmp_lt_u32_e32 vcc, s53, v15
	v_add_u32_e32 v15, 0xffffffa0, v131
	s_cselect_b32 s23, -3, 2
	v_cndmask_b32_e32 v113, v233, v65, vcc
	v_cmp_lt_u32_e32 vcc, s53, v15
	s_add_i32 s23, s23, s2
	v_add_u32_e32 v65, 0xffffffba, v131
	v_cndmask_b32_e32 v15, v233, v81, vcc
	v_cmp_lt_u32_e32 vcc, s53, v64
	v_add_u32_e32 v64, 0xffffffa1, v131
	s_mulk_i32 s23, 0x2400
	v_cndmask_b32_e32 v114, v233, v66, vcc
	v_cmp_lt_u32_e32 vcc, s53, v64
	v_add_u32_e32 v64, 0xffffff82, v131
	s_nop 7
	s_nop 3
	s_waitcnt vmcnt(3)
	ds_write_b128 v203, v[96:99] offset:18432
	v_cndmask_b32_e32 v132, v233, v82, vcc
	v_cmp_lt_u32_e32 vcc, s53, v64
	v_add_u32_e32 v64, 0xffffffa2, v131
	v_add_f32_e32 v96, v169, v230
	v_cndmask_b32_e32 v115, v233, v67, vcc
	v_cmp_lt_u32_e32 vcc, s53, v64
	v_add_u32_e32 v64, 0xffffff87, v131
	s_nop 0
	v_cndmask_b32_e32 v133, v233, v83, vcc
	v_cmp_lt_u32_e32 vcc, s53, v64
	v_add_u32_e32 v64, 0xffffffa7, v131
	s_nop 0
	v_cndmask_b32_e32 v140, v233, v68, vcc
	v_cmp_lt_u32_e32 vcc, s53, v64
	v_add_u32_e32 v64, 0xffffff88, v131
	s_nop 0
	v_cndmask_b32_e32 v134, v233, v84, vcc
	v_cmp_lt_u32_e32 vcc, s53, v64
	v_add_u32_e32 v64, 0xffffffa8, v131
	s_nop 0
	v_cndmask_b32_e32 v141, v233, v69, vcc
	v_cmp_lt_u32_e32 vcc, s53, v64
	v_add_u32_e32 v64, 0xffffff89, v131
	s_nop 0
	v_cndmask_b32_e32 v135, v233, v85, vcc
	v_cmp_lt_u32_e32 vcc, s53, v64
	v_add_u32_e32 v64, 0xffffffa9, v131
	s_nop 0
	v_cndmask_b32_e32 v146, v233, v70, vcc
	v_cmp_lt_u32_e32 vcc, s53, v64
	v_add_u32_e32 v64, 0xffffff8a, v131
	s_nop 0
	v_cndmask_b32_e32 v136, v233, v86, vcc
	v_cmp_lt_u32_e32 vcc, s53, v64
	v_add_u32_e32 v64, 0xffffffaa, v131
	s_nop 0
	v_cndmask_b32_e32 v147, v233, v71, vcc
	v_cmp_lt_u32_e32 vcc, s53, v64
	v_add_u32_e32 v64, 0xffffff8f, v131
	s_nop 0
	v_cndmask_b32_e32 v137, v233, v87, vcc
	v_cmp_lt_u32_e32 vcc, s53, v64
	v_add_u32_e32 v64, 0xffffffaf, v131
	s_nop 0
	v_cndmask_b32_e32 v148, v233, v72, vcc
	v_cmp_lt_u32_e32 vcc, s53, v64
	v_add_u32_e32 v64, 0xffffff90, v131
	s_nop 0
	v_cndmask_b32_e32 v138, v233, v88, vcc
	v_cmp_lt_u32_e32 vcc, s53, v64
	v_add_u32_e32 v64, 0xffffffb0, v131
	v_add_u32_e32 v88, s22, v201
	v_cndmask_b32_e32 v149, v233, v73, vcc
	v_cmp_lt_u32_e32 vcc, s53, v64
	v_add_u32_e32 v64, 0xffffff91, v131
	s_add_i32 s22, s45, 11
	v_cndmask_b32_e32 v139, v233, v89, vcc
	v_cmp_lt_u32_e32 vcc, s53, v64
	v_add_u32_e32 v64, 0xffffffb1, v131
	s_min_i32 s22, s22, s92
	v_cndmask_b32_e32 v176, v233, v74, vcc
	v_cmp_lt_u32_e32 vcc, s53, v64
	v_add_u32_e32 v64, 0xffffff92, v131
	s_cmp_gt_i32 s22, 3
	v_cndmask_b32_e32 v142, v233, v90, vcc
	v_cmp_lt_u32_e32 vcc, s53, v64
	v_add_u32_e32 v64, 0xffffffb2, v131
	s_nop 0
	v_cndmask_b32_e32 v177, v233, v75, vcc
	v_cmp_lt_u32_e32 vcc, s53, v64
	v_add_u32_e32 v64, 0xffffff97, v131
	s_nop 0
	v_cndmask_b32_e32 v143, v233, v91, vcc
	v_cmp_lt_u32_e32 vcc, s53, v64
	v_add_u32_e32 v64, 0xffffffb7, v131
	s_nop 0
	v_cndmask_b32_e32 v178, v233, v76, vcc
	v_cmp_lt_u32_e32 vcc, s53, v64
	v_add_u32_e32 v64, 0xffffff98, v131
	s_nop 0
	v_cndmask_b32_e32 v144, v233, v92, vcc
	v_cmp_lt_u32_e32 vcc, s53, v64
	v_add_u32_e32 v64, 0xffffffb8, v131
	s_nop 0
	v_cndmask_b32_e32 v179, v233, v77, vcc
	v_cmp_lt_u32_e32 vcc, s53, v64
	v_add_u32_e32 v64, 0xffffff99, v131
	s_nop 0
	v_cndmask_b32_e32 v145, v233, v93, vcc
	v_cmp_lt_u32_e32 vcc, s53, v64
	v_add_u32_e32 v64, 0xffffffb9, v131
	s_nop 0
	v_cndmask_b32_e32 v180, v233, v78, vcc
	v_cmp_lt_u32_e32 vcc, s53, v64
	v_add_u32_e32 v64, 0xffffff9a, v131
	s_nop 0
	v_cndmask_b32_e32 v150, v233, v94, vcc
	v_cmp_lt_u32_e32 vcc, s53, v65
	v_add_u32_e32 v65, s23, v203
	s_cselect_b32 s23, s13, 0
	s_add_i32 s22, s23, s22
	s_ashr_i32 s23, s22, 31
	s_lshl_b64 s[22:23], s[22:23], 13
	s_waitcnt vmcnt(2)
	ds_write_b128 v65, v[10:13] offset:36864
	v_lshl_add_u64 v[10:11], v[198:199], 0, s[22:23]
	s_lshl_b32 s22, s24, 6
	s_ashr_i32 s23, s22, 31
	global_load_dwordx4 v[168:171], v[10:11], off
	v_lshl_add_u64 v[10:11], s[22:23], 1, v[196:197]
	global_load_dwordx4 v[172:175], v[10:11], off
	v_cndmask_b32_e32 v151, v233, v95, vcc
	v_cmp_lt_u32_e32 vcc, s53, v64
	s_nop 1
	v_cndmask_b32_e32 v181, v233, v79, vcc
	ds_read_b128 v[240:243], v201 offset:9216
	ds_read_b128 v[244:247], v201 offset:13824
	ds_read_b128 v[10:13], v88 offset:41472
	ds_read_b128 v[64:67], v88 offset:36864
	ds_read_b128 v[68:71], v88 offset:36896
	ds_read_b128 v[72:75], v88 offset:41504
	ds_read_b128 v[76:79], v88 offset:36928
	ds_read_b128 v[80:83], v88 offset:41536
	ds_read_b128 v[84:87], v88 offset:36960
	ds_read_b128 v[88:91], v88 offset:41568
	s_setprio 1
	v_mov_b32_e32 v98, v112
	v_cvt_pk_bf16_f32 v92, v185, v186
	v_cvt_pk_bf16_f32 v93, v187, v204
	v_cvt_pk_bf16_f32 v94, v127, v128
	v_cvt_pk_bf16_f32 v95, v129, v130
	s_waitcnt lgkmcnt(6)
	s_nop 0
	v_mfma_f32_32x32x16_bf16 v[16:31], v[64:67], v[92:95], v[16:31]
	v_max3_f32 v98, v98, v113, v114
	v_max3_f32 v98, v98, v115, v140
	v_mov_b32_e32 v97, v185
	v_add_f32_e32 v97, v97, v186
	v_add_f32_e32 v97, v97, v187
	v_add_f32_e32 v97, v97, v204
	s_nop 0
	v_mfma_f32_32x32x16_bf16 v[32:47], v[10:13], v[92:95], v[32:47]
	v_cvt_pk_bf16_f32 v64, v123, v124
	v_cvt_pk_bf16_f32 v65, v125, v126
	v_cvt_pk_bf16_f32 v66, v119, v120
	v_cvt_pk_bf16_f32 v67, v121, v122
	v_max3_f32 v98, v98, v141, v146
	v_max3_f32 v98, v98, v147, v148
	v_add_f32_e32 v97, v97, v127
	v_add_f32_e32 v97, v97, v128
	v_add_f32_e32 v97, v97, v129
	v_add_f32_e32 v97, v97, v130
	s_waitcnt lgkmcnt(5)
	v_mfma_f32_32x32x16_bf16 v[16:31], v[68:71], v[64:67], v[16:31]
	v_max3_f32 v98, v98, v149, v176
	v_max3_f32 v98, v98, v177, v178
	v_add_f32_e32 v97, v97, v123
	v_add_f32_e32 v97, v97, v124
	v_add_f32_e32 v97, v97, v125
	v_add_f32_e32 v97, v97, v126
	s_waitcnt lgkmcnt(4)
	v_mfma_f32_32x32x16_bf16 v[32:47], v[72:75], v[64:67], v[32:47]
	v_cvt_pk_bf16_f32 v10, v111, v116
	v_cvt_pk_bf16_f32 v11, v117, v118
	v_cvt_pk_bf16_f32 v12, v107, v108
	v_cvt_pk_bf16_f32 v13, v109, v110
	v_max3_f32 v98, v98, v179, v180
	v_max3_f32 v98, v98, v181, v14
	v_add_f32_e32 v97, v97, v119
	v_add_f32_e32 v97, v97, v120
	v_add_f32_e32 v97, v97, v121
	v_add_f32_e32 v97, v97, v122
	s_waitcnt lgkmcnt(3)
	v_mfma_f32_32x32x16_bf16 v[16:31], v[76:79], v[10:13], v[16:31]
	v_max3_f32 v98, v98, v15, v132
	v_max3_f32 v98, v98, v133, v134
	v_add_f32_e32 v97, v97, v111
	v_add_f32_e32 v97, v97, v116
	v_add_f32_e32 v97, v97, v117
	v_add_f32_e32 v97, v97, v118
	s_waitcnt lgkmcnt(2)
	v_mfma_f32_32x32x16_bf16 v[32:47], v[80:83], v[10:13], v[32:47]
	v_cvt_pk_bf16_f32 v64, v103, v104
	v_cvt_pk_bf16_f32 v65, v105, v106
	v_cvt_pk_bf16_f32 v66, v1, v100
	v_cvt_pk_bf16_f32 v67, v101, v102
	v_max3_f32 v98, v98, v135, v136
	v_max3_f32 v98, v98, v137, v138
	v_add_f32_e32 v97, v97, v107
	v_add_f32_e32 v97, v97, v108
	v_add_f32_e32 v97, v97, v109
	v_add_f32_e32 v97, v97, v110
	s_waitcnt lgkmcnt(1)
	v_mfma_f32_32x32x16_bf16 v[16:31], v[84:87], v[64:67], v[16:31]
	v_max3_f32 v98, v98, v139, v142
	v_max3_f32 v98, v98, v143, v144
	v_add_f32_e32 v97, v97, v103
	v_add_f32_e32 v97, v97, v104
	v_add_f32_e32 v97, v97, v105
	v_add_f32_e32 v97, v97, v106
	s_waitcnt lgkmcnt(0)
	v_mfma_f32_32x32x16_bf16 v[32:47], v[88:91], v[64:67], v[32:47]
	v_max3_f32 v98, v98, v145, v150
	v_max3_f32 v98, v98, v151, v151
	v_add_f32_e32 v97, v97, v1
	v_add_f32_e32 v97, v97, v100
	v_add_f32_e32 v97, v97, v101
	v_add_f32_e32 v97, v97, v102
	s_setprio 0
	ds_read_b128 v[124:127], v201 offset:9248
	ds_read_b128 v[120:123], v201 offset:13856
	ds_read_b128 v[74:77], v201 offset:9280
	ds_read_b128 v[66:69], v201 offset:9312
	ds_read_b128 v[70:73], v201 offset:13888
	ds_read_b128 v[10:13], v201 offset:13920
	v_add_f32_e32 v64, v96, v97
	v_mov_b32_e32 v1, v98
	s_nop 1
	v_permlane32_swap_b32_e32 v98, v1
	v_max_f32_e32 v1, v1, v1
	v_max_f32_e32 v65, v98, v98
	v_max_f32_e32 v1, v65, v1
	v_cmp_lt_f32_e32 vcc, s52, v1
	s_cbranch_vccz .LBB0_703
	v_max_f32_e32 v1, v1, v1
	v_max_f32_e32 v82, 0, v1
	v_add_f32_e32 v195, v195, v82
	v_xor_b32_e32 v48, 0x80000000, v195
	v_pk_add_f32 v[112:113], v[112:113], v[82:83] op_sel_hi:[1,0] neg_lo:[0,1] neg_hi:[0,1]
	v_pk_add_f32 v[14:15], v[14:15], v[82:83] op_sel_hi:[1,0] neg_lo:[0,1] neg_hi:[0,1]
	v_pk_add_f32 v[114:115], v[114:115], v[82:83] op_sel_hi:[1,0] neg_lo:[0,1] neg_hi:[0,1]
	v_pk_add_f32 v[132:133], v[132:133], v[82:83] op_sel_hi:[1,0] neg_lo:[0,1] neg_hi:[0,1]
	v_pk_add_f32 v[140:141], v[140:141], v[82:83] op_sel_hi:[1,0] neg_lo:[0,1] neg_hi:[0,1]
	v_pk_add_f32 v[134:135], v[134:135], v[82:83] op_sel_hi:[1,0] neg_lo:[0,1] neg_hi:[0,1]
	v_pk_add_f32 v[146:147], v[146:147], v[82:83] op_sel_hi:[1,0] neg_lo:[0,1] neg_hi:[0,1]
	v_pk_add_f32 v[136:137], v[136:137], v[82:83] op_sel_hi:[1,0] neg_lo:[0,1] neg_hi:[0,1]
	v_pk_add_f32 v[148:149], v[148:149], v[82:83] op_sel_hi:[1,0] neg_lo:[0,1] neg_hi:[0,1]
	v_pk_add_f32 v[138:139], v[138:139], v[82:83] op_sel_hi:[1,0] neg_lo:[0,1] neg_hi:[0,1]
	v_pk_add_f32 v[176:177], v[176:177], v[82:83] op_sel_hi:[1,0] neg_lo:[0,1] neg_hi:[0,1]
	v_pk_add_f32 v[142:143], v[142:143], v[82:83] op_sel_hi:[1,0] neg_lo:[0,1] neg_hi:[0,1]
	v_pk_add_f32 v[178:179], v[178:179], v[82:83] op_sel_hi:[1,0] neg_lo:[0,1] neg_hi:[0,1]
	v_pk_add_f32 v[144:145], v[144:145], v[82:83] op_sel_hi:[1,0] neg_lo:[0,1] neg_hi:[0,1]
	v_pk_add_f32 v[180:181], v[180:181], v[82:83] op_sel_hi:[1,0] neg_lo:[0,1] neg_hi:[0,1]
	v_pk_add_f32 v[150:151], v[150:151], v[82:83] op_sel_hi:[1,0] neg_lo:[0,1] neg_hi:[0,1]
	v_exp_f32_e64 v82, -v82
	v_mov_b32_e32 v49, v48
	v_mov_b32_e32 v50, v48
	v_mov_b32_e32 v51, v48
	v_mov_b32_e32 v52, v48
	v_mov_b32_e32 v53, v48
	v_mov_b32_e32 v54, v48
	v_mov_b32_e32 v55, v48
	v_mov_b32_e32 v56, v48
	v_mov_b32_e32 v57, v48
	v_mov_b32_e32 v58, v48
	v_mov_b32_e32 v59, v48
	v_mov_b32_e32 v60, v48
	v_mov_b32_e32 v61, v48
	v_mov_b32_e32 v62, v48
	v_mov_b32_e32 v63, v48
	s_nop 11
	v_pk_mul_f32 v[30:31], v[30:31], v[82:83] op_sel_hi:[1,0]
	v_pk_mul_f32 v[28:29], v[28:29], v[82:83] op_sel_hi:[1,0]
	v_pk_mul_f32 v[26:27], v[26:27], v[82:83] op_sel_hi:[1,0]
	v_pk_mul_f32 v[24:25], v[24:25], v[82:83] op_sel_hi:[1,0]
	v_pk_mul_f32 v[22:23], v[22:23], v[82:83] op_sel_hi:[1,0]
	v_pk_mul_f32 v[20:21], v[20:21], v[82:83] op_sel_hi:[1,0]
	v_pk_mul_f32 v[18:19], v[18:19], v[82:83] op_sel_hi:[1,0]
	v_pk_mul_f32 v[16:17], v[16:17], v[82:83] op_sel_hi:[1,0]
	v_pk_mul_f32 v[46:47], v[46:47], v[82:83] op_sel_hi:[1,0]
	v_pk_mul_f32 v[44:45], v[44:45], v[82:83] op_sel_hi:[1,0]
	v_pk_mul_f32 v[42:43], v[42:43], v[82:83] op_sel_hi:[1,0]
	v_pk_mul_f32 v[40:41], v[40:41], v[82:83] op_sel_hi:[1,0]
	v_pk_mul_f32 v[38:39], v[38:39], v[82:83] op_sel_hi:[1,0]
	v_pk_mul_f32 v[36:37], v[36:37], v[82:83] op_sel_hi:[1,0]
	v_pk_mul_f32 v[34:35], v[34:35], v[82:83] op_sel_hi:[1,0]
	v_pk_mul_f32 v[32:33], v[32:33], v[82:83] op_sel_hi:[1,0]
	v_mul_f32_e32 v64, v64, v82

.LBB0_853:
	s_add_i32 s14, s8, 0xffff8000
	s_and_b64 s[4:5], s[4:5], exec
	s_cselect_b32 s5, s9, 0
	s_cselect_b32 s4, s8, s14
	s_cselect_b32 s14, s75, s10
	s_cselect_b32 s15, s74, s2
	s_lshl_b64 s[4:5], s[4:5], 12
	s_add_u32 s4, s15, s4
	s_addc_u32 s5, s14, s5
	global_load_dwordx4 v[80:83], v96, s[4:5]
	global_load_dwordx4 v[76:79], v96, s[4:5] offset:1024
	global_load_dwordx4 v[72:75], v96, s[4:5] offset:2048
	global_load_dwordx4 v[68:71], v96, s[4:5] offset:3072
	s_waitcnt vmcnt(3)
	v_mov_b32_e32 v2, v81
	v_mov_b32_e32 v3, v82
	v_mov_b32_e32 v98, v80
	v_mov_b32_e32 v99, v83
	v_pk_add_f32 v[2:3], v[2:3], v[98:99]
	s_waitcnt vmcnt(2)
	v_mov_b32_e32 v98, v77
	v_mov_b32_e32 v99, v78
	v_mov_b32_e32 v100, v76
	v_mov_b32_e32 v101, v79
	v_pk_add_f32 v[98:99], v[98:99], v[100:101]
	v_add_f32_e32 v1, v2, v3
	v_pk_add_f32 v[98:99], v[98:99], v[98:99] op_sel:[0,1] op_sel_hi:[1,0]
	v_add_f32_e32 v2, 0, v1
	s_waitcnt vmcnt(1)
	v_add_f32_e32 v100, v72, v73
	v_add_f32_e32 v102, v74, v75
	s_waitcnt vmcnt(0)
	v_mov_b32_e32 v3, v68
	v_mov_b32_e32 v99, v69
	v_mov_b32_e32 v101, v70
	v_mov_b32_e32 v103, v71
	v_pk_add_f32 v[2:3], v[2:3], v[98:99]
	v_pk_add_f32 v[98:99], v[100:101], v[102:103]
	s_nop 0
	v_pk_add_f32 v[2:3], v[2:3], v[98:99]
	s_nop 0
	v_add_f32_e32 v1, v2, v3
	s_nop 1
	v_add_f32_dpp v1, v1, v1 quad_perm:[1,0,3,2] row_mask:0xf bank_mask:0xf
	s_nop 1
	v_add_f32_dpp v1, v1, v1 quad_perm:[2,3,0,1] row_mask:0xf bank_mask:0xf
	s_nop 1
	v_add_f32_dpp v1, v1, v1 row_half_mirror row_mask:0xf bank_mask:0xf
	s_nop 1
	v_add_f32_dpp v1, v1, v1 row_mirror row_mask:0xf bank_mask:0xf
	v_mov_b32_e32 v2, v1
	s_nop 1
	v_permlane16_swap_b32_e32 v1, v2
	v_add_f32_e32 v1, v1, v2
	v_mov_b32_e32 v2, v1
	s_nop 1
	v_permlane32_swap_b32_e32 v1, v2
	v_add_f32_e32 v1, v1, v2
	v_fmamk_f32 v3, v1, 0xba800000, v83
	v_fmamk_f32 v81, v1, 0xba800000, v81
	v_fmamk_f32 v2, v1, 0xba800000, v82
	v_fmac_f32_e32 v80, 0xba800000, v1
	v_mul_f32_e32 v82, v81, v81
	v_mul_f32_e32 v83, v3, v3
	v_fmac_f32_e32 v82, v80, v80
	v_fmac_f32_e32 v83, v2, v2
	v_fmamk_f32 v79, v1, 0xba800000, v79
	v_fmamk_f32 v77, v1, 0xba800000, v77
	v_add_f32_e32 v82, v82, v83
	v_fmamk_f32 v78, v1, 0xba800000, v78
	v_fmac_f32_e32 v76, 0xba800000, v1
	v_mul_f32_e32 v83, v77, v77
	v_mul_f32_e32 v97, v79, v79
	v_fmac_f32_e32 v83, v76, v76
	v_fmac_f32_e32 v97, v78, v78
	v_add_f32_e32 v83, v83, v97
	v_fmamk_f32 v75, v1, 0xba800000, v75
	v_fmamk_f32 v73, v1, 0xba800000, v73
	v_add_f32_e32 v82, v82, v83
	v_fmamk_f32 v74, v1, 0xba800000, v74
	v_fmac_f32_e32 v72, 0xba800000, v1
	v_mul_f32_e32 v83, v73, v73
	v_mul_f32_e32 v97, v75, v75
	v_fmac_f32_e32 v83, v72, v72
	v_fmac_f32_e32 v97, v74, v74
	v_add_f32_e32 v83, v83, v97
	v_fmamk_f32 v71, v1, 0xba800000, v71
	v_fmamk_f32 v69, v1, 0xba800000, v69
	v_add_f32_e32 v82, v83, v82
	v_fmamk_f32 v70, v1, 0xba800000, v70
	v_fmac_f32_e32 v68, 0xba800000, v1
	v_mul_f32_e32 v83, v69, v69
	v_mul_f32_e32 v97, v71, v71
	v_fmac_f32_e32 v83, v68, v68
	v_fmac_f32_e32 v97, v70, v70
	v_add_f32_e32 v83, v83, v97
	v_add_f32_e32 v82, v83, v82
	s_nop 1
	v_add_f32_dpp v82, v82, v82 quad_perm:[1,0,3,2] row_mask:0xf bank_mask:0xf
	s_nop 1
	v_add_f32_dpp v82, v82, v82 quad_perm:[2,3,0,1] row_mask:0xf bank_mask:0xf
	s_nop 1
	v_add_f32_dpp v82, v82, v82 row_half_mirror row_mask:0xf bank_mask:0xf
	s_nop 1
	v_add_f32_dpp v82, v82, v82 row_mirror row_mask:0xf bank_mask:0xf
	v_mov_b32_e32 v83, v82
	s_nop 1
	v_permlane16_swap_b32_e32 v82, v83
	v_add_f32_e32 v82, v82, v83
	v_mov_b32_e32 v83, v82
	s_nop 1
	v_permlane32_swap_b32_e32 v82, v83
	v_add_f32_e32 v82, v82, v83
	v_fmamk_f32 v82, v82, 0x3a800000, v228
	v_cmp_gt_f32_e32 vcc, s49, v82
	v_mul_f32_e32 v83, 0x4f800000, v82
	s_nop 0
	v_cndmask_b32_e32 v82, v82, v83, vcc
	v_sqrt_f32_e32 v83, v82
	s_nop 0
	v_add_u32_e32 v97, -1, v83
	v_fma_f32 v98, -v97, v83, v82
	v_cmp_ge_f32_e64 s[4:5], 0, v98
	v_add_u32_e32 v98, 1, v83
	s_nop 0
	v_cndmask_b32_e64 v97, v83, v97, s[4:5]
	v_fma_f32 v83, -v98, v83, v82
	v_cmp_lt_f32_e64 s[4:5], 0, v83
	s_nop 1
	v_cndmask_b32_e64 v83, v97, v98, s[4:5]
	v_mul_f32_e32 v97, 0x37800000, v83
	v_cndmask_b32_e32 v83, v83, v97, vcc
	v_cmp_class_f32_e32 vcc, v82, v229
	s_nop 1
	v_cndmask_b32_e32 v82, v83, v82, vcc
	v_div_scale_f32 v83, s[4:5], v82, v82, 1.0
	v_rcp_f32_e32 v97, v83
	s_nop 0
	v_fma_f32 v98, -v83, v97, 1.0
	v_fmac_f32_e32 v97, v98, v97
	v_div_scale_f32 v98, vcc, 1.0, v82, 1.0
	v_mul_f32_e32 v99, v98, v97
	v_fma_f32 v100, -v83, v99, v98
	v_fmac_f32_e32 v99, v100, v97
	v_fma_f32 v83, -v83, v99, v98
	v_div_fmas_f32 v83, v83, v97, v99
	v_div_fixup_f32 v82, v83, v82, 1.0
	s_and_saveexec_b64 s[4:5], s[0:1]
	s_cbranch_execz .LBB0_850
	s_add_u32 s14, s6, s11
	v_mul_f32_e32 v98, 0x3a800000, v1
	s_addc_u32 s15, s7, s12
	v_mov_b32_e32 v99, v82
	global_store_dwordx2 v0, v[98:99], s[14:15]
	s_branch .LBB0_850
